# GEMM K-loops without the per-cluster s_setprio flips
# speedup vs baseline: 1.0475x; 1.0040x over previous
; #define PG8_STAGE(bufoff, gbase, voff) do { _Pragma("unroll") for (int _i = 0; _i < 2; ++_i) \
;         __builtin_amdgcn_global_load_lds((const unsigned*)((const char*)(gbase) + (voff)[_i]), (LAS unsigned*)(lds + (bufoff) + ldsw + _i * 8192), 16, 0, 0); } while (0)
; #define PG8_LDA(dst, b, h) do { _Pragma("unroll") for (int m = 0; m < 4; ++m) _Pragma("unroll") for (int k = 0; k < 2; ++k) dst[m][k] = *(const LAS bf16x8*)(lds + PG8_SA(b, h) + aoff + m * 2048 + k * 1024); } while (0)
; #define PG8_LDB(dst, b, h) do { _Pragma("unroll") for (int n = 0; n < 2; ++n) _Pragma("unroll") for (int k = 0; k < 2; ++k) dst[n][k] = *(const LAS bf16x8*)(lds + PG8_SB(b, h) + boff + n * 2048 + k * 1024); } while (0)
; #define PG8_MMA(ai, bj, At, Bt) do { __builtin_amdgcn_s_setprio(1); _Pragma("unroll") for (int m = 0; m < 4; ++m) _Pragma("unroll") for (int n = 0; n < 2; ++n) _Pragma("unroll") for (int k = 0; k < 2; ++k) \
;         acc[ai][bj][m][n] = __builtin_amdgcn_mfma_f32_16x16x32_bf16(Bt[n][k], At[m][k], acc[ai][bj][m][n], 0, 0, 0); __builtin_amdgcn_s_setprio(0); } while (0)
; #define PG8_WAIT_V(n) asm volatile("s_waitcnt vmcnt(" #n ")" ::: "memory")
; #define PG8_WAIT_L(n) asm volatile("s_waitcnt lgkmcnt(" #n ")" ::: "memory")
; #define PG8_BAR __builtin_amdgcn_s_barrier()
; #define PG8_SCHED __builtin_amdgcn_sched_barrier(0)
; template <class Epi, bool ALIGN_EPI>
; __device__ __forceinline__ void gemm_phase(LAS unsigned char* lds, const Gemm g, const StaticOrder& S, const Epi& E) {
;     ...
;             PG8_LDB(B0, 0, 0); PG8_LDB(B1, 0, 1); PG8_SCHED; PG8_LDA(At, 0, 0); PG8_STAGE(PG8_SA(1, 1), a1 + hsA, voffA);
;             PG8_WAIT_V(8); PG8_WAIT_L(0); PG8_BAR; PG8_MMA(0, 0, At, B0); PG8_MMA(0, 1, At, B1); PG8_BAR; PG8_SCHED;
;             PG8_LDA(At, 0, 1); PG8_STAGE(PG8_SB(0, 0), b2, voffB); PG8_STAGE(PG8_SB(0, 1), b2 + hsB, voffB); PG8_STAGE(PG8_SA(0, 0), a2, voffA);
;             PG8_WAIT_V(8); PG8_WAIT_L(0); PG8_BAR; PG8_MMA(1, 0, At, B0); PG8_MMA(1, 1, At, B1); PG8_BAR; PG8_SCHED;
.LBB0_156:
	ds_read_b128 v[156:159], v151
	ds_read_b128 v[160:163], v151 offset:1024
	ds_read_b128 v[164:167], v151 offset:2048
	ds_read_b128 v[168:171], v151 offset:3072
	ds_read_b128 v[172:175], v152
	ds_read_b128 v[176:179], v152 offset:1024
	ds_read_b128 v[180:183], v152 offset:2048
	ds_read_b128 v[184:187], v152 offset:3072
	s_add_u32 s28, s26, 0xfffc0080
	s_addc_u32 s29, s27, -1
	s_cmp_eq_u32 s54, 12
	s_cselect_b32 s31, s17, s29
	s_cselect_b32 s30, s50, s28
	s_cselect_b32 s29, s19, s53
	s_cselect_b32 s28, s51, s52
	v_lshl_add_u64 v[220:221], s[26:27], 0, v[140:141]
	s_add_i32 m0, s25, 0xc000
	ds_read_b128 v[188:191], v153
	ds_read_b128 v[192:195], v153 offset:1024
	ds_read_b128 v[196:199], v153 offset:2048
	ds_read_b128 v[200:203], v153 offset:3072
	ds_read_b128 v[204:207], v153 offset:4096
	ds_read_b128 v[208:211], v153 offset:5120
	ds_read_b128 v[212:215], v153 offset:6144
	ds_read_b128 v[216:219], v153 offset:7168
	global_load_lds_dwordx4 v[220:221], off
	v_lshl_add_u64 v[220:221], s[26:27], 0, v[142:143]
	s_add_i32 m0, s25, 0xe000
	s_nop 0
	global_load_lds_dwordx4 v[220:221], off
	s_waitcnt vmcnt(8)
	s_waitcnt lgkmcnt(0)
	s_barrier
	s_waitcnt lgkmcnt(0)
	v_mfma_f32_16x16x32_bf16 v[118:121], v[156:159], v[188:191], v[118:121]
	v_mfma_f32_16x16x32_bf16 v[114:117], v[164:167], v[188:191], v[114:117]
	v_mfma_f32_16x16x32_bf16 v[106:109], v[156:159], v[196:199], v[106:109]
	v_mfma_f32_16x16x32_bf16 v[102:105], v[164:167], v[196:199], v[102:105]
	v_mfma_f32_16x16x32_bf16 v[94:97], v[156:159], v[204:207], v[94:97]
	v_mfma_f32_16x16x32_bf16 v[90:93], v[164:167], v[204:207], v[90:93]
	v_mfma_f32_16x16x32_bf16 v[78:81], v[156:159], v[212:215], v[78:81]
	v_mfma_f32_16x16x32_bf16 v[74:77], v[164:167], v[212:215], v[74:77]
	v_mfma_f32_16x16x32_bf16 v[118:121], v[160:163], v[192:195], v[118:121]
	v_mfma_f32_16x16x32_bf16 v[114:117], v[168:171], v[192:195], v[114:117]
	v_mfma_f32_16x16x32_bf16 v[106:109], v[160:163], v[200:203], v[106:109]
	v_mfma_f32_16x16x32_bf16 v[102:105], v[168:171], v[200:203], v[102:105]
	v_mfma_f32_16x16x32_bf16 v[94:97], v[160:163], v[208:211], v[94:97]
	v_mfma_f32_16x16x32_bf16 v[90:93], v[168:171], v[208:211], v[90:93]
	v_mfma_f32_16x16x32_bf16 v[78:81], v[160:163], v[216:219], v[78:81]
	v_mfma_f32_16x16x32_bf16 v[74:77], v[168:171], v[216:219], v[74:77]
	v_mfma_f32_16x16x32_bf16 v[126:129], v[172:175], v[188:191], v[126:129]
	v_mfma_f32_16x16x32_bf16 v[122:125], v[180:183], v[188:191], v[122:125]
	v_mfma_f32_16x16x32_bf16 v[110:113], v[172:175], v[196:199], v[110:113]
	v_mfma_f32_16x16x32_bf16 v[98:101], v[180:183], v[196:199], v[98:101]
	v_mfma_f32_16x16x32_bf16 v[86:89], v[172:175], v[204:207], v[86:89]
	v_mfma_f32_16x16x32_bf16 v[82:85], v[180:183], v[204:207], v[82:85]
	v_mfma_f32_16x16x32_bf16 v[70:73], v[172:175], v[212:215], v[70:73]
	v_mfma_f32_16x16x32_bf16 v[66:69], v[180:183], v[212:215], v[66:69]
	v_mfma_f32_16x16x32_bf16 v[126:129], v[176:179], v[192:195], v[126:129]
	v_mfma_f32_16x16x32_bf16 v[122:125], v[184:187], v[192:195], v[122:125]
	v_mfma_f32_16x16x32_bf16 v[110:113], v[176:179], v[200:203], v[110:113]
	v_mfma_f32_16x16x32_bf16 v[98:101], v[184:187], v[200:203], v[98:101]
	v_mfma_f32_16x16x32_bf16 v[86:89], v[176:179], v[208:211], v[86:89]
	v_mfma_f32_16x16x32_bf16 v[82:85], v[184:187], v[208:211], v[82:85]
	v_mfma_f32_16x16x32_bf16 v[70:73], v[176:179], v[216:219], v[70:73]
	v_mfma_f32_16x16x32_bf16 v[66:69], v[184:187], v[216:219], v[66:69]
	s_barrier
	s_add_i32 s55, s46, s33
	v_lshl_add_u64 v[220:221], s[28:29], 0, v[134:135]
	s_mov_b32 m0, s55
	ds_read_b128 v[188:191], v153 offset:16384
	ds_read_b128 v[192:195], v153 offset:17408
	ds_read_b128 v[196:199], v153 offset:18432
	ds_read_b128 v[200:203], v153 offset:19456
	ds_read_b128 v[204:207], v153 offset:20480
	ds_read_b128 v[208:211], v153 offset:21504
	ds_read_b128 v[212:215], v153 offset:22528
	ds_read_b128 v[216:219], v153 offset:23552
	global_load_lds_dwordx4 v[220:221], off
	s_add_i32 m0, s55, 0x2000
	s_add_u32 s56, s28, 0x40000
	v_lshl_add_u64 v[222:223], s[28:29], 0, v[130:131]
	s_addc_u32 s57, s29, 0
	s_add_i32 s55, s47, s33
	global_load_lds_dwordx4 v[222:223], off
	v_lshl_add_u64 v[224:225], s[56:57], 0, v[134:135]
	s_mov_b32 m0, s55
	v_lshl_add_u64 v[226:227], s[30:31], 0, v[132:133]
	global_load_lds_dwordx4 v[224:225], off
	v_lshl_add_u64 v[224:225], s[56:57], 0, v[130:131]
	s_add_i32 m0, s55, 0x2000
	s_nop 0
	global_load_lds_dwordx4 v[224:225], off
	v_lshl_add_u64 v[224:225], s[30:31], 0, v[136:137]
	s_mov_b32 m0, s25
	s_nop 0
	global_load_lds_dwordx4 v[224:225], off
	s_mov_b32 m0, s36
	s_nop 0
	global_load_lds_dwordx4 v[226:227], off
	s_waitcnt vmcnt(8)
	s_waitcnt lgkmcnt(0)
	s_barrier
; #define PG8_STAGE(bufoff, gbase, voff) do { _Pragma("unroll") for (int _i = 0; _i < 2; ++_i) \
;         __builtin_amdgcn_global_load_lds((const unsigned*)((const char*)(gbase) + (voff)[_i]), (LAS unsigned*)(lds + (bufoff) + ldsw + _i * 8192), 16, 0, 0); } while (0)
; #define PG8_LDA(dst, b, h) do { _Pragma("unroll") for (int m = 0; m < 4; ++m) _Pragma("unroll") for (int k = 0; k < 2; ++k) dst[m][k] = *(const LAS bf16x8*)(lds + PG8_SA(b, h) + aoff + m * 2048 + k * 1024); } while (0)
; #define PG8_LDB(dst, b, h) do { _Pragma("unroll") for (int n = 0; n < 2; ++n) _Pragma("unroll") for (int k = 0; k < 2; ++k) dst[n][k] = *(const LAS bf16x8*)(lds + PG8_SB(b, h) + boff + n * 2048 + k * 1024); } while (0)
; #define PG8_MMA(ai, bj, At, Bt) do { __builtin_amdgcn_s_setprio(1); _Pragma("unroll") for (int m = 0; m < 4; ++m) _Pragma("unroll") for (int n = 0; n < 2; ++n) _Pragma("unroll") for (int k = 0; k < 2; ++k) \
;         acc[ai][bj][m][n] = __builtin_amdgcn_mfma_f32_16x16x32_bf16(Bt[n][k], At[m][k], acc[ai][bj][m][n], 0, 0, 0); __builtin_amdgcn_s_setprio(0); } while (0)
; #define PG8_WAIT_V(n) asm volatile("s_waitcnt vmcnt(" #n ")" ::: "memory")
; #define PG8_WAIT_L(n) asm volatile("s_waitcnt lgkmcnt(" #n ")" ::: "memory")
; #define PG8_BAR __builtin_amdgcn_s_barrier()
; #define PG8_SCHED __builtin_amdgcn_sched_barrier(0)
; template <class Epi, bool ALIGN_EPI>
; __device__ __forceinline__ void gemm_phase(LAS unsigned char* lds, const Gemm g, const StaticOrder& S, const Epi& E) {
;     ...
;             PG8_WAIT_V(8); PG8_WAIT_L(0); PG8_BAR; PG8_MMA(1, 0, At, B0); PG8_MMA(1, 1, At, B1); PG8_BAR; PG8_SCHED;
;             PG8_LDB(B0, 1, 0); PG8_LDB(B1, 1, 1); PG8_SCHED; PG8_LDA(At, 1, 0); PG8_STAGE(PG8_SA(0, 1), a2 + hsA, voffA);
;             PG8_WAIT_V(8); PG8_WAIT_L(0); PG8_BAR; PG8_MMA(0, 0, At, B0); PG8_MMA(0, 1, At, B1); PG8_BAR; PG8_SCHED;
	s_waitcnt lgkmcnt(0)
	v_mfma_f32_16x16x32_bf16 v[62:65], v[156:159], v[188:191], v[62:65]
	v_mfma_f32_16x16x32_bf16 v[58:61], v[164:167], v[188:191], v[58:61]
	v_mfma_f32_16x16x32_bf16 v[46:49], v[156:159], v[196:199], v[46:49]
	v_mfma_f32_16x16x32_bf16 v[42:45], v[164:167], v[196:199], v[42:45]
	v_mfma_f32_16x16x32_bf16 v[30:33], v[156:159], v[204:207], v[30:33]
	v_mfma_f32_16x16x32_bf16 v[26:29], v[164:167], v[204:207], v[26:29]
	v_mfma_f32_16x16x32_bf16 v[14:17], v[156:159], v[212:215], v[14:17]
	v_mfma_f32_16x16x32_bf16 v[10:13], v[164:167], v[212:215], v[10:13]
	v_mfma_f32_16x16x32_bf16 v[62:65], v[160:163], v[192:195], v[62:65]
	v_mfma_f32_16x16x32_bf16 v[58:61], v[168:171], v[192:195], v[58:61]
	v_mfma_f32_16x16x32_bf16 v[46:49], v[160:163], v[200:203], v[46:49]
	v_mfma_f32_16x16x32_bf16 v[42:45], v[168:171], v[200:203], v[42:45]
	v_mfma_f32_16x16x32_bf16 v[30:33], v[160:163], v[208:211], v[30:33]
	v_mfma_f32_16x16x32_bf16 v[26:29], v[168:171], v[208:211], v[26:29]
	v_mfma_f32_16x16x32_bf16 v[14:17], v[160:163], v[216:219], v[14:17]
	v_mfma_f32_16x16x32_bf16 v[10:13], v[168:171], v[216:219], v[10:13]
	v_mfma_f32_16x16x32_bf16 v[54:57], v[172:175], v[188:191], v[54:57]
	v_mfma_f32_16x16x32_bf16 v[50:53], v[180:183], v[188:191], v[50:53]
	v_mfma_f32_16x16x32_bf16 v[38:41], v[172:175], v[196:199], v[38:41]
	v_mfma_f32_16x16x32_bf16 v[34:37], v[180:183], v[196:199], v[34:37]
	v_mfma_f32_16x16x32_bf16 v[22:25], v[172:175], v[204:207], v[22:25]
	v_mfma_f32_16x16x32_bf16 v[18:21], v[180:183], v[204:207], v[18:21]
	v_mfma_f32_16x16x32_bf16 v[6:9], v[172:175], v[212:215], v[6:9]
	v_mfma_f32_16x16x32_bf16 v[2:5], v[180:183], v[212:215], v[2:5]
	v_mfma_f32_16x16x32_bf16 v[54:57], v[176:179], v[192:195], v[54:57]
	v_mfma_f32_16x16x32_bf16 v[50:53], v[184:187], v[192:195], v[50:53]
	v_mfma_f32_16x16x32_bf16 v[38:41], v[176:179], v[200:203], v[38:41]
	v_mfma_f32_16x16x32_bf16 v[34:37], v[184:187], v[200:203], v[34:37]
	v_mfma_f32_16x16x32_bf16 v[22:25], v[176:179], v[208:211], v[22:25]
	v_mfma_f32_16x16x32_bf16 v[18:21], v[184:187], v[208:211], v[18:21]
	v_mfma_f32_16x16x32_bf16 v[6:9], v[176:179], v[216:219], v[6:9]
	v_mfma_f32_16x16x32_bf16 v[2:5], v[184:187], v[216:219], v[2:5]
	s_barrier
	s_add_i32 s55, 0, 0x18000
	v_add_u32_e32 v138, s55, v150
	s_add_i32 s56, 0, 0x1c000
	ds_read_b128 v[156:159], v138
	ds_read_b128 v[160:163], v138 offset:1024
	ds_read_b128 v[164:167], v138 offset:2048
	ds_read_b128 v[168:171], v138 offset:3072
	v_add_u32_e32 v138, s56, v150
	ds_read_b128 v[172:175], v138
	ds_read_b128 v[176:179], v138 offset:1024
	ds_read_b128 v[180:183], v138 offset:2048
	ds_read_b128 v[184:187], v138 offset:3072
	s_add_u32 s30, s30, 0x40000
	s_addc_u32 s31, s31, 0
	s_mov_b32 m0, s37
	v_lshl_add_u64 v[228:229], s[30:31], 0, v[136:137]
	ds_read_b128 v[188:191], v153 offset:32768
	ds_read_b128 v[192:195], v153 offset:33792
	ds_read_b128 v[196:199], v153 offset:34816
	ds_read_b128 v[200:203], v153 offset:35840
	ds_read_b128 v[204:207], v153 offset:36864
	ds_read_b128 v[208:211], v153 offset:37888
	ds_read_b128 v[212:215], v153 offset:38912
	ds_read_b128 v[216:219], v153 offset:39936
	global_load_lds_dwordx4 v[228:229], off
	v_lshl_add_u64 v[228:229], s[30:31], 0, v[132:133]
	s_mov_b32 m0, s38
	s_nop 0
	global_load_lds_dwordx4 v[228:229], off
	s_waitcnt vmcnt(8)
	s_waitcnt lgkmcnt(0)
	s_barrier
	s_waitcnt lgkmcnt(0)
	v_mfma_f32_16x16x32_bf16 v[118:121], v[156:159], v[188:191], v[118:121]
	v_mfma_f32_16x16x32_bf16 v[114:117], v[164:167], v[188:191], v[114:117]
	v_mfma_f32_16x16x32_bf16 v[106:109], v[156:159], v[196:199], v[106:109]
	v_mfma_f32_16x16x32_bf16 v[102:105], v[164:167], v[196:199], v[102:105]
	v_mfma_f32_16x16x32_bf16 v[94:97], v[156:159], v[204:207], v[94:97]
	v_mfma_f32_16x16x32_bf16 v[90:93], v[164:167], v[204:207], v[90:93]
	v_mfma_f32_16x16x32_bf16 v[78:81], v[156:159], v[212:215], v[78:81]
	v_mfma_f32_16x16x32_bf16 v[74:77], v[164:167], v[212:215], v[74:77]
	v_mfma_f32_16x16x32_bf16 v[118:121], v[160:163], v[192:195], v[118:121]
	v_mfma_f32_16x16x32_bf16 v[114:117], v[168:171], v[192:195], v[114:117]
	v_mfma_f32_16x16x32_bf16 v[106:109], v[160:163], v[200:203], v[106:109]
	v_mfma_f32_16x16x32_bf16 v[102:105], v[168:171], v[200:203], v[102:105]
	v_mfma_f32_16x16x32_bf16 v[94:97], v[160:163], v[208:211], v[94:97]
	v_mfma_f32_16x16x32_bf16 v[90:93], v[168:171], v[208:211], v[90:93]
	v_mfma_f32_16x16x32_bf16 v[78:81], v[160:163], v[216:219], v[78:81]
	v_mfma_f32_16x16x32_bf16 v[74:77], v[168:171], v[216:219], v[74:77]
	v_mfma_f32_16x16x32_bf16 v[126:129], v[172:175], v[188:191], v[126:129]
	v_mfma_f32_16x16x32_bf16 v[122:125], v[180:183], v[188:191], v[122:125]
	v_mfma_f32_16x16x32_bf16 v[110:113], v[172:175], v[196:199], v[110:113]
	v_mfma_f32_16x16x32_bf16 v[98:101], v[180:183], v[196:199], v[98:101]
	v_mfma_f32_16x16x32_bf16 v[86:89], v[172:175], v[204:207], v[86:89]
	v_mfma_f32_16x16x32_bf16 v[82:85], v[180:183], v[204:207], v[82:85]
	v_mfma_f32_16x16x32_bf16 v[70:73], v[172:175], v[212:215], v[70:73]
	v_mfma_f32_16x16x32_bf16 v[66:69], v[180:183], v[212:215], v[66:69]
	v_mfma_f32_16x16x32_bf16 v[126:129], v[176:179], v[192:195], v[126:129]
	v_mfma_f32_16x16x32_bf16 v[122:125], v[184:187], v[192:195], v[122:125]
	v_mfma_f32_16x16x32_bf16 v[110:113], v[176:179], v[200:203], v[110:113]
	v_mfma_f32_16x16x32_bf16 v[98:101], v[184:187], v[200:203], v[98:101]
	v_mfma_f32_16x16x32_bf16 v[86:89], v[176:179], v[208:211], v[86:89]
	v_mfma_f32_16x16x32_bf16 v[82:85], v[184:187], v[208:211], v[82:85]
	v_mfma_f32_16x16x32_bf16 v[70:73], v[176:179], v[216:219], v[70:73]
	v_mfma_f32_16x16x32_bf16 v[66:69], v[184:187], v[216:219], v[66:69]
	s_barrier
; #define PG8_STAGE(bufoff, gbase, voff) do { _Pragma("unroll") for (int _i = 0; _i < 2; ++_i) \
;         __builtin_amdgcn_global_load_lds((const unsigned*)((const char*)(gbase) + (voff)[_i]), (LAS unsigned*)(lds + (bufoff) + ldsw + _i * 8192), 16, 0, 0); } while (0)
; #define PG8_LDA(dst, b, h) do { _Pragma("unroll") for (int m = 0; m < 4; ++m) _Pragma("unroll") for (int k = 0; k < 2; ++k) dst[m][k] = *(const LAS bf16x8*)(lds + PG8_SA(b, h) + aoff + m * 2048 + k * 1024); } while (0)
; #define PG8_MMA(ai, bj, At, Bt) do { __builtin_amdgcn_s_setprio(1); _Pragma("unroll") for (int m = 0; m < 4; ++m) _Pragma("unroll") for (int n = 0; n < 2; ++n) _Pragma("unroll") for (int k = 0; k < 2; ++k) \
;         acc[ai][bj][m][n] = __builtin_amdgcn_mfma_f32_16x16x32_bf16(Bt[n][k], At[m][k], acc[ai][bj][m][n], 0, 0, 0); __builtin_amdgcn_s_setprio(0); } while (0)
; #define PG8_WAIT_V(n) asm volatile("s_waitcnt vmcnt(" #n ")" ::: "memory")
; #define PG8_WAIT_L(n) asm volatile("s_waitcnt lgkmcnt(" #n ")" ::: "memory")
; #define PG8_BAR __builtin_amdgcn_s_barrier()
; #define PG8_SCHED __builtin_amdgcn_sched_barrier(0)
; template <class Epi, bool ALIGN_EPI>
; __device__ __forceinline__ void gemm_phase(LAS unsigned char* lds, const Gemm g, const StaticOrder& S, const Epi& E) {
;     ...
;             PG8_LDA(At, 1, 1); PG8_STAGE(PG8_SB(1, 0), b3, voffB); PG8_STAGE(PG8_SB(1, 1), b3 + hsB, voffB); PG8_STAGE(PG8_SA(1, 0), a3, voffA);
;             PG8_WAIT_V(8); PG8_WAIT_L(0); PG8_BAR; PG8_MMA(1, 0, At, B0); PG8_MMA(1, 1, At, B1); PG8_BAR; PG8_SCHED;
;         }
	s_add_i32 s30, s55, s33
	v_lshl_add_u64 v[220:221], v[220:221], 0, s[12:13]
	s_mov_b32 m0, s30
	ds_read_b128 v[188:191], v153 offset:49152
	ds_read_b128 v[192:195], v153 offset:50176
	ds_read_b128 v[196:199], v153 offset:51200
	ds_read_b128 v[200:203], v153 offset:52224
	ds_read_b128 v[204:207], v153 offset:53248
	ds_read_b128 v[208:211], v153 offset:54272
	ds_read_b128 v[212:215], v153 offset:55296
	ds_read_b128 v[216:219], v153 offset:56320
	global_load_lds_dwordx4 v[220:221], off
	s_add_i32 m0, s30, 0x2000
	s_add_u32 s28, s28, 0x40080
	v_lshl_add_u64 v[220:221], v[222:223], 0, s[12:13]
	s_addc_u32 s29, s29, 0
	s_add_i32 s30, s56, s33
	global_load_lds_dwordx4 v[220:221], off
	v_lshl_add_u64 v[220:221], s[28:29], 0, v[134:135]
	s_mov_b32 m0, s30
	s_nop 0
	global_load_lds_dwordx4 v[220:221], off
	v_lshl_add_u64 v[220:221], s[28:29], 0, v[130:131]
	s_add_i32 m0, s30, 0x2000
	s_nop 0
	global_load_lds_dwordx4 v[220:221], off
	v_lshl_add_u64 v[220:221], v[224:225], 0, s[12:13]
	s_mov_b32 m0, s42
	s_nop 0
	global_load_lds_dwordx4 v[220:221], off
	v_lshl_add_u64 v[220:221], v[226:227], 0, s[12:13]
	s_mov_b32 m0, s43
	s_nop 0
	global_load_lds_dwordx4 v[220:221], off
	s_waitcnt vmcnt(8)
	s_waitcnt lgkmcnt(0)
	s_barrier
	s_waitcnt lgkmcnt(0)
	v_mfma_f32_16x16x32_bf16 v[62:65], v[156:159], v[188:191], v[62:65]
	v_mfma_f32_16x16x32_bf16 v[58:61], v[164:167], v[188:191], v[58:61]
	v_mfma_f32_16x16x32_bf16 v[46:49], v[156:159], v[196:199], v[46:49]
	v_mfma_f32_16x16x32_bf16 v[42:45], v[164:167], v[196:199], v[42:45]
	v_mfma_f32_16x16x32_bf16 v[30:33], v[156:159], v[204:207], v[30:33]
	v_mfma_f32_16x16x32_bf16 v[26:29], v[164:167], v[204:207], v[26:29]
	v_mfma_f32_16x16x32_bf16 v[14:17], v[156:159], v[212:215], v[14:17]
	v_mfma_f32_16x16x32_bf16 v[10:13], v[164:167], v[212:215], v[10:13]
	v_mfma_f32_16x16x32_bf16 v[62:65], v[160:163], v[192:195], v[62:65]
	v_mfma_f32_16x16x32_bf16 v[58:61], v[168:171], v[192:195], v[58:61]
	v_mfma_f32_16x16x32_bf16 v[46:49], v[160:163], v[200:203], v[46:49]
	v_mfma_f32_16x16x32_bf16 v[42:45], v[168:171], v[200:203], v[42:45]
	v_mfma_f32_16x16x32_bf16 v[30:33], v[160:163], v[208:211], v[30:33]
	v_mfma_f32_16x16x32_bf16 v[26:29], v[168:171], v[208:211], v[26:29]
	v_mfma_f32_16x16x32_bf16 v[14:17], v[160:163], v[216:219], v[14:17]
	v_mfma_f32_16x16x32_bf16 v[10:13], v[168:171], v[216:219], v[10:13]
	v_mfma_f32_16x16x32_bf16 v[54:57], v[172:175], v[188:191], v[54:57]
	v_mfma_f32_16x16x32_bf16 v[50:53], v[180:183], v[188:191], v[50:53]
	v_mfma_f32_16x16x32_bf16 v[38:41], v[172:175], v[196:199], v[38:41]
	v_mfma_f32_16x16x32_bf16 v[34:37], v[180:183], v[196:199], v[34:37]
	v_mfma_f32_16x16x32_bf16 v[22:25], v[172:175], v[204:207], v[22:25]
	v_mfma_f32_16x16x32_bf16 v[18:21], v[180:183], v[204:207], v[18:21]
	v_mfma_f32_16x16x32_bf16 v[6:9], v[172:175], v[212:215], v[6:9]
	v_mfma_f32_16x16x32_bf16 v[2:5], v[180:183], v[212:215], v[2:5]
	v_mfma_f32_16x16x32_bf16 v[54:57], v[176:179], v[192:195], v[54:57]
	v_mfma_f32_16x16x32_bf16 v[50:53], v[184:187], v[192:195], v[50:53]
	v_mfma_f32_16x16x32_bf16 v[38:41], v[176:179], v[200:203], v[38:41]
	v_mfma_f32_16x16x32_bf16 v[34:37], v[184:187], v[200:203], v[34:37]
	v_mfma_f32_16x16x32_bf16 v[22:25], v[176:179], v[208:211], v[22:25]
	v_mfma_f32_16x16x32_bf16 v[18:21], v[184:187], v[208:211], v[18:21]
	v_mfma_f32_16x16x32_bf16 v[6:9], v[176:179], v[216:219], v[6:9]
	v_mfma_f32_16x16x32_bf16 v[2:5], v[184:187], v[216:219], v[2:5]
	s_barrier
	s_add_i32 s54, s54, 2
	s_add_u32 s26, s26, 0x100
	s_addc_u32 s27, s27, 0
	s_add_u32 s52, s52, 0x100
	s_addc_u32 s53, s53, 0
	s_cmp_gt_u32 s54, 13
	s_cbranch_scc0 .LBB0_156
	s_and_b64 vcc, exec, s[14:15]
	s_cbranch_vccz .LBB0_159
	s_barrier

; #define PG8_STAGE(bufoff, gbase, voff) do { _Pragma("unroll") for (int _i = 0; _i < 2; ++_i) \
;         __builtin_amdgcn_global_load_lds((const unsigned*)((const char*)(gbase) + (voff)[_i]), (LAS unsigned*)(lds + (bufoff) + ldsw + _i * 8192), 16, 0, 0); } while (0)
; #define PG8_LDA(dst, b, h) do { _Pragma("unroll") for (int m = 0; m < 4; ++m) _Pragma("unroll") for (int k = 0; k < 2; ++k) dst[m][k] = *(const LAS bf16x8*)(lds + PG8_SA(b, h) + aoff + m * 2048 + k * 1024); } while (0)
; #define PG8_LDB(dst, b, h) do { _Pragma("unroll") for (int n = 0; n < 2; ++n) _Pragma("unroll") for (int k = 0; k < 2; ++k) dst[n][k] = *(const LAS bf16x8*)(lds + PG8_SB(b, h) + boff + n * 2048 + k * 1024); } while (0)
; #define PG8_MMA(ai, bj, At, Bt) do { __builtin_amdgcn_s_setprio(1); _Pragma("unroll") for (int m = 0; m < 4; ++m) _Pragma("unroll") for (int n = 0; n < 2; ++n) _Pragma("unroll") for (int k = 0; k < 2; ++k) \
;         acc[ai][bj][m][n] = __builtin_amdgcn_mfma_f32_16x16x32_bf16(Bt[n][k], At[m][k], acc[ai][bj][m][n], 0, 0, 0); __builtin_amdgcn_s_setprio(0); } while (0)
; #define PG8_WAIT_V(n) asm volatile("s_waitcnt vmcnt(" #n ")" ::: "memory")
; #define PG8_WAIT_L(n) asm volatile("s_waitcnt lgkmcnt(" #n ")" ::: "memory")
; #define PG8_BAR __builtin_amdgcn_s_barrier()
; #define PG8_SCHED __builtin_amdgcn_sched_barrier(0)
; template <class Epi, bool ALIGN_EPI>
; __device__ __forceinline__ void gemm_phase(LAS unsigned char* lds, const Gemm g, const StaticOrder& S, const Epi& E) {
;     ...
;             PG8_LDB(B0, 0, 0); PG8_LDB(B1, 0, 1); PG8_SCHED; PG8_LDA(At, 0, 0); PG8_STAGE(PG8_SA(1, 1), a1 + hsA, voffA);
;             PG8_WAIT_V(8); PG8_WAIT_L(0); PG8_BAR; PG8_MMA(0, 0, At, B0); PG8_MMA(0, 1, At, B1); PG8_BAR; PG8_SCHED;
;             PG8_LDA(At, 0, 1); PG8_STAGE(PG8_SB(0, 0), b2, voffB); PG8_STAGE(PG8_SB(0, 1), b2 + hsB, voffB); PG8_STAGE(PG8_SA(0, 0), a2, voffA);
;             PG8_WAIT_V(8); PG8_WAIT_L(0); PG8_BAR; PG8_MMA(1, 0, At, B0); PG8_MMA(1, 1, At, B1); PG8_BAR; PG8_SCHED;
.LBB0_330:
	ds_read_b128 v[118:121], v190
	ds_read_b128 v[126:129], v190 offset:1024
	ds_read_b128 v[138:141], v190 offset:2048
	ds_read_b128 v[142:145], v190 offset:3072
	ds_read_b128 v[146:149], v191
	ds_read_b128 v[150:153], v191 offset:1024
	ds_read_b128 v[170:173], v191 offset:2048
	ds_read_b128 v[174:177], v191 offset:3072
	s_add_u32 s14, s12, 0x4000
	s_addc_u32 s15, s13, 0
	s_cmp_eq_u32 s48, 40
	s_cselect_b32 s18, s6, s14
	s_cselect_b32 s19, s7, s15
	s_cselect_b32 s16, s42, s46
	s_cselect_b32 s17, s43, s47
	s_add_u32 s14, s18, 0x8000
	s_addc_u32 s15, s19, 0
	v_lshl_add_u64 v[186:187], s[12:13], 0, v[162:163]
	s_add_i32 m0, s21, 0xc000
	ds_read_b128 v[178:181], v192
	ds_read_b128 v[182:185], v192 offset:1024
	ds_read_b128 v[194:197], v192 offset:2048
	ds_read_b128 v[198:201], v192 offset:3072
	ds_read_b128 v[202:205], v192 offset:4096
	ds_read_b128 v[206:209], v192 offset:5120
	ds_read_b128 v[210:213], v192 offset:6144
	ds_read_b128 v[214:217], v192 offset:7168
	global_load_lds_dwordx4 v[186:187], off
	v_lshl_add_u64 v[186:187], s[12:13], 0, v[164:165]
	s_add_i32 m0, s21, 0xe000
	s_nop 0
	global_load_lds_dwordx4 v[186:187], off
	s_waitcnt vmcnt(8)
	s_waitcnt lgkmcnt(0)
	s_barrier
	s_waitcnt lgkmcnt(0)
	v_mfma_f32_16x16x32_bf16 v[134:137], v[118:121], v[178:181], v[134:137]
	v_mfma_f32_16x16x32_bf16 v[130:133], v[138:141], v[178:181], v[130:133]
	v_mfma_f32_16x16x32_bf16 v[110:113], v[118:121], v[194:197], v[110:113]
	v_mfma_f32_16x16x32_bf16 v[106:109], v[138:141], v[194:197], v[106:109]
	v_mfma_f32_16x16x32_bf16 v[94:97], v[118:121], v[202:205], v[94:97]
	v_mfma_f32_16x16x32_bf16 v[90:93], v[138:141], v[202:205], v[90:93]
	v_mfma_f32_16x16x32_bf16 v[78:81], v[118:121], v[210:213], v[78:81]
	v_mfma_f32_16x16x32_bf16 v[74:77], v[138:141], v[210:213], v[74:77]
	v_mfma_f32_16x16x32_bf16 v[134:137], v[126:129], v[182:185], v[134:137]
	v_mfma_f32_16x16x32_bf16 v[130:133], v[142:145], v[182:185], v[130:133]
	v_mfma_f32_16x16x32_bf16 v[110:113], v[126:129], v[198:201], v[110:113]
	v_mfma_f32_16x16x32_bf16 v[106:109], v[142:145], v[198:201], v[106:109]
	v_mfma_f32_16x16x32_bf16 v[94:97], v[126:129], v[206:209], v[94:97]
	v_mfma_f32_16x16x32_bf16 v[90:93], v[142:145], v[206:209], v[90:93]
	v_mfma_f32_16x16x32_bf16 v[78:81], v[126:129], v[214:217], v[78:81]
	v_mfma_f32_16x16x32_bf16 v[74:77], v[142:145], v[214:217], v[74:77]
	v_mfma_f32_16x16x32_bf16 v[122:125], v[146:149], v[178:181], v[122:125]
	v_mfma_f32_16x16x32_bf16 v[114:117], v[170:173], v[178:181], v[114:117]
	v_mfma_f32_16x16x32_bf16 v[102:105], v[146:149], v[194:197], v[102:105]
	v_mfma_f32_16x16x32_bf16 v[98:101], v[170:173], v[194:197], v[98:101]
	v_mfma_f32_16x16x32_bf16 v[86:89], v[146:149], v[202:205], v[86:89]
	v_mfma_f32_16x16x32_bf16 v[82:85], v[170:173], v[202:205], v[82:85]
	v_mfma_f32_16x16x32_bf16 v[70:73], v[146:149], v[210:213], v[70:73]
	v_mfma_f32_16x16x32_bf16 v[66:69], v[170:173], v[210:213], v[66:69]
	v_mfma_f32_16x16x32_bf16 v[122:125], v[150:153], v[182:185], v[122:125]
	v_mfma_f32_16x16x32_bf16 v[114:117], v[174:177], v[182:185], v[114:117]
	v_mfma_f32_16x16x32_bf16 v[102:105], v[150:153], v[198:201], v[102:105]
	v_mfma_f32_16x16x32_bf16 v[98:101], v[174:177], v[198:201], v[98:101]
	v_mfma_f32_16x16x32_bf16 v[86:89], v[150:153], v[206:209], v[86:89]
	v_mfma_f32_16x16x32_bf16 v[82:85], v[174:177], v[206:209], v[82:85]
	v_mfma_f32_16x16x32_bf16 v[70:73], v[150:153], v[214:217], v[70:73]
	v_mfma_f32_16x16x32_bf16 v[66:69], v[174:177], v[214:217], v[66:69]
	s_barrier
	s_add_i32 s49, s31, s20
	v_lshl_add_u64 v[186:187], s[16:17], 0, v[156:157]
	s_mov_b32 m0, s49
	ds_read_b128 v[178:181], v192 offset:16384
	ds_read_b128 v[182:185], v192 offset:17408
	ds_read_b128 v[194:197], v192 offset:18432
	ds_read_b128 v[198:201], v192 offset:19456
	ds_read_b128 v[202:205], v192 offset:20480
	ds_read_b128 v[206:209], v192 offset:21504
	ds_read_b128 v[210:213], v192 offset:22528
	ds_read_b128 v[214:217], v192 offset:23552
	global_load_lds_dwordx4 v[186:187], off
	s_add_i32 m0, s49, 0x2000
	s_add_u32 s50, s16, 0xb0000
	v_lshl_add_u64 v[218:219], s[16:17], 0, v[160:161]
	s_addc_u32 s51, s17, 0
	s_add_i32 s49, s33, s20
	global_load_lds_dwordx4 v[218:219], off
	v_lshl_add_u64 v[220:221], s[50:51], 0, v[156:157]
	s_mov_b32 m0, s49
	s_nop 0
	global_load_lds_dwordx4 v[220:221], off
	v_lshl_add_u64 v[220:221], s[50:51], 0, v[160:161]
	s_add_i32 m0, s49, 0x2000
	s_nop 0
	global_load_lds_dwordx4 v[220:221], off
	v_lshl_add_u64 v[220:221], s[18:19], 0, v[154:155]
	s_mov_b32 m0, s21
	s_nop 0
	global_load_lds_dwordx4 v[220:221], off
	v_lshl_add_u64 v[220:221], s[18:19], 0, v[158:159]
	s_mov_b32 m0, s22
	s_nop 0
	global_load_lds_dwordx4 v[220:221], off
	s_waitcnt vmcnt(8)
	s_waitcnt lgkmcnt(0)
	s_barrier
; #define PG8_STAGE(bufoff, gbase, voff) do { _Pragma("unroll") for (int _i = 0; _i < 2; ++_i) \
;         __builtin_amdgcn_global_load_lds((const unsigned*)((const char*)(gbase) + (voff)[_i]), (LAS unsigned*)(lds + (bufoff) + ldsw + _i * 8192), 16, 0, 0); } while (0)
; #define PG8_LDA(dst, b, h) do { _Pragma("unroll") for (int m = 0; m < 4; ++m) _Pragma("unroll") for (int k = 0; k < 2; ++k) dst[m][k] = *(const LAS bf16x8*)(lds + PG8_SA(b, h) + aoff + m * 2048 + k * 1024); } while (0)
; #define PG8_LDB(dst, b, h) do { _Pragma("unroll") for (int n = 0; n < 2; ++n) _Pragma("unroll") for (int k = 0; k < 2; ++k) dst[n][k] = *(const LAS bf16x8*)(lds + PG8_SB(b, h) + boff + n * 2048 + k * 1024); } while (0)
; #define PG8_MMA(ai, bj, At, Bt) do { __builtin_amdgcn_s_setprio(1); _Pragma("unroll") for (int m = 0; m < 4; ++m) _Pragma("unroll") for (int n = 0; n < 2; ++n) _Pragma("unroll") for (int k = 0; k < 2; ++k) \
;         acc[ai][bj][m][n] = __builtin_amdgcn_mfma_f32_16x16x32_bf16(Bt[n][k], At[m][k], acc[ai][bj][m][n], 0, 0, 0); __builtin_amdgcn_s_setprio(0); } while (0)
; #define PG8_WAIT_V(n) asm volatile("s_waitcnt vmcnt(" #n ")" ::: "memory")
; #define PG8_WAIT_L(n) asm volatile("s_waitcnt lgkmcnt(" #n ")" ::: "memory")
; #define PG8_BAR __builtin_amdgcn_s_barrier()
; #define PG8_SCHED __builtin_amdgcn_sched_barrier(0)
; template <class Epi, bool ALIGN_EPI>
; __device__ __forceinline__ void gemm_phase(LAS unsigned char* lds, const Gemm g, const StaticOrder& S, const Epi& E) {
;     ...
;             PG8_WAIT_V(8); PG8_WAIT_L(0); PG8_BAR; PG8_MMA(1, 0, At, B0); PG8_MMA(1, 1, At, B1); PG8_BAR; PG8_SCHED;
;             PG8_LDB(B0, 1, 0); PG8_LDB(B1, 1, 1); PG8_SCHED; PG8_LDA(At, 1, 0); PG8_STAGE(PG8_SA(0, 1), a2 + hsA, voffA);
;             PG8_WAIT_V(8); PG8_WAIT_L(0); PG8_BAR; PG8_MMA(0, 0, At, B0); PG8_MMA(0, 1, At, B1); PG8_BAR; PG8_SCHED;
	s_waitcnt lgkmcnt(0)
	v_mfma_f32_16x16x32_bf16 v[62:65], v[118:121], v[178:181], v[62:65]
	v_mfma_f32_16x16x32_bf16 v[58:61], v[138:141], v[178:181], v[58:61]
	v_mfma_f32_16x16x32_bf16 v[46:49], v[118:121], v[194:197], v[46:49]
	v_mfma_f32_16x16x32_bf16 v[42:45], v[138:141], v[194:197], v[42:45]
	v_mfma_f32_16x16x32_bf16 v[30:33], v[118:121], v[202:205], v[30:33]
	v_mfma_f32_16x16x32_bf16 v[26:29], v[138:141], v[202:205], v[26:29]
	v_mfma_f32_16x16x32_bf16 v[14:17], v[118:121], v[210:213], v[14:17]
	v_mfma_f32_16x16x32_bf16 v[10:13], v[138:141], v[210:213], v[10:13]
	v_mfma_f32_16x16x32_bf16 v[62:65], v[126:129], v[182:185], v[62:65]
	v_mfma_f32_16x16x32_bf16 v[58:61], v[142:145], v[182:185], v[58:61]
	v_mfma_f32_16x16x32_bf16 v[46:49], v[126:129], v[198:201], v[46:49]
	v_mfma_f32_16x16x32_bf16 v[42:45], v[142:145], v[198:201], v[42:45]
	v_mfma_f32_16x16x32_bf16 v[30:33], v[126:129], v[206:209], v[30:33]
	v_mfma_f32_16x16x32_bf16 v[26:29], v[142:145], v[206:209], v[26:29]
	v_mfma_f32_16x16x32_bf16 v[14:17], v[126:129], v[214:217], v[14:17]
	v_mfma_f32_16x16x32_bf16 v[10:13], v[142:145], v[214:217], v[10:13]
	v_mfma_f32_16x16x32_bf16 v[54:57], v[146:149], v[178:181], v[54:57]
	v_mfma_f32_16x16x32_bf16 v[50:53], v[170:173], v[178:181], v[50:53]
	v_mfma_f32_16x16x32_bf16 v[38:41], v[146:149], v[194:197], v[38:41]
	v_mfma_f32_16x16x32_bf16 v[34:37], v[170:173], v[194:197], v[34:37]
	v_mfma_f32_16x16x32_bf16 v[22:25], v[146:149], v[202:205], v[22:25]
	v_mfma_f32_16x16x32_bf16 v[18:21], v[170:173], v[202:205], v[18:21]
	v_mfma_f32_16x16x32_bf16 v[6:9], v[146:149], v[210:213], v[6:9]
	v_mfma_f32_16x16x32_bf16 v[2:5], v[170:173], v[210:213], v[2:5]
	v_mfma_f32_16x16x32_bf16 v[54:57], v[150:153], v[182:185], v[54:57]
	v_mfma_f32_16x16x32_bf16 v[50:53], v[174:177], v[182:185], v[50:53]
	v_mfma_f32_16x16x32_bf16 v[38:41], v[150:153], v[198:201], v[38:41]
	v_mfma_f32_16x16x32_bf16 v[34:37], v[174:177], v[198:201], v[34:37]
	v_mfma_f32_16x16x32_bf16 v[22:25], v[150:153], v[206:209], v[22:25]
	v_mfma_f32_16x16x32_bf16 v[18:21], v[174:177], v[206:209], v[18:21]
	v_mfma_f32_16x16x32_bf16 v[6:9], v[150:153], v[214:217], v[6:9]
	v_mfma_f32_16x16x32_bf16 v[2:5], v[174:177], v[214:217], v[2:5]
	s_barrier
	s_add_i32 s49, 0, 0x18000
	s_add_i32 s50, 0, 0x1c000
	v_add_u32_e32 v142, s49, v188
	v_add_u32_e32 v174, s50, v188
	ds_read_b128 v[118:121], v142
	ds_read_b128 v[126:129], v142 offset:1024
	ds_read_b128 v[138:141], v142 offset:2048
	ds_read_b128 v[142:145], v142 offset:3072
	ds_read_b128 v[146:149], v174
	ds_read_b128 v[150:153], v174 offset:1024
	ds_read_b128 v[170:173], v174 offset:2048
	ds_read_b128 v[174:177], v174 offset:3072
	s_add_u32 s18, s18, 0x4000
	s_addc_u32 s19, s19, 0
	s_mov_b32 m0, s23
	v_lshl_add_u64 v[220:221], s[18:19], 0, v[154:155]
	ds_read_b128 v[178:181], v192 offset:32768
	ds_read_b128 v[182:185], v192 offset:33792
	ds_read_b128 v[194:197], v192 offset:34816
	ds_read_b128 v[198:201], v192 offset:35840
	ds_read_b128 v[202:205], v192 offset:36864
	ds_read_b128 v[206:209], v192 offset:37888
	ds_read_b128 v[210:213], v192 offset:38912
	ds_read_b128 v[214:217], v192 offset:39936
	global_load_lds_dwordx4 v[220:221], off
	v_lshl_add_u64 v[220:221], s[18:19], 0, v[158:159]
	s_mov_b32 m0, s24
	s_nop 0
	global_load_lds_dwordx4 v[220:221], off
	s_waitcnt vmcnt(8)
	s_waitcnt lgkmcnt(0)
	s_barrier
	s_waitcnt lgkmcnt(0)
	v_mfma_f32_16x16x32_bf16 v[134:137], v[118:121], v[178:181], v[134:137]
	v_mfma_f32_16x16x32_bf16 v[130:133], v[138:141], v[178:181], v[130:133]
	v_mfma_f32_16x16x32_bf16 v[110:113], v[118:121], v[194:197], v[110:113]
	v_mfma_f32_16x16x32_bf16 v[106:109], v[138:141], v[194:197], v[106:109]
	v_mfma_f32_16x16x32_bf16 v[94:97], v[118:121], v[202:205], v[94:97]
	v_mfma_f32_16x16x32_bf16 v[90:93], v[138:141], v[202:205], v[90:93]
	v_mfma_f32_16x16x32_bf16 v[78:81], v[118:121], v[210:213], v[78:81]
	v_mfma_f32_16x16x32_bf16 v[74:77], v[138:141], v[210:213], v[74:77]
	v_mfma_f32_16x16x32_bf16 v[134:137], v[126:129], v[182:185], v[134:137]
	v_mfma_f32_16x16x32_bf16 v[130:133], v[142:145], v[182:185], v[130:133]
	v_mfma_f32_16x16x32_bf16 v[110:113], v[126:129], v[198:201], v[110:113]
	v_mfma_f32_16x16x32_bf16 v[106:109], v[142:145], v[198:201], v[106:109]
	v_mfma_f32_16x16x32_bf16 v[94:97], v[126:129], v[206:209], v[94:97]
	v_mfma_f32_16x16x32_bf16 v[90:93], v[142:145], v[206:209], v[90:93]
	v_mfma_f32_16x16x32_bf16 v[78:81], v[126:129], v[214:217], v[78:81]
	v_mfma_f32_16x16x32_bf16 v[74:77], v[142:145], v[214:217], v[74:77]
	v_mfma_f32_16x16x32_bf16 v[122:125], v[146:149], v[178:181], v[122:125]
	v_mfma_f32_16x16x32_bf16 v[114:117], v[170:173], v[178:181], v[114:117]
	v_mfma_f32_16x16x32_bf16 v[102:105], v[146:149], v[194:197], v[102:105]
	v_mfma_f32_16x16x32_bf16 v[98:101], v[170:173], v[194:197], v[98:101]
	v_mfma_f32_16x16x32_bf16 v[86:89], v[146:149], v[202:205], v[86:89]
	v_mfma_f32_16x16x32_bf16 v[82:85], v[170:173], v[202:205], v[82:85]
	v_mfma_f32_16x16x32_bf16 v[70:73], v[146:149], v[210:213], v[70:73]
	v_mfma_f32_16x16x32_bf16 v[66:69], v[170:173], v[210:213], v[66:69]
	v_mfma_f32_16x16x32_bf16 v[122:125], v[150:153], v[182:185], v[122:125]
	v_mfma_f32_16x16x32_bf16 v[114:117], v[174:177], v[182:185], v[114:117]
	v_mfma_f32_16x16x32_bf16 v[102:105], v[150:153], v[198:201], v[102:105]
	v_mfma_f32_16x16x32_bf16 v[98:101], v[174:177], v[198:201], v[98:101]
	v_mfma_f32_16x16x32_bf16 v[86:89], v[150:153], v[206:209], v[86:89]
	v_mfma_f32_16x16x32_bf16 v[82:85], v[174:177], v[206:209], v[82:85]
	v_mfma_f32_16x16x32_bf16 v[70:73], v[150:153], v[214:217], v[70:73]
	v_mfma_f32_16x16x32_bf16 v[66:69], v[174:177], v[214:217], v[66:69]
	s_barrier
; #define PG8_STAGE(bufoff, gbase, voff) do { _Pragma("unroll") for (int _i = 0; _i < 2; ++_i) \
;         __builtin_amdgcn_global_load_lds((const unsigned*)((const char*)(gbase) + (voff)[_i]), (LAS unsigned*)(lds + (bufoff) + ldsw + _i * 8192), 16, 0, 0); } while (0)
; #define PG8_LDA(dst, b, h) do { _Pragma("unroll") for (int m = 0; m < 4; ++m) _Pragma("unroll") for (int k = 0; k < 2; ++k) dst[m][k] = *(const LAS bf16x8*)(lds + PG8_SA(b, h) + aoff + m * 2048 + k * 1024); } while (0)
; #define PG8_MMA(ai, bj, At, Bt) do { __builtin_amdgcn_s_setprio(1); _Pragma("unroll") for (int m = 0; m < 4; ++m) _Pragma("unroll") for (int n = 0; n < 2; ++n) _Pragma("unroll") for (int k = 0; k < 2; ++k) \
;         acc[ai][bj][m][n] = __builtin_amdgcn_mfma_f32_16x16x32_bf16(Bt[n][k], At[m][k], acc[ai][bj][m][n], 0, 0, 0); __builtin_amdgcn_s_setprio(0); } while (0)
; #define PG8_WAIT_V(n) asm volatile("s_waitcnt vmcnt(" #n ")" ::: "memory")
; #define PG8_WAIT_L(n) asm volatile("s_waitcnt lgkmcnt(" #n ")" ::: "memory")
; #define PG8_BAR __builtin_amdgcn_s_barrier()
; #define PG8_SCHED __builtin_amdgcn_sched_barrier(0)
; template <class Epi, bool ALIGN_EPI>
; __device__ __forceinline__ void gemm_phase(LAS unsigned char* lds, const Gemm g, const StaticOrder& S, const Epi& E) {
;     ...
;             PG8_LDA(At, 1, 1); PG8_STAGE(PG8_SB(1, 0), b3, voffB); PG8_STAGE(PG8_SB(1, 1), b3 + hsB, voffB); PG8_STAGE(PG8_SA(1, 0), a3, voffA);
;             PG8_WAIT_V(8); PG8_WAIT_L(0); PG8_BAR; PG8_MMA(1, 0, At, B0); PG8_MMA(1, 1, At, B1); PG8_BAR; PG8_SCHED;
;         }
	s_add_i32 s18, s49, s20
	v_lshl_add_u64 v[186:187], v[186:187], 0, s[38:39]
	s_mov_b32 m0, s18
	ds_read_b128 v[178:181], v192 offset:49152
	ds_read_b128 v[182:185], v192 offset:50176
	ds_read_b128 v[194:197], v192 offset:51200
	ds_read_b128 v[198:201], v192 offset:52224
	ds_read_b128 v[202:205], v192 offset:53248
	ds_read_b128 v[206:209], v192 offset:54272
	ds_read_b128 v[210:213], v192 offset:55296
	ds_read_b128 v[214:217], v192 offset:56320
	global_load_lds_dwordx4 v[186:187], off
	s_add_i32 m0, s18, 0x2000
	s_add_u32 s16, s16, 0xb0080
	v_lshl_add_u64 v[186:187], v[218:219], 0, s[38:39]
	s_addc_u32 s17, s17, 0
	s_add_i32 s18, s50, s20
	global_load_lds_dwordx4 v[186:187], off
	v_lshl_add_u64 v[186:187], s[16:17], 0, v[156:157]
	s_mov_b32 m0, s18
	s_nop 0
	global_load_lds_dwordx4 v[186:187], off
	v_lshl_add_u64 v[186:187], s[16:17], 0, v[160:161]
	s_add_i32 m0, s18, 0x2000
	s_nop 0
	global_load_lds_dwordx4 v[186:187], off
	v_lshl_add_u64 v[186:187], s[14:15], 0, v[154:155]
	s_mov_b32 m0, s26
	s_nop 0
	global_load_lds_dwordx4 v[186:187], off
	v_lshl_add_u64 v[186:187], s[14:15], 0, v[158:159]
	s_mov_b32 m0, s27
	s_nop 0
	global_load_lds_dwordx4 v[186:187], off
	s_waitcnt vmcnt(8)
	s_waitcnt lgkmcnt(0)
	s_barrier
	s_waitcnt lgkmcnt(0)
	v_mfma_f32_16x16x32_bf16 v[62:65], v[118:121], v[178:181], v[62:65]
	v_mfma_f32_16x16x32_bf16 v[58:61], v[138:141], v[178:181], v[58:61]
	v_mfma_f32_16x16x32_bf16 v[46:49], v[118:121], v[194:197], v[46:49]
	v_mfma_f32_16x16x32_bf16 v[42:45], v[138:141], v[194:197], v[42:45]
	v_mfma_f32_16x16x32_bf16 v[30:33], v[118:121], v[202:205], v[30:33]
	v_mfma_f32_16x16x32_bf16 v[26:29], v[138:141], v[202:205], v[26:29]
	v_mfma_f32_16x16x32_bf16 v[14:17], v[118:121], v[210:213], v[14:17]
	v_mfma_f32_16x16x32_bf16 v[10:13], v[138:141], v[210:213], v[10:13]
	v_mfma_f32_16x16x32_bf16 v[62:65], v[126:129], v[182:185], v[62:65]
	v_mfma_f32_16x16x32_bf16 v[58:61], v[142:145], v[182:185], v[58:61]
	v_mfma_f32_16x16x32_bf16 v[46:49], v[126:129], v[198:201], v[46:49]
	v_mfma_f32_16x16x32_bf16 v[42:45], v[142:145], v[198:201], v[42:45]
	v_mfma_f32_16x16x32_bf16 v[30:33], v[126:129], v[206:209], v[30:33]
	v_mfma_f32_16x16x32_bf16 v[26:29], v[142:145], v[206:209], v[26:29]
	v_mfma_f32_16x16x32_bf16 v[14:17], v[126:129], v[214:217], v[14:17]
	v_mfma_f32_16x16x32_bf16 v[10:13], v[142:145], v[214:217], v[10:13]
	v_mfma_f32_16x16x32_bf16 v[54:57], v[146:149], v[178:181], v[54:57]
	v_mfma_f32_16x16x32_bf16 v[50:53], v[170:173], v[178:181], v[50:53]
	v_mfma_f32_16x16x32_bf16 v[38:41], v[146:149], v[194:197], v[38:41]
	v_mfma_f32_16x16x32_bf16 v[34:37], v[170:173], v[194:197], v[34:37]
	v_mfma_f32_16x16x32_bf16 v[22:25], v[146:149], v[202:205], v[22:25]
	v_mfma_f32_16x16x32_bf16 v[18:21], v[170:173], v[202:205], v[18:21]
	v_mfma_f32_16x16x32_bf16 v[6:9], v[146:149], v[210:213], v[6:9]
	v_mfma_f32_16x16x32_bf16 v[2:5], v[170:173], v[210:213], v[2:5]
	v_mfma_f32_16x16x32_bf16 v[54:57], v[150:153], v[182:185], v[54:57]
	v_mfma_f32_16x16x32_bf16 v[50:53], v[174:177], v[182:185], v[50:53]
	v_mfma_f32_16x16x32_bf16 v[38:41], v[150:153], v[198:201], v[38:41]
	v_mfma_f32_16x16x32_bf16 v[34:37], v[174:177], v[198:201], v[34:37]
	v_mfma_f32_16x16x32_bf16 v[22:25], v[150:153], v[206:209], v[22:25]
	v_mfma_f32_16x16x32_bf16 v[18:21], v[174:177], v[206:209], v[18:21]
	v_mfma_f32_16x16x32_bf16 v[6:9], v[150:153], v[214:217], v[6:9]
	v_mfma_f32_16x16x32_bf16 v[2:5], v[174:177], v[214:217], v[2:5]
	s_barrier
	s_add_i32 s48, s48, 2
	s_add_u32 s12, s12, 0x10000
	s_addc_u32 s13, s13, 0
	s_add_u32 s46, s46, 0x100
	s_addc_u32 s47, s47, 0
	s_cmp_gt_u32 s48, 41
	s_cbranch_scc0 .LBB0_330
	s_and_b64 vcc, exec, s[40:41]
	s_cbranch_vccz .LBB0_333
	s_barrier

; #define PG8_STAGE(bufoff, gbase, voff) do { _Pragma("unroll") for (int _i = 0; _i < 2; ++_i) \
;         __builtin_amdgcn_global_load_lds((const unsigned*)((const char*)(gbase) + (voff)[_i]), (LAS unsigned*)(lds + (bufoff) + ldsw + _i * 8192), 16, 0, 0); } while (0)
; #define PG8_LDA(dst, b, h) do { _Pragma("unroll") for (int m = 0; m < 4; ++m) _Pragma("unroll") for (int k = 0; k < 2; ++k) dst[m][k] = *(const LAS bf16x8*)(lds + PG8_SA(b, h) + aoff + m * 2048 + k * 1024); } while (0)
; #define PG8_LDB(dst, b, h) do { _Pragma("unroll") for (int n = 0; n < 2; ++n) _Pragma("unroll") for (int k = 0; k < 2; ++k) dst[n][k] = *(const LAS bf16x8*)(lds + PG8_SB(b, h) + boff + n * 2048 + k * 1024); } while (0)
; #define PG8_MMA(ai, bj, At, Bt) do { __builtin_amdgcn_s_setprio(1); _Pragma("unroll") for (int m = 0; m < 4; ++m) _Pragma("unroll") for (int n = 0; n < 2; ++n) _Pragma("unroll") for (int k = 0; k < 2; ++k) \
;         acc[ai][bj][m][n] = __builtin_amdgcn_mfma_f32_16x16x32_bf16(Bt[n][k], At[m][k], acc[ai][bj][m][n], 0, 0, 0); __builtin_amdgcn_s_setprio(0); } while (0)
; #define PG8_WAIT_V(n) asm volatile("s_waitcnt vmcnt(" #n ")" ::: "memory")
; #define PG8_WAIT_L(n) asm volatile("s_waitcnt lgkmcnt(" #n ")" ::: "memory")
; #define PG8_BAR __builtin_amdgcn_s_barrier()
; #define PG8_SCHED __builtin_amdgcn_sched_barrier(0)
; template <class Epi, bool ALIGN_EPI>
; __device__ __forceinline__ void gemm_phase(LAS unsigned char* lds, const Gemm g, const StaticOrder& S, const Epi& E) {
;     ...
;             PG8_LDB(B0, 0, 0); PG8_LDB(B1, 0, 1); PG8_SCHED; PG8_LDA(At, 0, 0); PG8_STAGE(PG8_SA(1, 1), a1 + hsA, voffA);
;             PG8_WAIT_V(8); PG8_WAIT_L(0); PG8_BAR; PG8_MMA(0, 0, At, B0); PG8_MMA(0, 1, At, B1); PG8_BAR; PG8_SCHED;
;             PG8_LDA(At, 0, 1); PG8_STAGE(PG8_SB(0, 0), b2, voffB); PG8_STAGE(PG8_SB(0, 1), b2 + hsB, voffB); PG8_STAGE(PG8_SA(0, 0), a2, voffA);
;             PG8_WAIT_V(8); PG8_WAIT_L(0); PG8_BAR; PG8_MMA(1, 0, At, B0); PG8_MMA(1, 1, At, B1); PG8_BAR; PG8_SCHED;
.LBB0_419:
	ds_read_b128 v[130:133], v194
	ds_read_b128 v[160:163], v194 offset:1024
	ds_read_b128 v[164:167], v194 offset:2048
	ds_read_b128 v[168:171], v194 offset:3072
	ds_read_b128 v[172:175], v195
	ds_read_b128 v[176:179], v195 offset:1024
	s_waitcnt vmcnt(0)
	ds_read_b128 v[200:203], v195 offset:2048
	ds_read_b128 v[204:207], v195 offset:3072
	s_add_u32 s12, s8, 0xfffc0080
	s_addc_u32 s13, s9, -1
	s_cmp_eq_u32 s43, 12
	s_cselect_b32 s15, s7, s13
	s_cselect_b32 s14, s33, s12
	s_cselect_b32 s13, s39, s42
	s_cselect_b32 s12, s40, s41
	v_lshl_add_u64 v[180:181], s[8:9], 0, v[152:153]
	s_add_i32 m0, s17, 0xc000
	ds_read_b128 v[208:211], v196
	ds_read_b128 v[212:215], v196 offset:1024
	ds_read_b128 v[216:219], v196 offset:2048
	ds_read_b128 v[220:223], v196 offset:3072
	ds_read_b128 v[224:227], v196 offset:4096
	ds_read_b128 v[228:231], v196 offset:5120
	ds_read_b128 v[232:235], v196 offset:6144
	ds_read_b128 v[236:239], v196 offset:7168
	global_load_lds_dwordx4 v[180:181], off
	v_lshl_add_u64 v[180:181], s[8:9], 0, v[154:155]
	s_add_i32 m0, s17, 0xe000
	s_nop 0
	global_load_lds_dwordx4 v[180:181], off
	s_waitcnt vmcnt(8)
	s_waitcnt lgkmcnt(0)
	s_barrier
	s_waitcnt lgkmcnt(0)
	v_mfma_f32_16x16x32_bf16 v[118:121], v[130:133], v[208:211], v[118:121]
	v_mfma_f32_16x16x32_bf16 v[126:129], v[164:167], v[208:211], v[126:129]
	v_mfma_f32_16x16x32_bf16 v[106:109], v[130:133], v[216:219], v[106:109]
	v_mfma_f32_16x16x32_bf16 v[110:113], v[164:167], v[216:219], v[110:113]
	v_mfma_f32_16x16x32_bf16 v[90:93], v[130:133], v[224:227], v[90:93]
	v_mfma_f32_16x16x32_bf16 v[94:97], v[164:167], v[224:227], v[94:97]
	v_mfma_f32_16x16x32_bf16 v[74:77], v[130:133], v[232:235], v[74:77]
	v_mfma_f32_16x16x32_bf16 v[78:81], v[164:167], v[232:235], v[78:81]
	v_mfma_f32_16x16x32_bf16 v[118:121], v[160:163], v[212:215], v[118:121]
	v_mfma_f32_16x16x32_bf16 v[126:129], v[168:171], v[212:215], v[126:129]
	v_mfma_f32_16x16x32_bf16 v[106:109], v[160:163], v[220:223], v[106:109]
	v_mfma_f32_16x16x32_bf16 v[110:113], v[168:171], v[220:223], v[110:113]
	v_mfma_f32_16x16x32_bf16 v[90:93], v[160:163], v[228:231], v[90:93]
	v_mfma_f32_16x16x32_bf16 v[94:97], v[168:171], v[228:231], v[94:97]
	v_mfma_f32_16x16x32_bf16 v[74:77], v[160:163], v[236:239], v[74:77]
	v_mfma_f32_16x16x32_bf16 v[78:81], v[168:171], v[236:239], v[78:81]
	v_mfma_f32_16x16x32_bf16 v[114:117], v[172:175], v[208:211], v[114:117]
	v_mfma_f32_16x16x32_bf16 v[122:125], v[200:203], v[208:211], v[122:125]
	v_mfma_f32_16x16x32_bf16 v[98:101], v[172:175], v[216:219], v[98:101]
	v_mfma_f32_16x16x32_bf16 v[102:105], v[200:203], v[216:219], v[102:105]
	v_mfma_f32_16x16x32_bf16 v[82:85], v[172:175], v[224:227], v[82:85]
	v_mfma_f32_16x16x32_bf16 v[86:89], v[200:203], v[224:227], v[86:89]
	v_mfma_f32_16x16x32_bf16 v[66:69], v[172:175], v[232:235], v[66:69]
	v_mfma_f32_16x16x32_bf16 v[70:73], v[200:203], v[232:235], v[70:73]
	v_mfma_f32_16x16x32_bf16 v[114:117], v[176:179], v[212:215], v[114:117]
	v_mfma_f32_16x16x32_bf16 v[122:125], v[204:207], v[212:215], v[122:125]
	v_mfma_f32_16x16x32_bf16 v[98:101], v[176:179], v[220:223], v[98:101]
	v_mfma_f32_16x16x32_bf16 v[102:105], v[204:207], v[220:223], v[102:105]
	v_mfma_f32_16x16x32_bf16 v[82:85], v[176:179], v[228:231], v[82:85]
	v_mfma_f32_16x16x32_bf16 v[86:89], v[204:207], v[228:231], v[86:89]
	v_mfma_f32_16x16x32_bf16 v[66:69], v[176:179], v[236:239], v[66:69]
	v_mfma_f32_16x16x32_bf16 v[70:73], v[204:207], v[236:239], v[70:73]
	s_barrier
	s_add_i32 s44, s31, s16
	v_lshl_add_u64 v[180:181], s[12:13], 0, v[136:137]
	s_mov_b32 m0, s44
	ds_read_b128 v[208:211], v196 offset:16384
	ds_read_b128 v[212:215], v196 offset:17408
	ds_read_b128 v[216:219], v196 offset:18432
	ds_read_b128 v[220:223], v196 offset:19456
	ds_read_b128 v[224:227], v196 offset:20480
	ds_read_b128 v[228:231], v196 offset:21504
	ds_read_b128 v[232:235], v196 offset:22528
	ds_read_b128 v[236:239], v196 offset:23552
	global_load_lds_dwordx4 v[180:181], off
	s_add_i32 m0, s44, 0x2000
	s_add_u32 s44, s12, 0x40000
	v_lshl_add_u64 v[240:241], s[12:13], 0, v[140:141]
	s_addc_u32 s45, s13, 0
	s_add_i32 s46, s34, s16
	global_load_lds_dwordx4 v[240:241], off
	v_lshl_add_u64 v[242:243], s[44:45], 0, v[136:137]
	s_mov_b32 m0, s46
	v_lshl_add_u64 v[244:245], s[14:15], 0, v[138:139]
	global_load_lds_dwordx4 v[242:243], off
	v_lshl_add_u64 v[242:243], s[44:45], 0, v[140:141]
	s_add_i32 m0, s46, 0x2000
	s_nop 0
	global_load_lds_dwordx4 v[242:243], off
	v_lshl_add_u64 v[242:243], s[14:15], 0, v[134:135]
	s_mov_b32 m0, s17
	s_nop 0
	global_load_lds_dwordx4 v[242:243], off
	s_mov_b32 m0, s18
	s_nop 0
	global_load_lds_dwordx4 v[244:245], off
	s_waitcnt vmcnt(8)
	s_waitcnt lgkmcnt(0)
	s_barrier
; #define PG8_STAGE(bufoff, gbase, voff) do { _Pragma("unroll") for (int _i = 0; _i < 2; ++_i) \
;         __builtin_amdgcn_global_load_lds((const unsigned*)((const char*)(gbase) + (voff)[_i]), (LAS unsigned*)(lds + (bufoff) + ldsw + _i * 8192), 16, 0, 0); } while (0)
; #define PG8_LDA(dst, b, h) do { _Pragma("unroll") for (int m = 0; m < 4; ++m) _Pragma("unroll") for (int k = 0; k < 2; ++k) dst[m][k] = *(const LAS bf16x8*)(lds + PG8_SA(b, h) + aoff + m * 2048 + k * 1024); } while (0)
; #define PG8_LDB(dst, b, h) do { _Pragma("unroll") for (int n = 0; n < 2; ++n) _Pragma("unroll") for (int k = 0; k < 2; ++k) dst[n][k] = *(const LAS bf16x8*)(lds + PG8_SB(b, h) + boff + n * 2048 + k * 1024); } while (0)
; #define PG8_MMA(ai, bj, At, Bt) do { __builtin_amdgcn_s_setprio(1); _Pragma("unroll") for (int m = 0; m < 4; ++m) _Pragma("unroll") for (int n = 0; n < 2; ++n) _Pragma("unroll") for (int k = 0; k < 2; ++k) \
;         acc[ai][bj][m][n] = __builtin_amdgcn_mfma_f32_16x16x32_bf16(Bt[n][k], At[m][k], acc[ai][bj][m][n], 0, 0, 0); __builtin_amdgcn_s_setprio(0); } while (0)
; #define PG8_WAIT_V(n) asm volatile("s_waitcnt vmcnt(" #n ")" ::: "memory")
; #define PG8_WAIT_L(n) asm volatile("s_waitcnt lgkmcnt(" #n ")" ::: "memory")
; #define PG8_BAR __builtin_amdgcn_s_barrier()
; #define PG8_SCHED __builtin_amdgcn_sched_barrier(0)
; template <class Epi, bool ALIGN_EPI>
; __device__ __forceinline__ void gemm_phase(LAS unsigned char* lds, const Gemm g, const StaticOrder& S, const Epi& E) {
;     ...
;             PG8_WAIT_V(8); PG8_WAIT_L(0); PG8_BAR; PG8_MMA(1, 0, At, B0); PG8_MMA(1, 1, At, B1); PG8_BAR; PG8_SCHED;
;             PG8_LDB(B0, 1, 0); PG8_LDB(B1, 1, 1); PG8_SCHED; PG8_LDA(At, 1, 0); PG8_STAGE(PG8_SA(0, 1), a2 + hsA, voffA);
;             PG8_WAIT_V(8); PG8_WAIT_L(0); PG8_BAR; PG8_MMA(0, 0, At, B0); PG8_MMA(0, 1, At, B1); PG8_BAR; PG8_SCHED;
	s_waitcnt lgkmcnt(0)
	v_mfma_f32_16x16x32_bf16 v[58:61], v[130:133], v[208:211], v[58:61]
	v_mfma_f32_16x16x32_bf16 v[62:65], v[164:167], v[208:211], v[62:65]
	v_mfma_f32_16x16x32_bf16 v[42:45], v[130:133], v[216:219], v[42:45]
	v_mfma_f32_16x16x32_bf16 v[46:49], v[164:167], v[216:219], v[46:49]
	v_mfma_f32_16x16x32_bf16 v[26:29], v[130:133], v[224:227], v[26:29]
	v_mfma_f32_16x16x32_bf16 v[30:33], v[164:167], v[224:227], v[30:33]
	v_mfma_f32_16x16x32_bf16 v[10:13], v[130:133], v[232:235], v[10:13]
	v_mfma_f32_16x16x32_bf16 v[14:17], v[164:167], v[232:235], v[14:17]
	v_mfma_f32_16x16x32_bf16 v[58:61], v[160:163], v[212:215], v[58:61]
	v_mfma_f32_16x16x32_bf16 v[62:65], v[168:171], v[212:215], v[62:65]
	v_mfma_f32_16x16x32_bf16 v[42:45], v[160:163], v[220:223], v[42:45]
	v_mfma_f32_16x16x32_bf16 v[46:49], v[168:171], v[220:223], v[46:49]
	v_mfma_f32_16x16x32_bf16 v[26:29], v[160:163], v[228:231], v[26:29]
	v_mfma_f32_16x16x32_bf16 v[30:33], v[168:171], v[228:231], v[30:33]
	v_mfma_f32_16x16x32_bf16 v[10:13], v[160:163], v[236:239], v[10:13]
	v_mfma_f32_16x16x32_bf16 v[14:17], v[168:171], v[236:239], v[14:17]
	v_mfma_f32_16x16x32_bf16 v[50:53], v[172:175], v[208:211], v[50:53]
	v_mfma_f32_16x16x32_bf16 v[54:57], v[200:203], v[208:211], v[54:57]
	v_mfma_f32_16x16x32_bf16 v[34:37], v[172:175], v[216:219], v[34:37]
	v_mfma_f32_16x16x32_bf16 v[38:41], v[200:203], v[216:219], v[38:41]
	v_mfma_f32_16x16x32_bf16 v[18:21], v[172:175], v[224:227], v[18:21]
	v_mfma_f32_16x16x32_bf16 v[22:25], v[200:203], v[224:227], v[22:25]
	v_mfma_f32_16x16x32_bf16 v[2:5], v[172:175], v[232:235], v[2:5]
	v_mfma_f32_16x16x32_bf16 v[6:9], v[200:203], v[232:235], v[6:9]
	v_mfma_f32_16x16x32_bf16 v[50:53], v[176:179], v[212:215], v[50:53]
	v_mfma_f32_16x16x32_bf16 v[54:57], v[204:207], v[212:215], v[54:57]
	v_mfma_f32_16x16x32_bf16 v[34:37], v[176:179], v[220:223], v[34:37]
	v_mfma_f32_16x16x32_bf16 v[38:41], v[204:207], v[220:223], v[38:41]
	v_mfma_f32_16x16x32_bf16 v[18:21], v[176:179], v[228:231], v[18:21]
	v_mfma_f32_16x16x32_bf16 v[22:25], v[204:207], v[228:231], v[22:25]
	v_mfma_f32_16x16x32_bf16 v[2:5], v[176:179], v[236:239], v[2:5]
	v_mfma_f32_16x16x32_bf16 v[6:9], v[204:207], v[236:239], v[6:9]
	s_barrier
	s_add_i32 s44, 0, 0x18000
	v_add_u32_e32 v142, s44, v145
	s_add_i32 s45, 0, 0x1c000
	ds_read_b128 v[130:133], v142
	ds_read_b128 v[160:163], v142 offset:1024
	ds_read_b128 v[164:167], v142 offset:2048
	ds_read_b128 v[168:171], v142 offset:3072
	v_add_u32_e32 v142, s45, v145
	ds_read_b128 v[172:175], v142
	ds_read_b128 v[176:179], v142 offset:1024
	ds_read_b128 v[200:203], v142 offset:2048
	ds_read_b128 v[204:207], v142 offset:3072
	s_add_u32 s14, s14, 0x40000
	s_addc_u32 s15, s15, 0
	s_mov_b32 m0, s19
	v_lshl_add_u64 v[246:247], s[14:15], 0, v[134:135]
	ds_read_b128 v[208:211], v196 offset:32768
	ds_read_b128 v[212:215], v196 offset:33792
	ds_read_b128 v[216:219], v196 offset:34816
	ds_read_b128 v[220:223], v196 offset:35840
	ds_read_b128 v[224:227], v196 offset:36864
	ds_read_b128 v[228:231], v196 offset:37888
	ds_read_b128 v[232:235], v196 offset:38912
	ds_read_b128 v[236:239], v196 offset:39936
	global_load_lds_dwordx4 v[246:247], off
	v_lshl_add_u64 v[246:247], s[14:15], 0, v[138:139]
	s_mov_b32 m0, s20
	s_nop 0
	global_load_lds_dwordx4 v[246:247], off
	s_waitcnt vmcnt(8)
	s_waitcnt lgkmcnt(0)
	s_barrier
	s_waitcnt lgkmcnt(0)
	v_mfma_f32_16x16x32_bf16 v[118:121], v[130:133], v[208:211], v[118:121]
	v_mfma_f32_16x16x32_bf16 v[126:129], v[164:167], v[208:211], v[126:129]
	v_mfma_f32_16x16x32_bf16 v[106:109], v[130:133], v[216:219], v[106:109]
	v_mfma_f32_16x16x32_bf16 v[110:113], v[164:167], v[216:219], v[110:113]
	v_mfma_f32_16x16x32_bf16 v[90:93], v[130:133], v[224:227], v[90:93]
	v_mfma_f32_16x16x32_bf16 v[94:97], v[164:167], v[224:227], v[94:97]
	v_mfma_f32_16x16x32_bf16 v[74:77], v[130:133], v[232:235], v[74:77]
	v_mfma_f32_16x16x32_bf16 v[78:81], v[164:167], v[232:235], v[78:81]
	v_mfma_f32_16x16x32_bf16 v[118:121], v[160:163], v[212:215], v[118:121]
	v_mfma_f32_16x16x32_bf16 v[126:129], v[168:171], v[212:215], v[126:129]
	v_mfma_f32_16x16x32_bf16 v[106:109], v[160:163], v[220:223], v[106:109]
	v_mfma_f32_16x16x32_bf16 v[110:113], v[168:171], v[220:223], v[110:113]
	v_mfma_f32_16x16x32_bf16 v[90:93], v[160:163], v[228:231], v[90:93]
	v_mfma_f32_16x16x32_bf16 v[94:97], v[168:171], v[228:231], v[94:97]
	v_mfma_f32_16x16x32_bf16 v[74:77], v[160:163], v[236:239], v[74:77]
	v_mfma_f32_16x16x32_bf16 v[78:81], v[168:171], v[236:239], v[78:81]
	v_mfma_f32_16x16x32_bf16 v[114:117], v[172:175], v[208:211], v[114:117]
	v_mfma_f32_16x16x32_bf16 v[122:125], v[200:203], v[208:211], v[122:125]
	v_mfma_f32_16x16x32_bf16 v[98:101], v[172:175], v[216:219], v[98:101]
	v_mfma_f32_16x16x32_bf16 v[102:105], v[200:203], v[216:219], v[102:105]
	v_mfma_f32_16x16x32_bf16 v[82:85], v[172:175], v[224:227], v[82:85]
	v_mfma_f32_16x16x32_bf16 v[86:89], v[200:203], v[224:227], v[86:89]
	v_mfma_f32_16x16x32_bf16 v[66:69], v[172:175], v[232:235], v[66:69]
	v_mfma_f32_16x16x32_bf16 v[70:73], v[200:203], v[232:235], v[70:73]
	v_mfma_f32_16x16x32_bf16 v[114:117], v[176:179], v[212:215], v[114:117]
	v_mfma_f32_16x16x32_bf16 v[122:125], v[204:207], v[212:215], v[122:125]
	v_mfma_f32_16x16x32_bf16 v[98:101], v[176:179], v[220:223], v[98:101]
	v_mfma_f32_16x16x32_bf16 v[102:105], v[204:207], v[220:223], v[102:105]
	v_mfma_f32_16x16x32_bf16 v[82:85], v[176:179], v[228:231], v[82:85]
	v_mfma_f32_16x16x32_bf16 v[86:89], v[204:207], v[228:231], v[86:89]
	v_mfma_f32_16x16x32_bf16 v[66:69], v[176:179], v[236:239], v[66:69]
	v_mfma_f32_16x16x32_bf16 v[70:73], v[204:207], v[236:239], v[70:73]
	s_barrier
; #define PG8_STAGE(bufoff, gbase, voff) do { _Pragma("unroll") for (int _i = 0; _i < 2; ++_i) \
;         __builtin_amdgcn_global_load_lds((const unsigned*)((const char*)(gbase) + (voff)[_i]), (LAS unsigned*)(lds + (bufoff) + ldsw + _i * 8192), 16, 0, 0); } while (0)
; #define PG8_LDA(dst, b, h) do { _Pragma("unroll") for (int m = 0; m < 4; ++m) _Pragma("unroll") for (int k = 0; k < 2; ++k) dst[m][k] = *(const LAS bf16x8*)(lds + PG8_SA(b, h) + aoff + m * 2048 + k * 1024); } while (0)
; #define PG8_MMA(ai, bj, At, Bt) do { __builtin_amdgcn_s_setprio(1); _Pragma("unroll") for (int m = 0; m < 4; ++m) _Pragma("unroll") for (int n = 0; n < 2; ++n) _Pragma("unroll") for (int k = 0; k < 2; ++k) \
;         acc[ai][bj][m][n] = __builtin_amdgcn_mfma_f32_16x16x32_bf16(Bt[n][k], At[m][k], acc[ai][bj][m][n], 0, 0, 0); __builtin_amdgcn_s_setprio(0); } while (0)
; #define PG8_WAIT_V(n) asm volatile("s_waitcnt vmcnt(" #n ")" ::: "memory")
; #define PG8_WAIT_L(n) asm volatile("s_waitcnt lgkmcnt(" #n ")" ::: "memory")
; #define PG8_BAR __builtin_amdgcn_s_barrier()
; #define PG8_SCHED __builtin_amdgcn_sched_barrier(0)
; template <class Epi, bool ALIGN_EPI>
; __device__ __forceinline__ void gemm_phase(LAS unsigned char* lds, const Gemm g, const StaticOrder& S, const Epi& E) {
;     ...
;             PG8_LDA(At, 1, 1); PG8_STAGE(PG8_SB(1, 0), b3, voffB); PG8_STAGE(PG8_SB(1, 1), b3 + hsB, voffB); PG8_STAGE(PG8_SA(1, 0), a3, voffA);
;             PG8_WAIT_V(8); PG8_WAIT_L(0); PG8_BAR; PG8_MMA(1, 0, At, B0); PG8_MMA(1, 1, At, B1); PG8_BAR; PG8_SCHED;
;         }
	s_add_i32 s14, s44, s16
	v_lshl_add_u64 v[180:181], v[180:181], 0, s[96:97]
	s_mov_b32 m0, s14
	ds_read_b128 v[208:211], v196 offset:49152
	ds_read_b128 v[212:215], v196 offset:50176
	ds_read_b128 v[216:219], v196 offset:51200
	ds_read_b128 v[220:223], v196 offset:52224
	ds_read_b128 v[224:227], v196 offset:53248
	ds_read_b128 v[228:231], v196 offset:54272
	ds_read_b128 v[232:235], v196 offset:55296
	ds_read_b128 v[236:239], v196 offset:56320
	global_load_lds_dwordx4 v[180:181], off
	s_add_i32 m0, s14, 0x2000
	s_add_u32 s12, s12, 0x40080
	v_lshl_add_u64 v[180:181], v[240:241], 0, s[96:97]
	s_addc_u32 s13, s13, 0
	s_add_i32 s14, s45, s16
	global_load_lds_dwordx4 v[180:181], off
	v_lshl_add_u64 v[180:181], s[12:13], 0, v[136:137]
	s_mov_b32 m0, s14
	s_nop 0
	global_load_lds_dwordx4 v[180:181], off
	v_lshl_add_u64 v[180:181], s[12:13], 0, v[140:141]
	s_add_i32 m0, s14, 0x2000
	s_nop 0
	global_load_lds_dwordx4 v[180:181], off
	v_lshl_add_u64 v[180:181], v[242:243], 0, s[96:97]
	s_mov_b32 m0, s23
	s_nop 0
	global_load_lds_dwordx4 v[180:181], off
	v_lshl_add_u64 v[180:181], v[244:245], 0, s[96:97]
	s_mov_b32 m0, s24
	s_nop 0
	global_load_lds_dwordx4 v[180:181], off
	s_waitcnt vmcnt(8)
	s_waitcnt lgkmcnt(0)
	s_barrier
	s_waitcnt lgkmcnt(0)
	v_mfma_f32_16x16x32_bf16 v[58:61], v[130:133], v[208:211], v[58:61]
	v_mfma_f32_16x16x32_bf16 v[62:65], v[164:167], v[208:211], v[62:65]
	v_mfma_f32_16x16x32_bf16 v[42:45], v[130:133], v[216:219], v[42:45]
	v_mfma_f32_16x16x32_bf16 v[46:49], v[164:167], v[216:219], v[46:49]
	v_mfma_f32_16x16x32_bf16 v[26:29], v[130:133], v[224:227], v[26:29]
	v_mfma_f32_16x16x32_bf16 v[30:33], v[164:167], v[224:227], v[30:33]
	v_mfma_f32_16x16x32_bf16 v[10:13], v[130:133], v[232:235], v[10:13]
	v_mfma_f32_16x16x32_bf16 v[14:17], v[164:167], v[232:235], v[14:17]
	v_mfma_f32_16x16x32_bf16 v[58:61], v[160:163], v[212:215], v[58:61]
	v_mfma_f32_16x16x32_bf16 v[62:65], v[168:171], v[212:215], v[62:65]
	v_mfma_f32_16x16x32_bf16 v[42:45], v[160:163], v[220:223], v[42:45]
	v_mfma_f32_16x16x32_bf16 v[46:49], v[168:171], v[220:223], v[46:49]
	v_mfma_f32_16x16x32_bf16 v[26:29], v[160:163], v[228:231], v[26:29]
	v_mfma_f32_16x16x32_bf16 v[30:33], v[168:171], v[228:231], v[30:33]
	v_mfma_f32_16x16x32_bf16 v[10:13], v[160:163], v[236:239], v[10:13]
	v_mfma_f32_16x16x32_bf16 v[14:17], v[168:171], v[236:239], v[14:17]
	v_mfma_f32_16x16x32_bf16 v[50:53], v[172:175], v[208:211], v[50:53]
	v_mfma_f32_16x16x32_bf16 v[54:57], v[200:203], v[208:211], v[54:57]
	v_mfma_f32_16x16x32_bf16 v[34:37], v[172:175], v[216:219], v[34:37]
	v_mfma_f32_16x16x32_bf16 v[38:41], v[200:203], v[216:219], v[38:41]
	v_mfma_f32_16x16x32_bf16 v[18:21], v[172:175], v[224:227], v[18:21]
	v_mfma_f32_16x16x32_bf16 v[22:25], v[200:203], v[224:227], v[22:25]
	v_mfma_f32_16x16x32_bf16 v[2:5], v[172:175], v[232:235], v[2:5]
	v_mfma_f32_16x16x32_bf16 v[6:9], v[200:203], v[232:235], v[6:9]
	v_mfma_f32_16x16x32_bf16 v[50:53], v[176:179], v[212:215], v[50:53]
	v_mfma_f32_16x16x32_bf16 v[54:57], v[204:207], v[212:215], v[54:57]
	v_mfma_f32_16x16x32_bf16 v[34:37], v[176:179], v[220:223], v[34:37]
	v_mfma_f32_16x16x32_bf16 v[38:41], v[204:207], v[220:223], v[38:41]
	v_mfma_f32_16x16x32_bf16 v[18:21], v[176:179], v[228:231], v[18:21]
	v_mfma_f32_16x16x32_bf16 v[22:25], v[204:207], v[228:231], v[22:25]
	v_mfma_f32_16x16x32_bf16 v[2:5], v[176:179], v[236:239], v[2:5]
	v_mfma_f32_16x16x32_bf16 v[6:9], v[204:207], v[236:239], v[6:9]
	s_barrier
	s_add_i32 s43, s43, 2
	s_add_u32 s8, s8, 0x100
	s_addc_u32 s9, s9, 0
	s_add_u32 s41, s41, 0x100
	s_addc_u32 s42, s42, 0
	s_cmp_gt_u32 s43, 13
	s_cbranch_scc0 .LBB0_419
	s_and_b64 vcc, exec, s[86:87]
	s_cbranch_vccz .LBB0_422
	s_barrier

; #define PG8_STAGE(bufoff, gbase, voff) do { _Pragma("unroll") for (int _i = 0; _i < 2; ++_i) \
;         __builtin_amdgcn_global_load_lds((const unsigned*)((const char*)(gbase) + (voff)[_i]), (LAS unsigned*)(lds + (bufoff) + ldsw + _i * 8192), 16, 0, 0); } while (0)
; #define PG8_LDA(dst, b, h) do { _Pragma("unroll") for (int m = 0; m < 4; ++m) _Pragma("unroll") for (int k = 0; k < 2; ++k) dst[m][k] = *(const LAS bf16x8*)(lds + PG8_SA(b, h) + aoff + m * 2048 + k * 1024); } while (0)
; #define PG8_LDB(dst, b, h) do { _Pragma("unroll") for (int n = 0; n < 2; ++n) _Pragma("unroll") for (int k = 0; k < 2; ++k) dst[n][k] = *(const LAS bf16x8*)(lds + PG8_SB(b, h) + boff + n * 2048 + k * 1024); } while (0)
; #define PG8_MMA(ai, bj, At, Bt) do { __builtin_amdgcn_s_setprio(1); _Pragma("unroll") for (int m = 0; m < 4; ++m) _Pragma("unroll") for (int n = 0; n < 2; ++n) _Pragma("unroll") for (int k = 0; k < 2; ++k) \
;         acc[ai][bj][m][n] = __builtin_amdgcn_mfma_f32_16x16x32_bf16(Bt[n][k], At[m][k], acc[ai][bj][m][n], 0, 0, 0); __builtin_amdgcn_s_setprio(0); } while (0)
; #define PG8_WAIT_V(n) asm volatile("s_waitcnt vmcnt(" #n ")" ::: "memory")
; #define PG8_WAIT_L(n) asm volatile("s_waitcnt lgkmcnt(" #n ")" ::: "memory")
; #define PG8_BAR __builtin_amdgcn_s_barrier()
; #define PG8_SCHED __builtin_amdgcn_sched_barrier(0)
; template <class Epi, bool ALIGN_EPI>
; __device__ __forceinline__ void gemm_phase(LAS unsigned char* lds, const Gemm g, const StaticOrder& S, const Epi& E) {
;     ...
;             PG8_LDB(B0, 0, 0); PG8_LDB(B1, 0, 1); PG8_SCHED; PG8_LDA(At, 0, 0); PG8_STAGE(PG8_SA(1, 1), a1 + hsA, voffA);
;             PG8_WAIT_V(8); PG8_WAIT_L(0); PG8_BAR; PG8_MMA(0, 0, At, B0); PG8_MMA(0, 1, At, B1); PG8_BAR; PG8_SCHED;
;             PG8_LDA(At, 0, 1); PG8_STAGE(PG8_SB(0, 0), b2, voffB); PG8_STAGE(PG8_SB(0, 1), b2 + hsB, voffB); PG8_STAGE(PG8_SA(0, 0), a2, voffA);
;             PG8_WAIT_V(8); PG8_WAIT_L(0); PG8_BAR; PG8_MMA(1, 0, At, B0); PG8_MMA(1, 1, At, B1); PG8_BAR; PG8_SCHED;
.LBB0_670:
	ds_read_b128 v[148:151], v145
	ds_read_b128 v[152:155], v145 offset:1024
	ds_read_b128 v[156:159], v145 offset:2048
	ds_read_b128 v[160:163], v145 offset:3072
	ds_read_b128 v[164:167], v146
	ds_read_b128 v[168:171], v146 offset:1024
	ds_read_b128 v[172:175], v146 offset:2048
	ds_read_b128 v[176:179], v146 offset:3072
	s_add_i32 s55, s28, 2
	s_add_u32 s29, s26, 0xfffe0080
	s_addc_u32 s30, s27, -1
	s_cmp_eq_u32 s46, s28
	s_cselect_b32 s28, s52, s53
	s_cselect_b32 s31, s17, s30
	s_cselect_b32 s30, s19, s29
	s_cselect_b32 s29, s51, s54
	v_lshl_add_u64 v[212:213], s[26:27], 0, v[140:141]
	s_add_i32 m0, s38, 0xc000
	ds_read_b128 v[180:183], v147
	ds_read_b128 v[184:187], v147 offset:1024
	ds_read_b128 v[188:191], v147 offset:2048
	ds_read_b128 v[192:195], v147 offset:3072
	ds_read_b128 v[196:199], v147 offset:4096
	ds_read_b128 v[200:203], v147 offset:5120
	ds_read_b128 v[204:207], v147 offset:6144
	ds_read_b128 v[208:211], v147 offset:7168
	global_load_lds_dwordx4 v[212:213], off
	v_lshl_add_u64 v[212:213], s[26:27], 0, v[142:143]
	s_add_i32 m0, s38, 0xe000
	s_nop 0
	global_load_lds_dwordx4 v[212:213], off
	s_waitcnt vmcnt(8)
	s_waitcnt lgkmcnt(0)
	s_barrier
	s_waitcnt lgkmcnt(0)
	v_mfma_f32_16x16x32_bf16 v[126:129], v[148:151], v[180:183], v[126:129]
	v_mfma_f32_16x16x32_bf16 v[122:125], v[156:159], v[180:183], v[122:125]
	v_mfma_f32_16x16x32_bf16 v[110:113], v[148:151], v[188:191], v[110:113]
	v_mfma_f32_16x16x32_bf16 v[106:109], v[156:159], v[188:191], v[106:109]
	v_mfma_f32_16x16x32_bf16 v[94:97], v[148:151], v[196:199], v[94:97]
	v_mfma_f32_16x16x32_bf16 v[90:93], v[156:159], v[196:199], v[90:93]
	v_mfma_f32_16x16x32_bf16 v[78:81], v[148:151], v[204:207], v[78:81]
	v_mfma_f32_16x16x32_bf16 v[74:77], v[156:159], v[204:207], v[74:77]
	v_mfma_f32_16x16x32_bf16 v[126:129], v[152:155], v[184:187], v[126:129]
	v_mfma_f32_16x16x32_bf16 v[122:125], v[160:163], v[184:187], v[122:125]
	v_mfma_f32_16x16x32_bf16 v[110:113], v[152:155], v[192:195], v[110:113]
	v_mfma_f32_16x16x32_bf16 v[106:109], v[160:163], v[192:195], v[106:109]
	v_mfma_f32_16x16x32_bf16 v[94:97], v[152:155], v[200:203], v[94:97]
	v_mfma_f32_16x16x32_bf16 v[90:93], v[160:163], v[200:203], v[90:93]
	v_mfma_f32_16x16x32_bf16 v[78:81], v[152:155], v[208:211], v[78:81]
	v_mfma_f32_16x16x32_bf16 v[74:77], v[160:163], v[208:211], v[74:77]
	v_mfma_f32_16x16x32_bf16 v[118:121], v[164:167], v[180:183], v[118:121]
	v_mfma_f32_16x16x32_bf16 v[114:117], v[172:175], v[180:183], v[114:117]
	v_mfma_f32_16x16x32_bf16 v[102:105], v[164:167], v[188:191], v[102:105]
	v_mfma_f32_16x16x32_bf16 v[98:101], v[172:175], v[188:191], v[98:101]
	v_mfma_f32_16x16x32_bf16 v[86:89], v[164:167], v[196:199], v[86:89]
	v_mfma_f32_16x16x32_bf16 v[82:85], v[172:175], v[196:199], v[82:85]
	v_mfma_f32_16x16x32_bf16 v[70:73], v[164:167], v[204:207], v[70:73]
	v_mfma_f32_16x16x32_bf16 v[66:69], v[172:175], v[204:207], v[66:69]
	v_mfma_f32_16x16x32_bf16 v[118:121], v[168:171], v[184:187], v[118:121]
	v_mfma_f32_16x16x32_bf16 v[114:117], v[176:179], v[184:187], v[114:117]
	v_mfma_f32_16x16x32_bf16 v[102:105], v[168:171], v[192:195], v[102:105]
	v_mfma_f32_16x16x32_bf16 v[98:101], v[176:179], v[192:195], v[98:101]
	v_mfma_f32_16x16x32_bf16 v[86:89], v[168:171], v[200:203], v[86:89]
	v_mfma_f32_16x16x32_bf16 v[82:85], v[176:179], v[200:203], v[82:85]
	v_mfma_f32_16x16x32_bf16 v[70:73], v[168:171], v[208:211], v[70:73]
	v_mfma_f32_16x16x32_bf16 v[66:69], v[176:179], v[208:211], v[66:69]
	s_barrier
	s_add_i32 s56, s48, s36
	v_lshl_add_u64 v[212:213], s[28:29], 0, v[134:135]
	s_mov_b32 m0, s56
	ds_read_b128 v[180:183], v147 offset:16384
	ds_read_b128 v[184:187], v147 offset:17408
	ds_read_b128 v[188:191], v147 offset:18432
	ds_read_b128 v[192:195], v147 offset:19456
	ds_read_b128 v[196:199], v147 offset:20480
	ds_read_b128 v[200:203], v147 offset:21504
	ds_read_b128 v[204:207], v147 offset:22528
	ds_read_b128 v[208:211], v147 offset:23552
	global_load_lds_dwordx4 v[212:213], off
	s_add_i32 m0, s56, 0x2000
	s_add_u32 s56, s28, 0x10000
	v_lshl_add_u64 v[214:215], s[28:29], 0, v[130:131]
	s_addc_u32 s57, s29, 0
	s_add_i32 s58, s49, s36
	global_load_lds_dwordx4 v[214:215], off
	v_lshl_add_u64 v[216:217], s[56:57], 0, v[134:135]
	s_mov_b32 m0, s58
	v_lshl_add_u64 v[218:219], s[30:31], 0, v[132:133]
	global_load_lds_dwordx4 v[216:217], off
	v_lshl_add_u64 v[216:217], s[56:57], 0, v[130:131]
	s_add_i32 m0, s58, 0x2000
	s_nop 0
	global_load_lds_dwordx4 v[216:217], off
	v_lshl_add_u64 v[216:217], s[30:31], 0, v[136:137]
	s_mov_b32 m0, s38
	s_nop 0
	global_load_lds_dwordx4 v[216:217], off
	s_mov_b32 m0, s39
	s_nop 0
	global_load_lds_dwordx4 v[218:219], off
	s_waitcnt vmcnt(8)
	s_waitcnt lgkmcnt(0)
	s_barrier
; #define PG8_STAGE(bufoff, gbase, voff) do { _Pragma("unroll") for (int _i = 0; _i < 2; ++_i) \
;         __builtin_amdgcn_global_load_lds((const unsigned*)((const char*)(gbase) + (voff)[_i]), (LAS unsigned*)(lds + (bufoff) + ldsw + _i * 8192), 16, 0, 0); } while (0)
; #define PG8_LDA(dst, b, h) do { _Pragma("unroll") for (int m = 0; m < 4; ++m) _Pragma("unroll") for (int k = 0; k < 2; ++k) dst[m][k] = *(const LAS bf16x8*)(lds + PG8_SA(b, h) + aoff + m * 2048 + k * 1024); } while (0)
; #define PG8_LDB(dst, b, h) do { _Pragma("unroll") for (int n = 0; n < 2; ++n) _Pragma("unroll") for (int k = 0; k < 2; ++k) dst[n][k] = *(const LAS bf16x8*)(lds + PG8_SB(b, h) + boff + n * 2048 + k * 1024); } while (0)
; #define PG8_MMA(ai, bj, At, Bt) do { __builtin_amdgcn_s_setprio(1); _Pragma("unroll") for (int m = 0; m < 4; ++m) _Pragma("unroll") for (int n = 0; n < 2; ++n) _Pragma("unroll") for (int k = 0; k < 2; ++k) \
;         acc[ai][bj][m][n] = __builtin_amdgcn_mfma_f32_16x16x32_bf16(Bt[n][k], At[m][k], acc[ai][bj][m][n], 0, 0, 0); __builtin_amdgcn_s_setprio(0); } while (0)
; #define PG8_WAIT_V(n) asm volatile("s_waitcnt vmcnt(" #n ")" ::: "memory")
; #define PG8_WAIT_L(n) asm volatile("s_waitcnt lgkmcnt(" #n ")" ::: "memory")
; #define PG8_BAR __builtin_amdgcn_s_barrier()
; #define PG8_SCHED __builtin_amdgcn_sched_barrier(0)
; template <class Epi, bool ALIGN_EPI>
; __device__ __forceinline__ void gemm_phase(LAS unsigned char* lds, const Gemm g, const StaticOrder& S, const Epi& E) {
;     ...
;             PG8_WAIT_V(8); PG8_WAIT_L(0); PG8_BAR; PG8_MMA(1, 0, At, B0); PG8_MMA(1, 1, At, B1); PG8_BAR; PG8_SCHED;
;             PG8_LDB(B0, 1, 0); PG8_LDB(B1, 1, 1); PG8_SCHED; PG8_LDA(At, 1, 0); PG8_STAGE(PG8_SA(0, 1), a2 + hsA, voffA);
;             PG8_WAIT_V(8); PG8_WAIT_L(0); PG8_BAR; PG8_MMA(0, 0, At, B0); PG8_MMA(0, 1, At, B1); PG8_BAR; PG8_SCHED;
	s_waitcnt lgkmcnt(0)
	v_mfma_f32_16x16x32_bf16 v[62:65], v[148:151], v[180:183], v[62:65]
	v_mfma_f32_16x16x32_bf16 v[58:61], v[156:159], v[180:183], v[58:61]
	v_mfma_f32_16x16x32_bf16 v[46:49], v[148:151], v[188:191], v[46:49]
	v_mfma_f32_16x16x32_bf16 v[42:45], v[156:159], v[188:191], v[42:45]
	v_mfma_f32_16x16x32_bf16 v[30:33], v[148:151], v[196:199], v[30:33]
	v_mfma_f32_16x16x32_bf16 v[26:29], v[156:159], v[196:199], v[26:29]
	v_mfma_f32_16x16x32_bf16 v[14:17], v[148:151], v[204:207], v[14:17]
	v_mfma_f32_16x16x32_bf16 v[10:13], v[156:159], v[204:207], v[10:13]
	v_mfma_f32_16x16x32_bf16 v[62:65], v[152:155], v[184:187], v[62:65]
	v_mfma_f32_16x16x32_bf16 v[58:61], v[160:163], v[184:187], v[58:61]
	v_mfma_f32_16x16x32_bf16 v[46:49], v[152:155], v[192:195], v[46:49]
	v_mfma_f32_16x16x32_bf16 v[42:45], v[160:163], v[192:195], v[42:45]
	v_mfma_f32_16x16x32_bf16 v[30:33], v[152:155], v[200:203], v[30:33]
	v_mfma_f32_16x16x32_bf16 v[26:29], v[160:163], v[200:203], v[26:29]
	v_mfma_f32_16x16x32_bf16 v[14:17], v[152:155], v[208:211], v[14:17]
	v_mfma_f32_16x16x32_bf16 v[10:13], v[160:163], v[208:211], v[10:13]
	v_mfma_f32_16x16x32_bf16 v[54:57], v[164:167], v[180:183], v[54:57]
	v_mfma_f32_16x16x32_bf16 v[50:53], v[172:175], v[180:183], v[50:53]
	v_mfma_f32_16x16x32_bf16 v[38:41], v[164:167], v[188:191], v[38:41]
	v_mfma_f32_16x16x32_bf16 v[34:37], v[172:175], v[188:191], v[34:37]
	v_mfma_f32_16x16x32_bf16 v[22:25], v[164:167], v[196:199], v[22:25]
	v_mfma_f32_16x16x32_bf16 v[18:21], v[172:175], v[196:199], v[18:21]
	v_mfma_f32_16x16x32_bf16 v[6:9], v[164:167], v[204:207], v[6:9]
	v_mfma_f32_16x16x32_bf16 v[2:5], v[172:175], v[204:207], v[2:5]
	v_mfma_f32_16x16x32_bf16 v[54:57], v[168:171], v[184:187], v[54:57]
	v_mfma_f32_16x16x32_bf16 v[50:53], v[176:179], v[184:187], v[50:53]
	v_mfma_f32_16x16x32_bf16 v[38:41], v[168:171], v[192:195], v[38:41]
	v_mfma_f32_16x16x32_bf16 v[34:37], v[176:179], v[192:195], v[34:37]
	v_mfma_f32_16x16x32_bf16 v[22:25], v[168:171], v[200:203], v[22:25]
	v_mfma_f32_16x16x32_bf16 v[18:21], v[176:179], v[200:203], v[18:21]
	v_mfma_f32_16x16x32_bf16 v[6:9], v[168:171], v[208:211], v[6:9]
	v_mfma_f32_16x16x32_bf16 v[2:5], v[176:179], v[208:211], v[2:5]
	s_barrier
	s_add_i32 s56, 0, 0x18000
	s_add_i32 s57, 0, 0x1c000
	v_add_u32_e32 v160, s56, v144
	v_add_u32_e32 v176, s57, v144
	ds_read_b128 v[148:151], v160
	ds_read_b128 v[152:155], v160 offset:1024
	ds_read_b128 v[156:159], v160 offset:2048
	ds_read_b128 v[160:163], v160 offset:3072
	ds_read_b128 v[164:167], v176
	ds_read_b128 v[168:171], v176 offset:1024
	ds_read_b128 v[172:175], v176 offset:2048
	ds_read_b128 v[176:179], v176 offset:3072
	s_add_u32 s30, s30, 0x20000
	s_addc_u32 s31, s31, 0
	s_mov_b32 m0, s40
	v_lshl_add_u64 v[220:221], s[30:31], 0, v[136:137]
	ds_read_b128 v[180:183], v147 offset:32768
	ds_read_b128 v[184:187], v147 offset:33792
	ds_read_b128 v[188:191], v147 offset:34816
	ds_read_b128 v[192:195], v147 offset:35840
	ds_read_b128 v[196:199], v147 offset:36864
	ds_read_b128 v[200:203], v147 offset:37888
	ds_read_b128 v[204:207], v147 offset:38912
	ds_read_b128 v[208:211], v147 offset:39936
	global_load_lds_dwordx4 v[220:221], off
	v_lshl_add_u64 v[220:221], s[30:31], 0, v[132:133]
	s_mov_b32 m0, s41
	s_nop 0
	global_load_lds_dwordx4 v[220:221], off
	s_waitcnt vmcnt(8)
	s_waitcnt lgkmcnt(0)
	s_barrier
	s_waitcnt lgkmcnt(0)
	v_mfma_f32_16x16x32_bf16 v[126:129], v[148:151], v[180:183], v[126:129]
	v_mfma_f32_16x16x32_bf16 v[122:125], v[156:159], v[180:183], v[122:125]
	v_mfma_f32_16x16x32_bf16 v[110:113], v[148:151], v[188:191], v[110:113]
	v_mfma_f32_16x16x32_bf16 v[106:109], v[156:159], v[188:191], v[106:109]
	v_mfma_f32_16x16x32_bf16 v[94:97], v[148:151], v[196:199], v[94:97]
	v_mfma_f32_16x16x32_bf16 v[90:93], v[156:159], v[196:199], v[90:93]
	v_mfma_f32_16x16x32_bf16 v[78:81], v[148:151], v[204:207], v[78:81]
	v_mfma_f32_16x16x32_bf16 v[74:77], v[156:159], v[204:207], v[74:77]
	v_mfma_f32_16x16x32_bf16 v[126:129], v[152:155], v[184:187], v[126:129]
	v_mfma_f32_16x16x32_bf16 v[122:125], v[160:163], v[184:187], v[122:125]
	v_mfma_f32_16x16x32_bf16 v[110:113], v[152:155], v[192:195], v[110:113]
	v_mfma_f32_16x16x32_bf16 v[106:109], v[160:163], v[192:195], v[106:109]
	v_mfma_f32_16x16x32_bf16 v[94:97], v[152:155], v[200:203], v[94:97]
	v_mfma_f32_16x16x32_bf16 v[90:93], v[160:163], v[200:203], v[90:93]
	v_mfma_f32_16x16x32_bf16 v[78:81], v[152:155], v[208:211], v[78:81]
	v_mfma_f32_16x16x32_bf16 v[74:77], v[160:163], v[208:211], v[74:77]
	v_mfma_f32_16x16x32_bf16 v[118:121], v[164:167], v[180:183], v[118:121]
	v_mfma_f32_16x16x32_bf16 v[114:117], v[172:175], v[180:183], v[114:117]
	v_mfma_f32_16x16x32_bf16 v[102:105], v[164:167], v[188:191], v[102:105]
	v_mfma_f32_16x16x32_bf16 v[98:101], v[172:175], v[188:191], v[98:101]
	v_mfma_f32_16x16x32_bf16 v[86:89], v[164:167], v[196:199], v[86:89]
	v_mfma_f32_16x16x32_bf16 v[82:85], v[172:175], v[196:199], v[82:85]
	v_mfma_f32_16x16x32_bf16 v[70:73], v[164:167], v[204:207], v[70:73]
	v_mfma_f32_16x16x32_bf16 v[66:69], v[172:175], v[204:207], v[66:69]
	v_mfma_f32_16x16x32_bf16 v[118:121], v[168:171], v[184:187], v[118:121]
	v_mfma_f32_16x16x32_bf16 v[114:117], v[176:179], v[184:187], v[114:117]
	v_mfma_f32_16x16x32_bf16 v[102:105], v[168:171], v[192:195], v[102:105]
	v_mfma_f32_16x16x32_bf16 v[98:101], v[176:179], v[192:195], v[98:101]
	v_mfma_f32_16x16x32_bf16 v[86:89], v[168:171], v[200:203], v[86:89]
	v_mfma_f32_16x16x32_bf16 v[82:85], v[176:179], v[200:203], v[82:85]
	v_mfma_f32_16x16x32_bf16 v[70:73], v[168:171], v[208:211], v[70:73]
	v_mfma_f32_16x16x32_bf16 v[66:69], v[176:179], v[208:211], v[66:69]
	s_barrier
; #define PG8_STAGE(bufoff, gbase, voff) do { _Pragma("unroll") for (int _i = 0; _i < 2; ++_i) \
;         __builtin_amdgcn_global_load_lds((const unsigned*)((const char*)(gbase) + (voff)[_i]), (LAS unsigned*)(lds + (bufoff) + ldsw + _i * 8192), 16, 0, 0); } while (0)
; #define PG8_LDA(dst, b, h) do { _Pragma("unroll") for (int m = 0; m < 4; ++m) _Pragma("unroll") for (int k = 0; k < 2; ++k) dst[m][k] = *(const LAS bf16x8*)(lds + PG8_SA(b, h) + aoff + m * 2048 + k * 1024); } while (0)
; #define PG8_MMA(ai, bj, At, Bt) do { __builtin_amdgcn_s_setprio(1); _Pragma("unroll") for (int m = 0; m < 4; ++m) _Pragma("unroll") for (int n = 0; n < 2; ++n) _Pragma("unroll") for (int k = 0; k < 2; ++k) \
;         acc[ai][bj][m][n] = __builtin_amdgcn_mfma_f32_16x16x32_bf16(Bt[n][k], At[m][k], acc[ai][bj][m][n], 0, 0, 0); __builtin_amdgcn_s_setprio(0); } while (0)
; #define PG8_WAIT_V(n) asm volatile("s_waitcnt vmcnt(" #n ")" ::: "memory")
; #define PG8_WAIT_L(n) asm volatile("s_waitcnt lgkmcnt(" #n ")" ::: "memory")
; #define PG8_BAR __builtin_amdgcn_s_barrier()
; #define PG8_SCHED __builtin_amdgcn_sched_barrier(0)
; template <class Epi, bool ALIGN_EPI>
; __device__ __forceinline__ void gemm_phase(LAS unsigned char* lds, const Gemm g, const StaticOrder& S, const Epi& E) {
;     ...
;             PG8_LDA(At, 1, 1); PG8_STAGE(PG8_SB(1, 0), b3, voffB); PG8_STAGE(PG8_SB(1, 1), b3 + hsB, voffB); PG8_STAGE(PG8_SA(1, 0), a3, voffA);
;             PG8_WAIT_V(8); PG8_WAIT_L(0); PG8_BAR; PG8_MMA(1, 0, At, B0); PG8_MMA(1, 1, At, B1); PG8_BAR; PG8_SCHED;
;         }
	s_add_i32 s30, s56, s36
	v_lshl_add_u64 v[212:213], v[212:213], 0, s[8:9]
	s_mov_b32 m0, s30
	ds_read_b128 v[180:183], v147 offset:49152
	ds_read_b128 v[184:187], v147 offset:50176
	ds_read_b128 v[188:191], v147 offset:51200
	ds_read_b128 v[192:195], v147 offset:52224
	ds_read_b128 v[196:199], v147 offset:53248
	ds_read_b128 v[200:203], v147 offset:54272
	ds_read_b128 v[204:207], v147 offset:55296
	ds_read_b128 v[208:211], v147 offset:56320
	global_load_lds_dwordx4 v[212:213], off
	s_add_i32 m0, s30, 0x2000
	s_add_u32 s28, s28, 0x10080
	v_lshl_add_u64 v[212:213], v[214:215], 0, s[8:9]
	s_addc_u32 s29, s29, 0
	s_add_i32 s30, s57, s36
	global_load_lds_dwordx4 v[212:213], off
	v_lshl_add_u64 v[212:213], s[28:29], 0, v[134:135]
	s_mov_b32 m0, s30
	s_nop 0
	global_load_lds_dwordx4 v[212:213], off
	v_lshl_add_u64 v[212:213], s[28:29], 0, v[130:131]
	s_add_i32 m0, s30, 0x2000
	s_nop 0
	global_load_lds_dwordx4 v[212:213], off
	v_lshl_add_u64 v[212:213], v[216:217], 0, s[8:9]
	s_mov_b32 m0, s44
	s_nop 0
	global_load_lds_dwordx4 v[212:213], off
	v_lshl_add_u64 v[212:213], v[218:219], 0, s[8:9]
	s_mov_b32 m0, s45
	s_nop 0
	global_load_lds_dwordx4 v[212:213], off
	s_waitcnt vmcnt(8)
	s_waitcnt lgkmcnt(0)
	s_barrier
	s_waitcnt lgkmcnt(0)
	v_mfma_f32_16x16x32_bf16 v[62:65], v[148:151], v[180:183], v[62:65]
	v_mfma_f32_16x16x32_bf16 v[58:61], v[156:159], v[180:183], v[58:61]
	v_mfma_f32_16x16x32_bf16 v[46:49], v[148:151], v[188:191], v[46:49]
	v_mfma_f32_16x16x32_bf16 v[42:45], v[156:159], v[188:191], v[42:45]
	v_mfma_f32_16x16x32_bf16 v[30:33], v[148:151], v[196:199], v[30:33]
	v_mfma_f32_16x16x32_bf16 v[26:29], v[156:159], v[196:199], v[26:29]
	v_mfma_f32_16x16x32_bf16 v[14:17], v[148:151], v[204:207], v[14:17]
	v_mfma_f32_16x16x32_bf16 v[10:13], v[156:159], v[204:207], v[10:13]
	v_mfma_f32_16x16x32_bf16 v[62:65], v[152:155], v[184:187], v[62:65]
	v_mfma_f32_16x16x32_bf16 v[58:61], v[160:163], v[184:187], v[58:61]
	v_mfma_f32_16x16x32_bf16 v[46:49], v[152:155], v[192:195], v[46:49]
	v_mfma_f32_16x16x32_bf16 v[42:45], v[160:163], v[192:195], v[42:45]
	v_mfma_f32_16x16x32_bf16 v[30:33], v[152:155], v[200:203], v[30:33]
	v_mfma_f32_16x16x32_bf16 v[26:29], v[160:163], v[200:203], v[26:29]
	v_mfma_f32_16x16x32_bf16 v[14:17], v[152:155], v[208:211], v[14:17]
	v_mfma_f32_16x16x32_bf16 v[10:13], v[160:163], v[208:211], v[10:13]
	v_mfma_f32_16x16x32_bf16 v[54:57], v[164:167], v[180:183], v[54:57]
	v_mfma_f32_16x16x32_bf16 v[50:53], v[172:175], v[180:183], v[50:53]
	v_mfma_f32_16x16x32_bf16 v[38:41], v[164:167], v[188:191], v[38:41]
	v_mfma_f32_16x16x32_bf16 v[34:37], v[172:175], v[188:191], v[34:37]
	v_mfma_f32_16x16x32_bf16 v[22:25], v[164:167], v[196:199], v[22:25]
	v_mfma_f32_16x16x32_bf16 v[18:21], v[172:175], v[196:199], v[18:21]
	v_mfma_f32_16x16x32_bf16 v[6:9], v[164:167], v[204:207], v[6:9]
	v_mfma_f32_16x16x32_bf16 v[2:5], v[172:175], v[204:207], v[2:5]
	v_mfma_f32_16x16x32_bf16 v[54:57], v[168:171], v[184:187], v[54:57]
	v_mfma_f32_16x16x32_bf16 v[50:53], v[176:179], v[184:187], v[50:53]
	v_mfma_f32_16x16x32_bf16 v[38:41], v[168:171], v[192:195], v[38:41]
	v_mfma_f32_16x16x32_bf16 v[34:37], v[176:179], v[192:195], v[34:37]
	v_mfma_f32_16x16x32_bf16 v[22:25], v[168:171], v[200:203], v[22:25]
	v_mfma_f32_16x16x32_bf16 v[18:21], v[176:179], v[200:203], v[18:21]
	v_mfma_f32_16x16x32_bf16 v[6:9], v[168:171], v[208:211], v[6:9]
	v_mfma_f32_16x16x32_bf16 v[2:5], v[176:179], v[208:211], v[2:5]
	s_barrier
	s_add_u32 s26, s26, 0x100
	s_addc_u32 s27, s27, 0
	s_add_u32 s53, s53, 0x100
	s_addc_u32 s54, s54, 0
	s_cmp_ge_i32 s55, s43
	s_mov_b32 s28, s55
	s_cbranch_scc0 .LBB0_670

; #define PG8_STAGE(bufoff, gbase, voff) do { _Pragma("unroll") for (int _i = 0; _i < 2; ++_i) \
;         __builtin_amdgcn_global_load_lds((const unsigned*)((const char*)(gbase) + (voff)[_i]), (LAS unsigned*)(lds + (bufoff) + ldsw + _i * 8192), 16, 0, 0); } while (0)
; #define PG8_LDA(dst, b, h) do { _Pragma("unroll") for (int m = 0; m < 4; ++m) _Pragma("unroll") for (int k = 0; k < 2; ++k) dst[m][k] = *(const LAS bf16x8*)(lds + PG8_SA(b, h) + aoff + m * 2048 + k * 1024); } while (0)
; #define PG8_LDB(dst, b, h) do { _Pragma("unroll") for (int n = 0; n < 2; ++n) _Pragma("unroll") for (int k = 0; k < 2; ++k) dst[n][k] = *(const LAS bf16x8*)(lds + PG8_SB(b, h) + boff + n * 2048 + k * 1024); } while (0)
; #define PG8_MMA(ai, bj, At, Bt) do { __builtin_amdgcn_s_setprio(1); _Pragma("unroll") for (int m = 0; m < 4; ++m) _Pragma("unroll") for (int n = 0; n < 2; ++n) _Pragma("unroll") for (int k = 0; k < 2; ++k) \
;         acc[ai][bj][m][n] = __builtin_amdgcn_mfma_f32_16x16x32_bf16(Bt[n][k], At[m][k], acc[ai][bj][m][n], 0, 0, 0); __builtin_amdgcn_s_setprio(0); } while (0)
; #define PG8_WAIT_V(n) asm volatile("s_waitcnt vmcnt(" #n ")" ::: "memory")
; #define PG8_WAIT_L(n) asm volatile("s_waitcnt lgkmcnt(" #n ")" ::: "memory")
; #define PG8_BAR __builtin_amdgcn_s_barrier()
; #define PG8_SCHED __builtin_amdgcn_sched_barrier(0)
; template <class Epi, bool ALIGN_EPI>
; __device__ __forceinline__ void gemm_phase(LAS unsigned char* lds, const Gemm g, const StaticOrder& S, const Epi& E) {
;     ...
;             PG8_LDB(B0, 0, 0); PG8_LDB(B1, 0, 1); PG8_SCHED; PG8_LDA(At, 0, 0); PG8_STAGE(PG8_SA(1, 1), a1 + hsA, voffA);
;             PG8_WAIT_V(8); PG8_WAIT_L(0); PG8_BAR; PG8_MMA(0, 0, At, B0); PG8_MMA(0, 1, At, B1); PG8_BAR; PG8_SCHED;
;             PG8_LDA(At, 0, 1); PG8_STAGE(PG8_SB(0, 0), b2, voffB); PG8_STAGE(PG8_SB(0, 1), b2 + hsB, voffB); PG8_STAGE(PG8_SA(0, 0), a2, voffA);
;             PG8_WAIT_V(8); PG8_WAIT_L(0); PG8_BAR; PG8_MMA(1, 0, At, B0); PG8_MMA(1, 1, At, B1); PG8_BAR; PG8_SCHED;
.LBB0_948:
	ds_read_b128 v[154:157], v151
	ds_read_b128 v[158:161], v151 offset:1024
	ds_read_b128 v[162:165], v151 offset:2048
	ds_read_b128 v[166:169], v151 offset:3072
	ds_read_b128 v[170:173], v152
	ds_read_b128 v[174:177], v152 offset:1024
	ds_read_b128 v[178:181], v152 offset:2048
	ds_read_b128 v[182:185], v152 offset:3072
	s_add_u32 s26, s24, 0xfffe0080
	s_addc_u32 s27, s25, -1
	s_cmp_eq_u32 s21, 4
	s_cselect_b32 s29, s5, s27
	s_cselect_b32 s28, s4, s26
	s_cselect_b32 s27, s23, s19
	s_cselect_b32 s26, s22, s17
	v_lshl_add_u64 v[218:219], s[24:25], 0, v[140:141]
	s_add_i32 m0, s30, 0xc000
	ds_read_b128 v[186:189], v153
	ds_read_b128 v[190:193], v153 offset:1024
	ds_read_b128 v[194:197], v153 offset:2048
	ds_read_b128 v[198:201], v153 offset:3072
	ds_read_b128 v[202:205], v153 offset:4096
	ds_read_b128 v[206:209], v153 offset:5120
	ds_read_b128 v[210:213], v153 offset:6144
	ds_read_b128 v[214:217], v153 offset:7168
	global_load_lds_dwordx4 v[218:219], off
	v_lshl_add_u64 v[218:219], s[24:25], 0, v[142:143]
	s_add_i32 m0, s30, 0xe000
	s_nop 0
	global_load_lds_dwordx4 v[218:219], off
	s_waitcnt vmcnt(8)
	s_waitcnt lgkmcnt(0)
	s_barrier
	s_waitcnt lgkmcnt(0)
	v_mfma_f32_16x16x32_bf16 v[126:129], v[154:157], v[186:189], v[126:129]
	v_mfma_f32_16x16x32_bf16 v[122:125], v[162:165], v[186:189], v[122:125]
	v_mfma_f32_16x16x32_bf16 v[110:113], v[154:157], v[194:197], v[110:113]
	v_mfma_f32_16x16x32_bf16 v[106:109], v[162:165], v[194:197], v[106:109]
	v_mfma_f32_16x16x32_bf16 v[94:97], v[154:157], v[202:205], v[94:97]
	v_mfma_f32_16x16x32_bf16 v[90:93], v[162:165], v[202:205], v[90:93]
	v_mfma_f32_16x16x32_bf16 v[78:81], v[154:157], v[210:213], v[78:81]
	v_mfma_f32_16x16x32_bf16 v[74:77], v[162:165], v[210:213], v[74:77]
	v_mfma_f32_16x16x32_bf16 v[126:129], v[158:161], v[190:193], v[126:129]
	v_mfma_f32_16x16x32_bf16 v[122:125], v[166:169], v[190:193], v[122:125]
	v_mfma_f32_16x16x32_bf16 v[110:113], v[158:161], v[198:201], v[110:113]
	v_mfma_f32_16x16x32_bf16 v[106:109], v[166:169], v[198:201], v[106:109]
	v_mfma_f32_16x16x32_bf16 v[94:97], v[158:161], v[206:209], v[94:97]
	v_mfma_f32_16x16x32_bf16 v[90:93], v[166:169], v[206:209], v[90:93]
	v_mfma_f32_16x16x32_bf16 v[78:81], v[158:161], v[214:217], v[78:81]
	v_mfma_f32_16x16x32_bf16 v[74:77], v[166:169], v[214:217], v[74:77]
	v_mfma_f32_16x16x32_bf16 v[118:121], v[170:173], v[186:189], v[118:121]
	v_mfma_f32_16x16x32_bf16 v[114:117], v[178:181], v[186:189], v[114:117]
	v_mfma_f32_16x16x32_bf16 v[102:105], v[170:173], v[194:197], v[102:105]
	v_mfma_f32_16x16x32_bf16 v[98:101], v[178:181], v[194:197], v[98:101]
	v_mfma_f32_16x16x32_bf16 v[86:89], v[170:173], v[202:205], v[86:89]
	v_mfma_f32_16x16x32_bf16 v[82:85], v[178:181], v[202:205], v[82:85]
	v_mfma_f32_16x16x32_bf16 v[70:73], v[170:173], v[210:213], v[70:73]
	v_mfma_f32_16x16x32_bf16 v[66:69], v[178:181], v[210:213], v[66:69]
	v_mfma_f32_16x16x32_bf16 v[118:121], v[174:177], v[190:193], v[118:121]
	v_mfma_f32_16x16x32_bf16 v[114:117], v[182:185], v[190:193], v[114:117]
	v_mfma_f32_16x16x32_bf16 v[102:105], v[174:177], v[198:201], v[102:105]
	v_mfma_f32_16x16x32_bf16 v[98:101], v[182:185], v[198:201], v[98:101]
	v_mfma_f32_16x16x32_bf16 v[86:89], v[174:177], v[206:209], v[86:89]
	v_mfma_f32_16x16x32_bf16 v[82:85], v[182:185], v[206:209], v[82:85]
	v_mfma_f32_16x16x32_bf16 v[70:73], v[174:177], v[214:217], v[70:73]
	v_mfma_f32_16x16x32_bf16 v[66:69], v[182:185], v[214:217], v[66:69]
	s_barrier
	s_add_i32 s42, s39, s15
	v_lshl_add_u64 v[218:219], s[26:27], 0, v[134:135]
	s_mov_b32 m0, s42
	ds_read_b128 v[186:189], v153 offset:16384
	ds_read_b128 v[190:193], v153 offset:17408
	ds_read_b128 v[194:197], v153 offset:18432
	ds_read_b128 v[198:201], v153 offset:19456
	ds_read_b128 v[202:205], v153 offset:20480
	ds_read_b128 v[206:209], v153 offset:21504
	ds_read_b128 v[210:213], v153 offset:22528
	ds_read_b128 v[214:217], v153 offset:23552
	global_load_lds_dwordx4 v[218:219], off
	s_add_i32 m0, s42, 0x2000
	s_add_u32 s42, s26, 0x20000
	v_lshl_add_u64 v[220:221], s[26:27], 0, v[130:131]
	s_addc_u32 s43, s27, 0
	s_add_i32 s44, s40, s15
	global_load_lds_dwordx4 v[220:221], off
	v_lshl_add_u64 v[222:223], s[42:43], 0, v[134:135]
	s_mov_b32 m0, s44
	v_lshl_add_u64 v[224:225], s[28:29], 0, v[132:133]
	global_load_lds_dwordx4 v[222:223], off
	v_lshl_add_u64 v[222:223], s[42:43], 0, v[130:131]
	s_add_i32 m0, s44, 0x2000
	s_nop 0
	global_load_lds_dwordx4 v[222:223], off
	v_lshl_add_u64 v[222:223], s[28:29], 0, v[136:137]
	s_mov_b32 m0, s30
	s_nop 0
	global_load_lds_dwordx4 v[222:223], off
	s_mov_b32 m0, s31
	s_nop 0
	global_load_lds_dwordx4 v[224:225], off
	s_waitcnt vmcnt(8)
	s_waitcnt lgkmcnt(0)
	s_barrier
; #define PG8_STAGE(bufoff, gbase, voff) do { _Pragma("unroll") for (int _i = 0; _i < 2; ++_i) \
;         __builtin_amdgcn_global_load_lds((const unsigned*)((const char*)(gbase) + (voff)[_i]), (LAS unsigned*)(lds + (bufoff) + ldsw + _i * 8192), 16, 0, 0); } while (0)
; #define PG8_LDA(dst, b, h) do { _Pragma("unroll") for (int m = 0; m < 4; ++m) _Pragma("unroll") for (int k = 0; k < 2; ++k) dst[m][k] = *(const LAS bf16x8*)(lds + PG8_SA(b, h) + aoff + m * 2048 + k * 1024); } while (0)
; #define PG8_LDB(dst, b, h) do { _Pragma("unroll") for (int n = 0; n < 2; ++n) _Pragma("unroll") for (int k = 0; k < 2; ++k) dst[n][k] = *(const LAS bf16x8*)(lds + PG8_SB(b, h) + boff + n * 2048 + k * 1024); } while (0)
; #define PG8_MMA(ai, bj, At, Bt) do { __builtin_amdgcn_s_setprio(1); _Pragma("unroll") for (int m = 0; m < 4; ++m) _Pragma("unroll") for (int n = 0; n < 2; ++n) _Pragma("unroll") for (int k = 0; k < 2; ++k) \
;         acc[ai][bj][m][n] = __builtin_amdgcn_mfma_f32_16x16x32_bf16(Bt[n][k], At[m][k], acc[ai][bj][m][n], 0, 0, 0); __builtin_amdgcn_s_setprio(0); } while (0)
; #define PG8_WAIT_V(n) asm volatile("s_waitcnt vmcnt(" #n ")" ::: "memory")
; #define PG8_WAIT_L(n) asm volatile("s_waitcnt lgkmcnt(" #n ")" ::: "memory")
; #define PG8_BAR __builtin_amdgcn_s_barrier()
; #define PG8_SCHED __builtin_amdgcn_sched_barrier(0)
; template <class Epi, bool ALIGN_EPI>
; __device__ __forceinline__ void gemm_phase(LAS unsigned char* lds, const Gemm g, const StaticOrder& S, const Epi& E) {
;     ...
;             PG8_WAIT_V(8); PG8_WAIT_L(0); PG8_BAR; PG8_MMA(1, 0, At, B0); PG8_MMA(1, 1, At, B1); PG8_BAR; PG8_SCHED;
;             PG8_LDB(B0, 1, 0); PG8_LDB(B1, 1, 1); PG8_SCHED; PG8_LDA(At, 1, 0); PG8_STAGE(PG8_SA(0, 1), a2 + hsA, voffA);
;             PG8_WAIT_V(8); PG8_WAIT_L(0); PG8_BAR; PG8_MMA(0, 0, At, B0); PG8_MMA(0, 1, At, B1); PG8_BAR; PG8_SCHED;
	s_waitcnt lgkmcnt(0)
	v_mfma_f32_16x16x32_bf16 v[62:65], v[154:157], v[186:189], v[62:65]
	v_mfma_f32_16x16x32_bf16 v[58:61], v[162:165], v[186:189], v[58:61]
	v_mfma_f32_16x16x32_bf16 v[46:49], v[154:157], v[194:197], v[46:49]
	v_mfma_f32_16x16x32_bf16 v[42:45], v[162:165], v[194:197], v[42:45]
	v_mfma_f32_16x16x32_bf16 v[30:33], v[154:157], v[202:205], v[30:33]
	v_mfma_f32_16x16x32_bf16 v[26:29], v[162:165], v[202:205], v[26:29]
	v_mfma_f32_16x16x32_bf16 v[14:17], v[154:157], v[210:213], v[14:17]
	v_mfma_f32_16x16x32_bf16 v[10:13], v[162:165], v[210:213], v[10:13]
	v_mfma_f32_16x16x32_bf16 v[62:65], v[158:161], v[190:193], v[62:65]
	v_mfma_f32_16x16x32_bf16 v[58:61], v[166:169], v[190:193], v[58:61]
	v_mfma_f32_16x16x32_bf16 v[46:49], v[158:161], v[198:201], v[46:49]
	v_mfma_f32_16x16x32_bf16 v[42:45], v[166:169], v[198:201], v[42:45]
	v_mfma_f32_16x16x32_bf16 v[30:33], v[158:161], v[206:209], v[30:33]
	v_mfma_f32_16x16x32_bf16 v[26:29], v[166:169], v[206:209], v[26:29]
	v_mfma_f32_16x16x32_bf16 v[14:17], v[158:161], v[214:217], v[14:17]
	v_mfma_f32_16x16x32_bf16 v[10:13], v[166:169], v[214:217], v[10:13]
	v_mfma_f32_16x16x32_bf16 v[54:57], v[170:173], v[186:189], v[54:57]
	v_mfma_f32_16x16x32_bf16 v[50:53], v[178:181], v[186:189], v[50:53]
	v_mfma_f32_16x16x32_bf16 v[38:41], v[170:173], v[194:197], v[38:41]
	v_mfma_f32_16x16x32_bf16 v[34:37], v[178:181], v[194:197], v[34:37]
	v_mfma_f32_16x16x32_bf16 v[22:25], v[170:173], v[202:205], v[22:25]
	v_mfma_f32_16x16x32_bf16 v[18:21], v[178:181], v[202:205], v[18:21]
	v_mfma_f32_16x16x32_bf16 v[6:9], v[170:173], v[210:213], v[6:9]
	v_mfma_f32_16x16x32_bf16 v[2:5], v[178:181], v[210:213], v[2:5]
	v_mfma_f32_16x16x32_bf16 v[54:57], v[174:177], v[190:193], v[54:57]
	v_mfma_f32_16x16x32_bf16 v[50:53], v[182:185], v[190:193], v[50:53]
	v_mfma_f32_16x16x32_bf16 v[38:41], v[174:177], v[198:201], v[38:41]
	v_mfma_f32_16x16x32_bf16 v[34:37], v[182:185], v[198:201], v[34:37]
	v_mfma_f32_16x16x32_bf16 v[22:25], v[174:177], v[206:209], v[22:25]
	v_mfma_f32_16x16x32_bf16 v[18:21], v[182:185], v[206:209], v[18:21]
	v_mfma_f32_16x16x32_bf16 v[6:9], v[174:177], v[214:217], v[6:9]
	v_mfma_f32_16x16x32_bf16 v[2:5], v[182:185], v[214:217], v[2:5]
	s_barrier
	s_add_i32 s42, 0, 0x18000
	s_add_i32 s43, 0, 0x1c000
	v_add_u32_e32 v166, s42, v1
	v_add_u32_e32 v182, s43, v1
	ds_read_b128 v[154:157], v166
	ds_read_b128 v[158:161], v166 offset:1024
	ds_read_b128 v[162:165], v166 offset:2048
	ds_read_b128 v[166:169], v166 offset:3072
	ds_read_b128 v[170:173], v182
	ds_read_b128 v[174:177], v182 offset:1024
	ds_read_b128 v[178:181], v182 offset:2048
	ds_read_b128 v[182:185], v182 offset:3072
	s_add_u32 s28, s28, 0x20000
	s_addc_u32 s29, s29, 0
	s_mov_b32 m0, s33
	v_lshl_add_u64 v[226:227], s[28:29], 0, v[136:137]
	ds_read_b128 v[186:189], v153 offset:32768
	ds_read_b128 v[190:193], v153 offset:33792
	ds_read_b128 v[194:197], v153 offset:34816
	ds_read_b128 v[198:201], v153 offset:35840
	ds_read_b128 v[202:205], v153 offset:36864
	ds_read_b128 v[206:209], v153 offset:37888
	ds_read_b128 v[210:213], v153 offset:38912
	ds_read_b128 v[214:217], v153 offset:39936
	global_load_lds_dwordx4 v[226:227], off
	v_lshl_add_u64 v[226:227], s[28:29], 0, v[132:133]
	s_mov_b32 m0, s34
	s_nop 0
	global_load_lds_dwordx4 v[226:227], off
	s_waitcnt vmcnt(8)
	s_waitcnt lgkmcnt(0)
	s_barrier
	s_waitcnt lgkmcnt(0)
	v_mfma_f32_16x16x32_bf16 v[126:129], v[154:157], v[186:189], v[126:129]
	v_mfma_f32_16x16x32_bf16 v[122:125], v[162:165], v[186:189], v[122:125]
	v_mfma_f32_16x16x32_bf16 v[110:113], v[154:157], v[194:197], v[110:113]
	v_mfma_f32_16x16x32_bf16 v[106:109], v[162:165], v[194:197], v[106:109]
	v_mfma_f32_16x16x32_bf16 v[94:97], v[154:157], v[202:205], v[94:97]
	v_mfma_f32_16x16x32_bf16 v[90:93], v[162:165], v[202:205], v[90:93]
	v_mfma_f32_16x16x32_bf16 v[78:81], v[154:157], v[210:213], v[78:81]
	v_mfma_f32_16x16x32_bf16 v[74:77], v[162:165], v[210:213], v[74:77]
	v_mfma_f32_16x16x32_bf16 v[126:129], v[158:161], v[190:193], v[126:129]
	v_mfma_f32_16x16x32_bf16 v[122:125], v[166:169], v[190:193], v[122:125]
	v_mfma_f32_16x16x32_bf16 v[110:113], v[158:161], v[198:201], v[110:113]
	v_mfma_f32_16x16x32_bf16 v[106:109], v[166:169], v[198:201], v[106:109]
	v_mfma_f32_16x16x32_bf16 v[94:97], v[158:161], v[206:209], v[94:97]
	v_mfma_f32_16x16x32_bf16 v[90:93], v[166:169], v[206:209], v[90:93]
	v_mfma_f32_16x16x32_bf16 v[78:81], v[158:161], v[214:217], v[78:81]
	v_mfma_f32_16x16x32_bf16 v[74:77], v[166:169], v[214:217], v[74:77]
	v_mfma_f32_16x16x32_bf16 v[118:121], v[170:173], v[186:189], v[118:121]
	v_mfma_f32_16x16x32_bf16 v[114:117], v[178:181], v[186:189], v[114:117]
	v_mfma_f32_16x16x32_bf16 v[102:105], v[170:173], v[194:197], v[102:105]
	v_mfma_f32_16x16x32_bf16 v[98:101], v[178:181], v[194:197], v[98:101]
	v_mfma_f32_16x16x32_bf16 v[86:89], v[170:173], v[202:205], v[86:89]
	v_mfma_f32_16x16x32_bf16 v[82:85], v[178:181], v[202:205], v[82:85]
	v_mfma_f32_16x16x32_bf16 v[70:73], v[170:173], v[210:213], v[70:73]
	v_mfma_f32_16x16x32_bf16 v[66:69], v[178:181], v[210:213], v[66:69]
	v_mfma_f32_16x16x32_bf16 v[118:121], v[174:177], v[190:193], v[118:121]
	v_mfma_f32_16x16x32_bf16 v[114:117], v[182:185], v[190:193], v[114:117]
	v_mfma_f32_16x16x32_bf16 v[102:105], v[174:177], v[198:201], v[102:105]
	v_mfma_f32_16x16x32_bf16 v[98:101], v[182:185], v[198:201], v[98:101]
	v_mfma_f32_16x16x32_bf16 v[86:89], v[174:177], v[206:209], v[86:89]
	v_mfma_f32_16x16x32_bf16 v[82:85], v[182:185], v[206:209], v[82:85]
	v_mfma_f32_16x16x32_bf16 v[70:73], v[174:177], v[214:217], v[70:73]
	v_mfma_f32_16x16x32_bf16 v[66:69], v[182:185], v[214:217], v[66:69]
	s_barrier
; #define PG8_STAGE(bufoff, gbase, voff) do { _Pragma("unroll") for (int _i = 0; _i < 2; ++_i) \
;         __builtin_amdgcn_global_load_lds((const unsigned*)((const char*)(gbase) + (voff)[_i]), (LAS unsigned*)(lds + (bufoff) + ldsw + _i * 8192), 16, 0, 0); } while (0)
; #define PG8_LDA(dst, b, h) do { _Pragma("unroll") for (int m = 0; m < 4; ++m) _Pragma("unroll") for (int k = 0; k < 2; ++k) dst[m][k] = *(const LAS bf16x8*)(lds + PG8_SA(b, h) + aoff + m * 2048 + k * 1024); } while (0)
; #define PG8_MMA(ai, bj, At, Bt) do { __builtin_amdgcn_s_setprio(1); _Pragma("unroll") for (int m = 0; m < 4; ++m) _Pragma("unroll") for (int n = 0; n < 2; ++n) _Pragma("unroll") for (int k = 0; k < 2; ++k) \
;         acc[ai][bj][m][n] = __builtin_amdgcn_mfma_f32_16x16x32_bf16(Bt[n][k], At[m][k], acc[ai][bj][m][n], 0, 0, 0); __builtin_amdgcn_s_setprio(0); } while (0)
; #define PG8_WAIT_V(n) asm volatile("s_waitcnt vmcnt(" #n ")" ::: "memory")
; #define PG8_WAIT_L(n) asm volatile("s_waitcnt lgkmcnt(" #n ")" ::: "memory")
; #define PG8_BAR __builtin_amdgcn_s_barrier()
; #define PG8_SCHED __builtin_amdgcn_sched_barrier(0)
; template <class Epi, bool ALIGN_EPI>
; __device__ __forceinline__ void gemm_phase(LAS unsigned char* lds, const Gemm g, const StaticOrder& S, const Epi& E) {
;     ...
;             PG8_LDA(At, 1, 1); PG8_STAGE(PG8_SB(1, 0), b3, voffB); PG8_STAGE(PG8_SB(1, 1), b3 + hsB, voffB); PG8_STAGE(PG8_SA(1, 0), a3, voffA);
;             PG8_WAIT_V(8); PG8_WAIT_L(0); PG8_BAR; PG8_MMA(1, 0, At, B0); PG8_MMA(1, 1, At, B1); PG8_BAR; PG8_SCHED;
;         }
	s_add_i32 s28, s42, s15
	v_lshl_add_u64 v[218:219], v[218:219], 0, s[8:9]
	s_mov_b32 m0, s28
	ds_read_b128 v[186:189], v153 offset:49152
	ds_read_b128 v[190:193], v153 offset:50176
	ds_read_b128 v[194:197], v153 offset:51200
	ds_read_b128 v[198:201], v153 offset:52224
	ds_read_b128 v[202:205], v153 offset:53248
	ds_read_b128 v[206:209], v153 offset:54272
	ds_read_b128 v[210:213], v153 offset:55296
	ds_read_b128 v[214:217], v153 offset:56320
	global_load_lds_dwordx4 v[218:219], off
	s_add_i32 m0, s28, 0x2000
	s_add_u32 s26, s26, 0x20080
	v_lshl_add_u64 v[218:219], v[220:221], 0, s[8:9]
	s_addc_u32 s27, s27, 0
	s_add_i32 s28, s43, s15
	global_load_lds_dwordx4 v[218:219], off
	v_lshl_add_u64 v[218:219], s[26:27], 0, v[134:135]
	s_mov_b32 m0, s28
	s_nop 0
	global_load_lds_dwordx4 v[218:219], off
	v_lshl_add_u64 v[218:219], s[26:27], 0, v[130:131]
	s_add_i32 m0, s28, 0x2000
	s_nop 0
	global_load_lds_dwordx4 v[218:219], off
	v_lshl_add_u64 v[218:219], v[222:223], 0, s[8:9]
	s_mov_b32 m0, s36
	s_nop 0
	global_load_lds_dwordx4 v[218:219], off
	v_lshl_add_u64 v[218:219], v[224:225], 0, s[8:9]
	s_mov_b32 m0, s37
	s_nop 0
	global_load_lds_dwordx4 v[218:219], off
	s_waitcnt vmcnt(8)
	s_waitcnt lgkmcnt(0)
	s_barrier
	s_waitcnt lgkmcnt(0)
	v_mfma_f32_16x16x32_bf16 v[62:65], v[154:157], v[186:189], v[62:65]
	v_mfma_f32_16x16x32_bf16 v[58:61], v[162:165], v[186:189], v[58:61]
	v_mfma_f32_16x16x32_bf16 v[46:49], v[154:157], v[194:197], v[46:49]
	v_mfma_f32_16x16x32_bf16 v[42:45], v[162:165], v[194:197], v[42:45]
	v_mfma_f32_16x16x32_bf16 v[30:33], v[154:157], v[202:205], v[30:33]
	v_mfma_f32_16x16x32_bf16 v[26:29], v[162:165], v[202:205], v[26:29]
	v_mfma_f32_16x16x32_bf16 v[14:17], v[154:157], v[210:213], v[14:17]
	v_mfma_f32_16x16x32_bf16 v[10:13], v[162:165], v[210:213], v[10:13]
	v_mfma_f32_16x16x32_bf16 v[62:65], v[158:161], v[190:193], v[62:65]
	v_mfma_f32_16x16x32_bf16 v[58:61], v[166:169], v[190:193], v[58:61]
	v_mfma_f32_16x16x32_bf16 v[46:49], v[158:161], v[198:201], v[46:49]
	v_mfma_f32_16x16x32_bf16 v[42:45], v[166:169], v[198:201], v[42:45]
	v_mfma_f32_16x16x32_bf16 v[30:33], v[158:161], v[206:209], v[30:33]
	v_mfma_f32_16x16x32_bf16 v[26:29], v[166:169], v[206:209], v[26:29]
	v_mfma_f32_16x16x32_bf16 v[14:17], v[158:161], v[214:217], v[14:17]
	v_mfma_f32_16x16x32_bf16 v[10:13], v[166:169], v[214:217], v[10:13]
	v_mfma_f32_16x16x32_bf16 v[54:57], v[170:173], v[186:189], v[54:57]
	v_mfma_f32_16x16x32_bf16 v[50:53], v[178:181], v[186:189], v[50:53]
	v_mfma_f32_16x16x32_bf16 v[38:41], v[170:173], v[194:197], v[38:41]
	v_mfma_f32_16x16x32_bf16 v[34:37], v[178:181], v[194:197], v[34:37]
	v_mfma_f32_16x16x32_bf16 v[22:25], v[170:173], v[202:205], v[22:25]
	v_mfma_f32_16x16x32_bf16 v[18:21], v[178:181], v[202:205], v[18:21]
	v_mfma_f32_16x16x32_bf16 v[6:9], v[170:173], v[210:213], v[6:9]
	v_mfma_f32_16x16x32_bf16 v[2:5], v[178:181], v[210:213], v[2:5]
	v_mfma_f32_16x16x32_bf16 v[54:57], v[174:177], v[190:193], v[54:57]
	v_mfma_f32_16x16x32_bf16 v[50:53], v[182:185], v[190:193], v[50:53]
	v_mfma_f32_16x16x32_bf16 v[38:41], v[174:177], v[198:201], v[38:41]
	v_mfma_f32_16x16x32_bf16 v[34:37], v[182:185], v[198:201], v[34:37]
	v_mfma_f32_16x16x32_bf16 v[22:25], v[174:177], v[206:209], v[22:25]
	v_mfma_f32_16x16x32_bf16 v[18:21], v[182:185], v[206:209], v[18:21]
	v_mfma_f32_16x16x32_bf16 v[6:9], v[174:177], v[214:217], v[6:9]
	v_mfma_f32_16x16x32_bf16 v[2:5], v[182:185], v[214:217], v[2:5]
	s_barrier
	s_add_i32 s21, s21, 2
	s_add_u32 s24, s24, 0x100
	s_addc_u32 s25, s25, 0
	s_add_u32 s17, s17, 0x100
	s_addc_u32 s19, s19, 0
	s_cmp_gt_u32 s21, 5
	s_cbranch_scc0 .LBB0_948
	s_and_b64 vcc, exec, s[10:11]
	s_cbranch_vccz .LBB0_951
	s_barrier

; #define PG8_STAGE(bufoff, gbase, voff) do { _Pragma("unroll") for (int _i = 0; _i < 2; ++_i) \
;         __builtin_amdgcn_global_load_lds((const unsigned*)((const char*)(gbase) + (voff)[_i]), (LAS unsigned*)(lds + (bufoff) + ldsw + _i * 8192), 16, 0, 0); } while (0)
; #define PG8_LDA(dst, b, h) do { _Pragma("unroll") for (int m = 0; m < 4; ++m) _Pragma("unroll") for (int k = 0; k < 2; ++k) dst[m][k] = *(const LAS bf16x8*)(lds + PG8_SA(b, h) + aoff + m * 2048 + k * 1024); } while (0)
; #define PG8_LDB(dst, b, h) do { _Pragma("unroll") for (int n = 0; n < 2; ++n) _Pragma("unroll") for (int k = 0; k < 2; ++k) dst[n][k] = *(const LAS bf16x8*)(lds + PG8_SB(b, h) + boff + n * 2048 + k * 1024); } while (0)
; #define PG8_MMA(ai, bj, At, Bt) do { __builtin_amdgcn_s_setprio(1); _Pragma("unroll") for (int m = 0; m < 4; ++m) _Pragma("unroll") for (int n = 0; n < 2; ++n) _Pragma("unroll") for (int k = 0; k < 2; ++k) \
;         acc[ai][bj][m][n] = __builtin_amdgcn_mfma_f32_16x16x32_bf16(Bt[n][k], At[m][k], acc[ai][bj][m][n], 0, 0, 0); __builtin_amdgcn_s_setprio(0); } while (0)
; #define PG8_WAIT_V(n) asm volatile("s_waitcnt vmcnt(" #n ")" ::: "memory")
; #define PG8_WAIT_L(n) asm volatile("s_waitcnt lgkmcnt(" #n ")" ::: "memory")
; #define PG8_BAR __builtin_amdgcn_s_barrier()
; #define PG8_SCHED __builtin_amdgcn_sched_barrier(0)
; template <class Epi, bool ALIGN_EPI>
; __device__ __forceinline__ void gemm_phase(LAS unsigned char* lds, const Gemm g, const StaticOrder& S, const Epi& E) {
;     ...
;             PG8_LDB(B0, 0, 0); PG8_LDB(B1, 0, 1); PG8_SCHED; PG8_LDA(At, 0, 0); PG8_STAGE(PG8_SA(1, 1), a1 + hsA, voffA);
;             PG8_WAIT_V(8); PG8_WAIT_L(0); PG8_BAR; PG8_MMA(0, 0, At, B0); PG8_MMA(0, 1, At, B1); PG8_BAR; PG8_SCHED;
;             PG8_LDA(At, 0, 1); PG8_STAGE(PG8_SB(0, 0), b2, voffB); PG8_STAGE(PG8_SB(0, 1), b2 + hsB, voffB); PG8_STAGE(PG8_SA(0, 0), a2, voffA);
;             PG8_WAIT_V(8); PG8_WAIT_L(0); PG8_BAR; PG8_MMA(1, 0, At, B0); PG8_MMA(1, 1, At, B1); PG8_BAR; PG8_SCHED;
.LBB0_1027:
	ds_read_b128 v[74:77], v232
	ds_read_b128 v[82:85], v232 offset:1024
	ds_read_b128 v[90:93], v232 offset:2048
	ds_read_b128 v[98:101], v232 offset:3072
	ds_read_b128 v[106:109], v233
	ds_read_b128 v[114:117], v233 offset:1024
	ds_read_b128 v[130:133], v233 offset:2048
	ds_read_b128 v[138:141], v233 offset:3072
	s_add_u32 s30, s26, 0xfffe0080
	s_addc_u32 s31, s27, -1
	s_cmp_eq_u32 s51, 4
	s_cselect_b32 s35, s9, s31
	s_cselect_b32 s34, s47, s30
	s_cselect_b32 s31, s21, s50
	s_cselect_b32 s30, s48, s49
	v_lshl_add_u64 v[194:195], s[26:27], 0, v[206:207]
	s_add_i32 m0, s25, 0xc000
	ds_read_b128 v[154:157], v234
	ds_read_b128 v[166:169], v234 offset:1024
	ds_read_b128 v[170:173], v234 offset:2048
	ds_read_b128 v[174:177], v234 offset:3072
	ds_read_b128 v[178:181], v234 offset:4096
	ds_read_b128 v[182:185], v234 offset:5120
	ds_read_b128 v[186:189], v234 offset:6144
	ds_read_b128 v[190:193], v234 offset:7168
	global_load_lds_dwordx4 v[194:195], off
	v_lshl_add_u64 v[194:195], s[26:27], 0, v[208:209]
	s_add_i32 m0, s25, 0xe000
	s_nop 0
	global_load_lds_dwordx4 v[194:195], off
	s_waitcnt vmcnt(8)
	s_waitcnt lgkmcnt(0)
	s_barrier
	s_waitcnt lgkmcnt(0)
	v_mfma_f32_16x16x32_bf16 v[162:165], v[74:77], v[154:157], v[162:165]
	v_mfma_f32_16x16x32_bf16 v[158:161], v[90:93], v[154:157], v[158:161]
	v_mfma_f32_16x16x32_bf16 v[142:145], v[74:77], v[170:173], v[142:145]
	v_mfma_f32_16x16x32_bf16 v[134:137], v[90:93], v[170:173], v[134:137]
	v_mfma_f32_16x16x32_bf16 v[118:121], v[74:77], v[178:181], v[118:121]
	v_mfma_f32_16x16x32_bf16 v[110:113], v[90:93], v[178:181], v[110:113]
	v_mfma_f32_16x16x32_bf16 v[86:89], v[74:77], v[186:189], v[86:89]
	v_mfma_f32_16x16x32_bf16 v[78:81], v[90:93], v[186:189], v[78:81]
	v_mfma_f32_16x16x32_bf16 v[162:165], v[82:85], v[166:169], v[162:165]
	v_mfma_f32_16x16x32_bf16 v[158:161], v[98:101], v[166:169], v[158:161]
	v_mfma_f32_16x16x32_bf16 v[142:145], v[82:85], v[174:177], v[142:145]
	v_mfma_f32_16x16x32_bf16 v[134:137], v[98:101], v[174:177], v[134:137]
	v_mfma_f32_16x16x32_bf16 v[118:121], v[82:85], v[182:185], v[118:121]
	v_mfma_f32_16x16x32_bf16 v[110:113], v[98:101], v[182:185], v[110:113]
	v_mfma_f32_16x16x32_bf16 v[86:89], v[82:85], v[190:193], v[86:89]
	v_mfma_f32_16x16x32_bf16 v[78:81], v[98:101], v[190:193], v[78:81]
	v_mfma_f32_16x16x32_bf16 v[150:153], v[106:109], v[154:157], v[150:153]
	v_mfma_f32_16x16x32_bf16 v[146:149], v[130:133], v[154:157], v[146:149]
	v_mfma_f32_16x16x32_bf16 v[126:129], v[106:109], v[170:173], v[126:129]
	v_mfma_f32_16x16x32_bf16 v[122:125], v[130:133], v[170:173], v[122:125]
	v_mfma_f32_16x16x32_bf16 v[102:105], v[106:109], v[178:181], v[102:105]
	v_mfma_f32_16x16x32_bf16 v[94:97], v[130:133], v[178:181], v[94:97]
	v_mfma_f32_16x16x32_bf16 v[70:73], v[106:109], v[186:189], v[70:73]
	v_mfma_f32_16x16x32_bf16 v[66:69], v[130:133], v[186:189], v[66:69]
	v_mfma_f32_16x16x32_bf16 v[150:153], v[114:117], v[166:169], v[150:153]
	v_mfma_f32_16x16x32_bf16 v[146:149], v[138:141], v[166:169], v[146:149]
	v_mfma_f32_16x16x32_bf16 v[126:129], v[114:117], v[174:177], v[126:129]
	v_mfma_f32_16x16x32_bf16 v[122:125], v[138:141], v[174:177], v[122:125]
	v_mfma_f32_16x16x32_bf16 v[102:105], v[114:117], v[182:185], v[102:105]
	v_mfma_f32_16x16x32_bf16 v[94:97], v[138:141], v[182:185], v[94:97]
	v_mfma_f32_16x16x32_bf16 v[70:73], v[114:117], v[190:193], v[70:73]
	v_mfma_f32_16x16x32_bf16 v[66:69], v[138:141], v[190:193], v[66:69]
	s_barrier
	s_add_i32 s52, s44, s33
	v_lshl_add_u64 v[194:195], s[30:31], 0, v[200:201]
	s_mov_b32 m0, s52
	ds_read_b128 v[154:157], v234 offset:16384
	ds_read_b128 v[166:169], v234 offset:17408
	ds_read_b128 v[170:173], v234 offset:18432
	ds_read_b128 v[174:177], v234 offset:19456
	ds_read_b128 v[178:181], v234 offset:20480
	ds_read_b128 v[182:185], v234 offset:21504
	ds_read_b128 v[186:189], v234 offset:22528
	ds_read_b128 v[190:193], v234 offset:23552
	global_load_lds_dwordx4 v[194:195], off
	s_add_i32 m0, s52, 0x2000
	s_add_u32 s52, s30, 0x20000
	v_lshl_add_u64 v[196:197], s[30:31], 0, v[204:205]
	s_addc_u32 s53, s31, 0
	s_add_i32 s54, s45, s33
	global_load_lds_dwordx4 v[196:197], off
	v_lshl_add_u64 v[214:215], s[52:53], 0, v[200:201]
	s_mov_b32 m0, s54
	v_lshl_add_u64 v[216:217], s[34:35], 0, v[202:203]
	global_load_lds_dwordx4 v[214:215], off
	v_lshl_add_u64 v[214:215], s[52:53], 0, v[204:205]
	s_add_i32 m0, s54, 0x2000
	s_nop 0
	global_load_lds_dwordx4 v[214:215], off
	v_lshl_add_u64 v[214:215], s[34:35], 0, v[198:199]
	s_mov_b32 m0, s25
	s_nop 0
	global_load_lds_dwordx4 v[214:215], off
	s_mov_b32 m0, s36
	s_nop 0
	global_load_lds_dwordx4 v[216:217], off
	s_waitcnt vmcnt(8)
	s_waitcnt lgkmcnt(0)
	s_barrier
; #define PG8_STAGE(bufoff, gbase, voff) do { _Pragma("unroll") for (int _i = 0; _i < 2; ++_i) \
;         __builtin_amdgcn_global_load_lds((const unsigned*)((const char*)(gbase) + (voff)[_i]), (LAS unsigned*)(lds + (bufoff) + ldsw + _i * 8192), 16, 0, 0); } while (0)
; #define PG8_LDA(dst, b, h) do { _Pragma("unroll") for (int m = 0; m < 4; ++m) _Pragma("unroll") for (int k = 0; k < 2; ++k) dst[m][k] = *(const LAS bf16x8*)(lds + PG8_SA(b, h) + aoff + m * 2048 + k * 1024); } while (0)
; #define PG8_LDB(dst, b, h) do { _Pragma("unroll") for (int n = 0; n < 2; ++n) _Pragma("unroll") for (int k = 0; k < 2; ++k) dst[n][k] = *(const LAS bf16x8*)(lds + PG8_SB(b, h) + boff + n * 2048 + k * 1024); } while (0)
; #define PG8_MMA(ai, bj, At, Bt) do { __builtin_amdgcn_s_setprio(1); _Pragma("unroll") for (int m = 0; m < 4; ++m) _Pragma("unroll") for (int n = 0; n < 2; ++n) _Pragma("unroll") for (int k = 0; k < 2; ++k) \
;         acc[ai][bj][m][n] = __builtin_amdgcn_mfma_f32_16x16x32_bf16(Bt[n][k], At[m][k], acc[ai][bj][m][n], 0, 0, 0); __builtin_amdgcn_s_setprio(0); } while (0)
; #define PG8_WAIT_V(n) asm volatile("s_waitcnt vmcnt(" #n ")" ::: "memory")
; #define PG8_WAIT_L(n) asm volatile("s_waitcnt lgkmcnt(" #n ")" ::: "memory")
; #define PG8_BAR __builtin_amdgcn_s_barrier()
; #define PG8_SCHED __builtin_amdgcn_sched_barrier(0)
; template <class Epi, bool ALIGN_EPI>
; __device__ __forceinline__ void gemm_phase(LAS unsigned char* lds, const Gemm g, const StaticOrder& S, const Epi& E) {
;     ...
;             PG8_WAIT_V(8); PG8_WAIT_L(0); PG8_BAR; PG8_MMA(1, 0, At, B0); PG8_MMA(1, 1, At, B1); PG8_BAR; PG8_SCHED;
;             PG8_LDB(B0, 1, 0); PG8_LDB(B1, 1, 1); PG8_SCHED; PG8_LDA(At, 1, 0); PG8_STAGE(PG8_SA(0, 1), a2 + hsA, voffA);
;             PG8_WAIT_V(8); PG8_WAIT_L(0); PG8_BAR; PG8_MMA(0, 0, At, B0); PG8_MMA(0, 1, At, B1); PG8_BAR; PG8_SCHED;
	s_waitcnt lgkmcnt(0)
	v_mfma_f32_16x16x32_bf16 v[62:65], v[74:77], v[154:157], v[62:65]
	v_mfma_f32_16x16x32_bf16 v[58:61], v[90:93], v[154:157], v[58:61]
	v_mfma_f32_16x16x32_bf16 v[46:49], v[74:77], v[170:173], v[46:49]
	v_mfma_f32_16x16x32_bf16 v[42:45], v[90:93], v[170:173], v[42:45]
	v_mfma_f32_16x16x32_bf16 v[30:33], v[74:77], v[178:181], v[30:33]
	v_mfma_f32_16x16x32_bf16 v[26:29], v[90:93], v[178:181], v[26:29]
	v_mfma_f32_16x16x32_bf16 v[14:17], v[74:77], v[186:189], v[14:17]
	v_mfma_f32_16x16x32_bf16 v[10:13], v[90:93], v[186:189], v[10:13]
	v_mfma_f32_16x16x32_bf16 v[62:65], v[82:85], v[166:169], v[62:65]
	v_mfma_f32_16x16x32_bf16 v[58:61], v[98:101], v[166:169], v[58:61]
	v_mfma_f32_16x16x32_bf16 v[46:49], v[82:85], v[174:177], v[46:49]
	v_mfma_f32_16x16x32_bf16 v[42:45], v[98:101], v[174:177], v[42:45]
	v_mfma_f32_16x16x32_bf16 v[30:33], v[82:85], v[182:185], v[30:33]
	v_mfma_f32_16x16x32_bf16 v[26:29], v[98:101], v[182:185], v[26:29]
	v_mfma_f32_16x16x32_bf16 v[14:17], v[82:85], v[190:193], v[14:17]
	v_mfma_f32_16x16x32_bf16 v[10:13], v[98:101], v[190:193], v[10:13]
	v_mfma_f32_16x16x32_bf16 v[54:57], v[106:109], v[154:157], v[54:57]
	v_mfma_f32_16x16x32_bf16 v[50:53], v[130:133], v[154:157], v[50:53]
	v_mfma_f32_16x16x32_bf16 v[38:41], v[106:109], v[170:173], v[38:41]
	v_mfma_f32_16x16x32_bf16 v[34:37], v[130:133], v[170:173], v[34:37]
	v_mfma_f32_16x16x32_bf16 v[22:25], v[106:109], v[178:181], v[22:25]
	v_mfma_f32_16x16x32_bf16 v[18:21], v[130:133], v[178:181], v[18:21]
	v_mfma_f32_16x16x32_bf16 v[6:9], v[106:109], v[186:189], v[6:9]
	v_mfma_f32_16x16x32_bf16 v[2:5], v[130:133], v[186:189], v[2:5]
	v_mfma_f32_16x16x32_bf16 v[54:57], v[114:117], v[166:169], v[54:57]
	v_mfma_f32_16x16x32_bf16 v[50:53], v[138:141], v[166:169], v[50:53]
	v_mfma_f32_16x16x32_bf16 v[38:41], v[114:117], v[174:177], v[38:41]
	v_mfma_f32_16x16x32_bf16 v[34:37], v[138:141], v[174:177], v[34:37]
	v_mfma_f32_16x16x32_bf16 v[22:25], v[114:117], v[182:185], v[22:25]
	v_mfma_f32_16x16x32_bf16 v[18:21], v[138:141], v[182:185], v[18:21]
	v_mfma_f32_16x16x32_bf16 v[6:9], v[114:117], v[190:193], v[6:9]
	v_mfma_f32_16x16x32_bf16 v[2:5], v[138:141], v[190:193], v[2:5]
	s_barrier
	s_add_i32 s52, 0, 0x18000
	s_add_i32 s53, 0, 0x1c000
	v_add_u32_e32 v98, s52, v230
	v_add_u32_e32 v138, s53, v230
	ds_read_b128 v[74:77], v98
	ds_read_b128 v[82:85], v98 offset:1024
	ds_read_b128 v[90:93], v98 offset:2048
	ds_read_b128 v[98:101], v98 offset:3072
	ds_read_b128 v[106:109], v138
	ds_read_b128 v[114:117], v138 offset:1024
	ds_read_b128 v[130:133], v138 offset:2048
	ds_read_b128 v[138:141], v138 offset:3072
	s_add_u32 s34, s34, 0x20000
	s_addc_u32 s35, s35, 0
	s_mov_b32 m0, s37
	v_lshl_add_u64 v[218:219], s[34:35], 0, v[198:199]
	ds_read_b128 v[154:157], v234 offset:32768
	ds_read_b128 v[166:169], v234 offset:33792
	ds_read_b128 v[170:173], v234 offset:34816
	ds_read_b128 v[174:177], v234 offset:35840
	ds_read_b128 v[178:181], v234 offset:36864
	ds_read_b128 v[182:185], v234 offset:37888
	ds_read_b128 v[186:189], v234 offset:38912
	ds_read_b128 v[190:193], v234 offset:39936
	global_load_lds_dwordx4 v[218:219], off
	v_lshl_add_u64 v[218:219], s[34:35], 0, v[202:203]
	s_mov_b32 m0, s38
	s_nop 0
	global_load_lds_dwordx4 v[218:219], off
	s_waitcnt vmcnt(8)
	s_waitcnt lgkmcnt(0)
	s_barrier
	s_waitcnt lgkmcnt(0)
	v_mfma_f32_16x16x32_bf16 v[162:165], v[74:77], v[154:157], v[162:165]
	v_mfma_f32_16x16x32_bf16 v[158:161], v[90:93], v[154:157], v[158:161]
	v_mfma_f32_16x16x32_bf16 v[142:145], v[74:77], v[170:173], v[142:145]
	v_mfma_f32_16x16x32_bf16 v[134:137], v[90:93], v[170:173], v[134:137]
	v_mfma_f32_16x16x32_bf16 v[118:121], v[74:77], v[178:181], v[118:121]
	v_mfma_f32_16x16x32_bf16 v[110:113], v[90:93], v[178:181], v[110:113]
	v_mfma_f32_16x16x32_bf16 v[86:89], v[74:77], v[186:189], v[86:89]
	v_mfma_f32_16x16x32_bf16 v[78:81], v[90:93], v[186:189], v[78:81]
	v_mfma_f32_16x16x32_bf16 v[162:165], v[82:85], v[166:169], v[162:165]
	v_mfma_f32_16x16x32_bf16 v[158:161], v[98:101], v[166:169], v[158:161]
	v_mfma_f32_16x16x32_bf16 v[142:145], v[82:85], v[174:177], v[142:145]
	v_mfma_f32_16x16x32_bf16 v[134:137], v[98:101], v[174:177], v[134:137]
	v_mfma_f32_16x16x32_bf16 v[118:121], v[82:85], v[182:185], v[118:121]
	v_mfma_f32_16x16x32_bf16 v[110:113], v[98:101], v[182:185], v[110:113]
	v_mfma_f32_16x16x32_bf16 v[86:89], v[82:85], v[190:193], v[86:89]
	v_mfma_f32_16x16x32_bf16 v[78:81], v[98:101], v[190:193], v[78:81]
	v_mfma_f32_16x16x32_bf16 v[150:153], v[106:109], v[154:157], v[150:153]
	v_mfma_f32_16x16x32_bf16 v[146:149], v[130:133], v[154:157], v[146:149]
	v_mfma_f32_16x16x32_bf16 v[126:129], v[106:109], v[170:173], v[126:129]
	v_mfma_f32_16x16x32_bf16 v[122:125], v[130:133], v[170:173], v[122:125]
	v_mfma_f32_16x16x32_bf16 v[102:105], v[106:109], v[178:181], v[102:105]
	v_mfma_f32_16x16x32_bf16 v[94:97], v[130:133], v[178:181], v[94:97]
	v_mfma_f32_16x16x32_bf16 v[70:73], v[106:109], v[186:189], v[70:73]
	v_mfma_f32_16x16x32_bf16 v[66:69], v[130:133], v[186:189], v[66:69]
	v_mfma_f32_16x16x32_bf16 v[150:153], v[114:117], v[166:169], v[150:153]
	v_mfma_f32_16x16x32_bf16 v[146:149], v[138:141], v[166:169], v[146:149]
	v_mfma_f32_16x16x32_bf16 v[126:129], v[114:117], v[174:177], v[126:129]
	v_mfma_f32_16x16x32_bf16 v[122:125], v[138:141], v[174:177], v[122:125]
	v_mfma_f32_16x16x32_bf16 v[102:105], v[114:117], v[182:185], v[102:105]
	v_mfma_f32_16x16x32_bf16 v[94:97], v[138:141], v[182:185], v[94:97]
	v_mfma_f32_16x16x32_bf16 v[70:73], v[114:117], v[190:193], v[70:73]
	v_mfma_f32_16x16x32_bf16 v[66:69], v[138:141], v[190:193], v[66:69]
	s_barrier
; #define PG8_STAGE(bufoff, gbase, voff) do { _Pragma("unroll") for (int _i = 0; _i < 2; ++_i) \
;         __builtin_amdgcn_global_load_lds((const unsigned*)((const char*)(gbase) + (voff)[_i]), (LAS unsigned*)(lds + (bufoff) + ldsw + _i * 8192), 16, 0, 0); } while (0)
; #define PG8_LDA(dst, b, h) do { _Pragma("unroll") for (int m = 0; m < 4; ++m) _Pragma("unroll") for (int k = 0; k < 2; ++k) dst[m][k] = *(const LAS bf16x8*)(lds + PG8_SA(b, h) + aoff + m * 2048 + k * 1024); } while (0)
; #define PG8_MMA(ai, bj, At, Bt) do { __builtin_amdgcn_s_setprio(1); _Pragma("unroll") for (int m = 0; m < 4; ++m) _Pragma("unroll") for (int n = 0; n < 2; ++n) _Pragma("unroll") for (int k = 0; k < 2; ++k) \
;         acc[ai][bj][m][n] = __builtin_amdgcn_mfma_f32_16x16x32_bf16(Bt[n][k], At[m][k], acc[ai][bj][m][n], 0, 0, 0); __builtin_amdgcn_s_setprio(0); } while (0)
; #define PG8_WAIT_V(n) asm volatile("s_waitcnt vmcnt(" #n ")" ::: "memory")
; #define PG8_WAIT_L(n) asm volatile("s_waitcnt lgkmcnt(" #n ")" ::: "memory")
; #define PG8_BAR __builtin_amdgcn_s_barrier()
; #define PG8_SCHED __builtin_amdgcn_sched_barrier(0)
; template <class Epi, bool ALIGN_EPI>
; __device__ __forceinline__ void gemm_phase(LAS unsigned char* lds, const Gemm g, const StaticOrder& S, const Epi& E) {
;     ...
;             PG8_LDA(At, 1, 1); PG8_STAGE(PG8_SB(1, 0), b3, voffB); PG8_STAGE(PG8_SB(1, 1), b3 + hsB, voffB); PG8_STAGE(PG8_SA(1, 0), a3, voffA);
;             PG8_WAIT_V(8); PG8_WAIT_L(0); PG8_BAR; PG8_MMA(1, 0, At, B0); PG8_MMA(1, 1, At, B1); PG8_BAR; PG8_SCHED;
;         }
	s_add_i32 s34, s52, s33
	v_lshl_add_u64 v[194:195], v[194:195], 0, s[12:13]
	s_mov_b32 m0, s34
	ds_read_b128 v[154:157], v234 offset:49152
	ds_read_b128 v[166:169], v234 offset:50176
	ds_read_b128 v[170:173], v234 offset:51200
	ds_read_b128 v[174:177], v234 offset:52224
	ds_read_b128 v[178:181], v234 offset:53248
	ds_read_b128 v[182:185], v234 offset:54272
	ds_read_b128 v[186:189], v234 offset:55296
	ds_read_b128 v[190:193], v234 offset:56320
	global_load_lds_dwordx4 v[194:195], off
	s_add_i32 m0, s34, 0x2000
	s_add_u32 s30, s30, 0x20080
	v_lshl_add_u64 v[194:195], v[196:197], 0, s[12:13]
	s_addc_u32 s31, s31, 0
	s_add_i32 s34, s53, s33
	global_load_lds_dwordx4 v[194:195], off
	v_lshl_add_u64 v[194:195], s[30:31], 0, v[200:201]
	s_mov_b32 m0, s34
	s_nop 0
	global_load_lds_dwordx4 v[194:195], off
	v_lshl_add_u64 v[194:195], s[30:31], 0, v[204:205]
	s_add_i32 m0, s34, 0x2000
	s_nop 0
	global_load_lds_dwordx4 v[194:195], off
	v_lshl_add_u64 v[194:195], v[214:215], 0, s[12:13]
	s_mov_b32 m0, s40
	s_nop 0
	global_load_lds_dwordx4 v[194:195], off
	v_lshl_add_u64 v[194:195], v[216:217], 0, s[12:13]
	s_mov_b32 m0, s41
	s_nop 0
	global_load_lds_dwordx4 v[194:195], off
	s_waitcnt vmcnt(8)
	s_waitcnt lgkmcnt(0)
	s_barrier
	s_waitcnt lgkmcnt(0)
	v_mfma_f32_16x16x32_bf16 v[62:65], v[74:77], v[154:157], v[62:65]
	v_mfma_f32_16x16x32_bf16 v[58:61], v[90:93], v[154:157], v[58:61]
	v_mfma_f32_16x16x32_bf16 v[46:49], v[74:77], v[170:173], v[46:49]
	v_mfma_f32_16x16x32_bf16 v[42:45], v[90:93], v[170:173], v[42:45]
	v_mfma_f32_16x16x32_bf16 v[30:33], v[74:77], v[178:181], v[30:33]
	v_mfma_f32_16x16x32_bf16 v[26:29], v[90:93], v[178:181], v[26:29]
	v_mfma_f32_16x16x32_bf16 v[14:17], v[74:77], v[186:189], v[14:17]
	v_mfma_f32_16x16x32_bf16 v[10:13], v[90:93], v[186:189], v[10:13]
	v_mfma_f32_16x16x32_bf16 v[62:65], v[82:85], v[166:169], v[62:65]
	v_mfma_f32_16x16x32_bf16 v[58:61], v[98:101], v[166:169], v[58:61]
	v_mfma_f32_16x16x32_bf16 v[46:49], v[82:85], v[174:177], v[46:49]
	v_mfma_f32_16x16x32_bf16 v[42:45], v[98:101], v[174:177], v[42:45]
	v_mfma_f32_16x16x32_bf16 v[30:33], v[82:85], v[182:185], v[30:33]
	v_mfma_f32_16x16x32_bf16 v[26:29], v[98:101], v[182:185], v[26:29]
	v_mfma_f32_16x16x32_bf16 v[14:17], v[82:85], v[190:193], v[14:17]
	v_mfma_f32_16x16x32_bf16 v[10:13], v[98:101], v[190:193], v[10:13]
	v_mfma_f32_16x16x32_bf16 v[54:57], v[106:109], v[154:157], v[54:57]
	v_mfma_f32_16x16x32_bf16 v[50:53], v[130:133], v[154:157], v[50:53]
	v_mfma_f32_16x16x32_bf16 v[38:41], v[106:109], v[170:173], v[38:41]
	v_mfma_f32_16x16x32_bf16 v[34:37], v[130:133], v[170:173], v[34:37]
	v_mfma_f32_16x16x32_bf16 v[22:25], v[106:109], v[178:181], v[22:25]
	v_mfma_f32_16x16x32_bf16 v[18:21], v[130:133], v[178:181], v[18:21]
	v_mfma_f32_16x16x32_bf16 v[6:9], v[106:109], v[186:189], v[6:9]
	v_mfma_f32_16x16x32_bf16 v[2:5], v[130:133], v[186:189], v[2:5]
	v_mfma_f32_16x16x32_bf16 v[54:57], v[114:117], v[166:169], v[54:57]
	v_mfma_f32_16x16x32_bf16 v[50:53], v[138:141], v[166:169], v[50:53]
	v_mfma_f32_16x16x32_bf16 v[38:41], v[114:117], v[174:177], v[38:41]
	v_mfma_f32_16x16x32_bf16 v[34:37], v[138:141], v[174:177], v[34:37]
	v_mfma_f32_16x16x32_bf16 v[22:25], v[114:117], v[182:185], v[22:25]
	v_mfma_f32_16x16x32_bf16 v[18:21], v[138:141], v[182:185], v[18:21]
	v_mfma_f32_16x16x32_bf16 v[6:9], v[114:117], v[190:193], v[6:9]
	v_mfma_f32_16x16x32_bf16 v[2:5], v[138:141], v[190:193], v[2:5]
	s_barrier
	s_add_i32 s51, s51, 2
	s_add_u32 s26, s26, 0x100
	s_addc_u32 s27, s27, 0
	s_add_u32 s49, s49, 0x100
	s_addc_u32 s50, s50, 0
	s_cmp_gt_u32 s51, 5
	s_cbranch_scc0 .LBB0_1027
	s_and_b64 vcc, exec, s[14:15]
	s_cbranch_vccz .LBB0_1030
	s_barrier

; #define PG8_STAGE(bufoff, gbase, voff) do { _Pragma("unroll") for (int _i = 0; _i < 2; ++_i) \
;         __builtin_amdgcn_global_load_lds((const unsigned*)((const char*)(gbase) + (voff)[_i]), (LAS unsigned*)(lds + (bufoff) + ldsw + _i * 8192), 16, 0, 0); } while (0)
; #define PG8_LDA(dst, b, h) do { _Pragma("unroll") for (int m = 0; m < 4; ++m) _Pragma("unroll") for (int k = 0; k < 2; ++k) dst[m][k] = *(const LAS bf16x8*)(lds + PG8_SA(b, h) + aoff + m * 2048 + k * 1024); } while (0)
; #define PG8_LDB(dst, b, h) do { _Pragma("unroll") for (int n = 0; n < 2; ++n) _Pragma("unroll") for (int k = 0; k < 2; ++k) dst[n][k] = *(const LAS bf16x8*)(lds + PG8_SB(b, h) + boff + n * 2048 + k * 1024); } while (0)
; #define PG8_MMA(ai, bj, At, Bt) do { __builtin_amdgcn_s_setprio(1); _Pragma("unroll") for (int m = 0; m < 4; ++m) _Pragma("unroll") for (int n = 0; n < 2; ++n) _Pragma("unroll") for (int k = 0; k < 2; ++k) \
;         acc[ai][bj][m][n] = __builtin_amdgcn_mfma_f32_16x16x32_bf16(Bt[n][k], At[m][k], acc[ai][bj][m][n], 0, 0, 0); __builtin_amdgcn_s_setprio(0); } while (0)
; #define PG8_WAIT_V(n) asm volatile("s_waitcnt vmcnt(" #n ")" ::: "memory")
; #define PG8_WAIT_L(n) asm volatile("s_waitcnt lgkmcnt(" #n ")" ::: "memory")
; #define PG8_BAR __builtin_amdgcn_s_barrier()
; #define PG8_SCHED __builtin_amdgcn_sched_barrier(0)
; template <class Epi, bool ALIGN_EPI>
; __device__ __forceinline__ void gemm_phase(LAS unsigned char* lds, const Gemm g, const StaticOrder& S, const Epi& E) {
;     ...
;             PG8_LDB(B0, 0, 0); PG8_LDB(B1, 0, 1); PG8_SCHED; PG8_LDA(At, 0, 0); PG8_STAGE(PG8_SA(1, 1), a1 + hsA, voffA);
;             PG8_WAIT_V(8); PG8_WAIT_L(0); PG8_BAR; PG8_MMA(0, 0, At, B0); PG8_MMA(0, 1, At, B1); PG8_BAR; PG8_SCHED;
;             PG8_LDA(At, 0, 1); PG8_STAGE(PG8_SB(0, 0), b2, voffB); PG8_STAGE(PG8_SB(0, 1), b2 + hsB, voffB); PG8_STAGE(PG8_SA(0, 0), a2, voffA);
;             PG8_WAIT_V(8); PG8_WAIT_L(0); PG8_BAR; PG8_MMA(1, 0, At, B0); PG8_MMA(1, 1, At, B1); PG8_BAR; PG8_SCHED;
.LBB0_1106:
	ds_read_b128 v[146:149], v160
	ds_read_b128 v[150:153], v160 offset:1024
	ds_read_b128 v[154:157], v160 offset:2048
	ds_read_b128 v[164:167], v160 offset:3072
	ds_read_b128 v[168:171], v161
	ds_read_b128 v[172:175], v161 offset:1024
	ds_read_b128 v[176:179], v161 offset:2048
	ds_read_b128 v[180:183], v161 offset:3072
	s_add_u32 s36, s34, 0xfffe0080
	s_addc_u32 s37, s35, -1
	s_cmp_eq_u32 s55, 4
	s_cselect_b32 s39, s23, s37
	s_cselect_b32 s38, s51, s36
	s_cselect_b32 s37, s25, s54
	s_cselect_b32 s36, s52, s53
	v_lshl_add_u64 v[216:217], s[34:35], 0, v[138:139]
	s_add_i32 m0, s31, 0xc000
	ds_read_b128 v[184:187], v162
	ds_read_b128 v[188:191], v162 offset:1024
	ds_read_b128 v[192:195], v162 offset:2048
	ds_read_b128 v[196:199], v162 offset:3072
	ds_read_b128 v[200:203], v162 offset:4096
	ds_read_b128 v[204:207], v162 offset:5120
	ds_read_b128 v[208:211], v162 offset:6144
	ds_read_b128 v[212:215], v162 offset:7168
	global_load_lds_dwordx4 v[216:217], off
	v_lshl_add_u64 v[216:217], s[34:35], 0, v[140:141]
	s_add_i32 m0, s31, 0xe000
	s_nop 0
	global_load_lds_dwordx4 v[216:217], off
	s_waitcnt vmcnt(8)
	s_waitcnt lgkmcnt(0)
	s_barrier
	s_waitcnt lgkmcnt(0)
	v_mfma_f32_16x16x32_bf16 v[126:129], v[146:149], v[184:187], v[126:129]
	v_mfma_f32_16x16x32_bf16 v[122:125], v[154:157], v[184:187], v[122:125]
	v_mfma_f32_16x16x32_bf16 v[118:121], v[146:149], v[192:195], v[118:121]
	v_mfma_f32_16x16x32_bf16 v[106:109], v[154:157], v[192:195], v[106:109]
	v_mfma_f32_16x16x32_bf16 v[94:97], v[146:149], v[200:203], v[94:97]
	v_mfma_f32_16x16x32_bf16 v[90:93], v[154:157], v[200:203], v[90:93]
	v_mfma_f32_16x16x32_bf16 v[78:81], v[146:149], v[208:211], v[78:81]
	v_mfma_f32_16x16x32_bf16 v[74:77], v[154:157], v[208:211], v[74:77]
	v_mfma_f32_16x16x32_bf16 v[126:129], v[150:153], v[188:191], v[126:129]
	v_mfma_f32_16x16x32_bf16 v[122:125], v[164:167], v[188:191], v[122:125]
	v_mfma_f32_16x16x32_bf16 v[118:121], v[150:153], v[196:199], v[118:121]
	v_mfma_f32_16x16x32_bf16 v[106:109], v[164:167], v[196:199], v[106:109]
	v_mfma_f32_16x16x32_bf16 v[94:97], v[150:153], v[204:207], v[94:97]
	v_mfma_f32_16x16x32_bf16 v[90:93], v[164:167], v[204:207], v[90:93]
	v_mfma_f32_16x16x32_bf16 v[78:81], v[150:153], v[212:215], v[78:81]
	v_mfma_f32_16x16x32_bf16 v[74:77], v[164:167], v[212:215], v[74:77]
	v_mfma_f32_16x16x32_bf16 v[114:117], v[168:171], v[184:187], v[114:117]
	v_mfma_f32_16x16x32_bf16 v[110:113], v[176:179], v[184:187], v[110:113]
	v_mfma_f32_16x16x32_bf16 v[102:105], v[168:171], v[192:195], v[102:105]
	v_mfma_f32_16x16x32_bf16 v[98:101], v[176:179], v[192:195], v[98:101]
	v_mfma_f32_16x16x32_bf16 v[86:89], v[168:171], v[200:203], v[86:89]
	v_mfma_f32_16x16x32_bf16 v[82:85], v[176:179], v[200:203], v[82:85]
	v_mfma_f32_16x16x32_bf16 v[70:73], v[168:171], v[208:211], v[70:73]
	v_mfma_f32_16x16x32_bf16 v[66:69], v[176:179], v[208:211], v[66:69]
	v_mfma_f32_16x16x32_bf16 v[114:117], v[172:175], v[188:191], v[114:117]
	v_mfma_f32_16x16x32_bf16 v[110:113], v[180:183], v[188:191], v[110:113]
	v_mfma_f32_16x16x32_bf16 v[102:105], v[172:175], v[196:199], v[102:105]
	v_mfma_f32_16x16x32_bf16 v[98:101], v[180:183], v[196:199], v[98:101]
	v_mfma_f32_16x16x32_bf16 v[86:89], v[172:175], v[204:207], v[86:89]
	v_mfma_f32_16x16x32_bf16 v[82:85], v[180:183], v[204:207], v[82:85]
	v_mfma_f32_16x16x32_bf16 v[70:73], v[172:175], v[212:215], v[70:73]
	v_mfma_f32_16x16x32_bf16 v[66:69], v[180:183], v[212:215], v[66:69]
	s_barrier
	s_add_i32 s56, s48, s33
	v_lshl_add_u64 v[216:217], s[36:37], 0, v[132:133]
	s_mov_b32 m0, s56
	ds_read_b128 v[184:187], v162 offset:16384
	ds_read_b128 v[188:191], v162 offset:17408
	ds_read_b128 v[192:195], v162 offset:18432
	ds_read_b128 v[196:199], v162 offset:19456
	ds_read_b128 v[200:203], v162 offset:20480
	ds_read_b128 v[204:207], v162 offset:21504
	ds_read_b128 v[208:211], v162 offset:22528
	ds_read_b128 v[212:215], v162 offset:23552
	global_load_lds_dwordx4 v[216:217], off
	s_add_i32 m0, s56, 0x2000
	s_add_u32 s56, s36, 0x20000
	v_lshl_add_u64 v[218:219], s[36:37], 0, v[136:137]
	s_addc_u32 s57, s37, 0
	s_add_i32 s58, s49, s33
	global_load_lds_dwordx4 v[218:219], off
	v_lshl_add_u64 v[220:221], s[56:57], 0, v[132:133]
	s_mov_b32 m0, s58
	v_lshl_add_u64 v[222:223], s[38:39], 0, v[134:135]
	global_load_lds_dwordx4 v[220:221], off
	v_lshl_add_u64 v[220:221], s[56:57], 0, v[136:137]
	s_add_i32 m0, s58, 0x2000
	s_nop 0
	global_load_lds_dwordx4 v[220:221], off
	v_lshl_add_u64 v[220:221], s[38:39], 0, v[130:131]
	s_mov_b32 m0, s31
	s_nop 0
	global_load_lds_dwordx4 v[220:221], off
	s_mov_b32 m0, s40
	s_nop 0
	global_load_lds_dwordx4 v[222:223], off
	s_waitcnt vmcnt(8)
	s_waitcnt lgkmcnt(0)
	s_barrier
; #define PG8_STAGE(bufoff, gbase, voff) do { _Pragma("unroll") for (int _i = 0; _i < 2; ++_i) \
;         __builtin_amdgcn_global_load_lds((const unsigned*)((const char*)(gbase) + (voff)[_i]), (LAS unsigned*)(lds + (bufoff) + ldsw + _i * 8192), 16, 0, 0); } while (0)
; #define PG8_LDA(dst, b, h) do { _Pragma("unroll") for (int m = 0; m < 4; ++m) _Pragma("unroll") for (int k = 0; k < 2; ++k) dst[m][k] = *(const LAS bf16x8*)(lds + PG8_SA(b, h) + aoff + m * 2048 + k * 1024); } while (0)
; #define PG8_LDB(dst, b, h) do { _Pragma("unroll") for (int n = 0; n < 2; ++n) _Pragma("unroll") for (int k = 0; k < 2; ++k) dst[n][k] = *(const LAS bf16x8*)(lds + PG8_SB(b, h) + boff + n * 2048 + k * 1024); } while (0)
; #define PG8_MMA(ai, bj, At, Bt) do { __builtin_amdgcn_s_setprio(1); _Pragma("unroll") for (int m = 0; m < 4; ++m) _Pragma("unroll") for (int n = 0; n < 2; ++n) _Pragma("unroll") for (int k = 0; k < 2; ++k) \
;         acc[ai][bj][m][n] = __builtin_amdgcn_mfma_f32_16x16x32_bf16(Bt[n][k], At[m][k], acc[ai][bj][m][n], 0, 0, 0); __builtin_amdgcn_s_setprio(0); } while (0)
; #define PG8_WAIT_V(n) asm volatile("s_waitcnt vmcnt(" #n ")" ::: "memory")
; #define PG8_WAIT_L(n) asm volatile("s_waitcnt lgkmcnt(" #n ")" ::: "memory")
; #define PG8_BAR __builtin_amdgcn_s_barrier()
; #define PG8_SCHED __builtin_amdgcn_sched_barrier(0)
; template <class Epi, bool ALIGN_EPI>
; __device__ __forceinline__ void gemm_phase(LAS unsigned char* lds, const Gemm g, const StaticOrder& S, const Epi& E) {
;     ...
;             PG8_WAIT_V(8); PG8_WAIT_L(0); PG8_BAR; PG8_MMA(1, 0, At, B0); PG8_MMA(1, 1, At, B1); PG8_BAR; PG8_SCHED;
;             PG8_LDB(B0, 1, 0); PG8_LDB(B1, 1, 1); PG8_SCHED; PG8_LDA(At, 1, 0); PG8_STAGE(PG8_SA(0, 1), a2 + hsA, voffA);
;             PG8_WAIT_V(8); PG8_WAIT_L(0); PG8_BAR; PG8_MMA(0, 0, At, B0); PG8_MMA(0, 1, At, B1); PG8_BAR; PG8_SCHED;
	s_waitcnt lgkmcnt(0)
	v_mfma_f32_16x16x32_bf16 v[62:65], v[146:149], v[184:187], v[62:65]
	v_mfma_f32_16x16x32_bf16 v[58:61], v[154:157], v[184:187], v[58:61]
	v_mfma_f32_16x16x32_bf16 v[46:49], v[146:149], v[192:195], v[46:49]
	v_mfma_f32_16x16x32_bf16 v[42:45], v[154:157], v[192:195], v[42:45]
	v_mfma_f32_16x16x32_bf16 v[30:33], v[146:149], v[200:203], v[30:33]
	v_mfma_f32_16x16x32_bf16 v[26:29], v[154:157], v[200:203], v[26:29]
	v_mfma_f32_16x16x32_bf16 v[14:17], v[146:149], v[208:211], v[14:17]
	v_mfma_f32_16x16x32_bf16 v[10:13], v[154:157], v[208:211], v[10:13]
	v_mfma_f32_16x16x32_bf16 v[62:65], v[150:153], v[188:191], v[62:65]
	v_mfma_f32_16x16x32_bf16 v[58:61], v[164:167], v[188:191], v[58:61]
	v_mfma_f32_16x16x32_bf16 v[46:49], v[150:153], v[196:199], v[46:49]
	v_mfma_f32_16x16x32_bf16 v[42:45], v[164:167], v[196:199], v[42:45]
	v_mfma_f32_16x16x32_bf16 v[30:33], v[150:153], v[204:207], v[30:33]
	v_mfma_f32_16x16x32_bf16 v[26:29], v[164:167], v[204:207], v[26:29]
	v_mfma_f32_16x16x32_bf16 v[14:17], v[150:153], v[212:215], v[14:17]
	v_mfma_f32_16x16x32_bf16 v[10:13], v[164:167], v[212:215], v[10:13]
	v_mfma_f32_16x16x32_bf16 v[54:57], v[168:171], v[184:187], v[54:57]
	v_mfma_f32_16x16x32_bf16 v[50:53], v[176:179], v[184:187], v[50:53]
	v_mfma_f32_16x16x32_bf16 v[38:41], v[168:171], v[192:195], v[38:41]
	v_mfma_f32_16x16x32_bf16 v[34:37], v[176:179], v[192:195], v[34:37]
	v_mfma_f32_16x16x32_bf16 v[22:25], v[168:171], v[200:203], v[22:25]
	v_mfma_f32_16x16x32_bf16 v[18:21], v[176:179], v[200:203], v[18:21]
	v_mfma_f32_16x16x32_bf16 v[6:9], v[168:171], v[208:211], v[6:9]
	v_mfma_f32_16x16x32_bf16 v[2:5], v[176:179], v[208:211], v[2:5]
	v_mfma_f32_16x16x32_bf16 v[54:57], v[172:175], v[188:191], v[54:57]
	v_mfma_f32_16x16x32_bf16 v[50:53], v[180:183], v[188:191], v[50:53]
	v_mfma_f32_16x16x32_bf16 v[38:41], v[172:175], v[196:199], v[38:41]
	v_mfma_f32_16x16x32_bf16 v[34:37], v[180:183], v[196:199], v[34:37]
	v_mfma_f32_16x16x32_bf16 v[22:25], v[172:175], v[204:207], v[22:25]
	v_mfma_f32_16x16x32_bf16 v[18:21], v[180:183], v[204:207], v[18:21]
	v_mfma_f32_16x16x32_bf16 v[6:9], v[172:175], v[212:215], v[6:9]
	v_mfma_f32_16x16x32_bf16 v[2:5], v[180:183], v[212:215], v[2:5]
	s_barrier
	s_add_i32 s56, 0, 0x18000
	v_add_u32_e32 v163, s56, v158
	s_add_i32 s57, 0, 0x1c000
	ds_read_b128 v[146:149], v163
	ds_read_b128 v[150:153], v163 offset:1024
	ds_read_b128 v[154:157], v163 offset:2048
	ds_read_b128 v[164:167], v163 offset:3072
	v_add_u32_e32 v163, s57, v158
	ds_read_b128 v[168:171], v163
	ds_read_b128 v[172:175], v163 offset:1024
	ds_read_b128 v[176:179], v163 offset:2048
	ds_read_b128 v[180:183], v163 offset:3072
	s_add_u32 s38, s38, 0x20000
	s_addc_u32 s39, s39, 0
	s_mov_b32 m0, s41
	v_lshl_add_u64 v[224:225], s[38:39], 0, v[130:131]
	ds_read_b128 v[184:187], v162 offset:32768
	ds_read_b128 v[188:191], v162 offset:33792
	ds_read_b128 v[192:195], v162 offset:34816
	ds_read_b128 v[196:199], v162 offset:35840
	ds_read_b128 v[200:203], v162 offset:36864
	ds_read_b128 v[204:207], v162 offset:37888
	ds_read_b128 v[208:211], v162 offset:38912
	ds_read_b128 v[212:215], v162 offset:39936
	global_load_lds_dwordx4 v[224:225], off
	v_lshl_add_u64 v[224:225], s[38:39], 0, v[134:135]
	s_mov_b32 m0, s42
	s_nop 0
	global_load_lds_dwordx4 v[224:225], off
	s_waitcnt vmcnt(8)
	s_waitcnt lgkmcnt(0)
	s_barrier
	s_waitcnt lgkmcnt(0)
	v_mfma_f32_16x16x32_bf16 v[126:129], v[146:149], v[184:187], v[126:129]
	v_mfma_f32_16x16x32_bf16 v[122:125], v[154:157], v[184:187], v[122:125]
	v_mfma_f32_16x16x32_bf16 v[118:121], v[146:149], v[192:195], v[118:121]
	v_mfma_f32_16x16x32_bf16 v[106:109], v[154:157], v[192:195], v[106:109]
	v_mfma_f32_16x16x32_bf16 v[94:97], v[146:149], v[200:203], v[94:97]
	v_mfma_f32_16x16x32_bf16 v[90:93], v[154:157], v[200:203], v[90:93]
	v_mfma_f32_16x16x32_bf16 v[78:81], v[146:149], v[208:211], v[78:81]
	v_mfma_f32_16x16x32_bf16 v[74:77], v[154:157], v[208:211], v[74:77]
	v_mfma_f32_16x16x32_bf16 v[126:129], v[150:153], v[188:191], v[126:129]
	v_mfma_f32_16x16x32_bf16 v[122:125], v[164:167], v[188:191], v[122:125]
	v_mfma_f32_16x16x32_bf16 v[118:121], v[150:153], v[196:199], v[118:121]
	v_mfma_f32_16x16x32_bf16 v[106:109], v[164:167], v[196:199], v[106:109]
	v_mfma_f32_16x16x32_bf16 v[94:97], v[150:153], v[204:207], v[94:97]
	v_mfma_f32_16x16x32_bf16 v[90:93], v[164:167], v[204:207], v[90:93]
	v_mfma_f32_16x16x32_bf16 v[78:81], v[150:153], v[212:215], v[78:81]
	v_mfma_f32_16x16x32_bf16 v[74:77], v[164:167], v[212:215], v[74:77]
	v_mfma_f32_16x16x32_bf16 v[114:117], v[168:171], v[184:187], v[114:117]
	v_mfma_f32_16x16x32_bf16 v[110:113], v[176:179], v[184:187], v[110:113]
	v_mfma_f32_16x16x32_bf16 v[102:105], v[168:171], v[192:195], v[102:105]
	v_mfma_f32_16x16x32_bf16 v[98:101], v[176:179], v[192:195], v[98:101]
	v_mfma_f32_16x16x32_bf16 v[86:89], v[168:171], v[200:203], v[86:89]
	v_mfma_f32_16x16x32_bf16 v[82:85], v[176:179], v[200:203], v[82:85]
	v_mfma_f32_16x16x32_bf16 v[70:73], v[168:171], v[208:211], v[70:73]
	v_mfma_f32_16x16x32_bf16 v[66:69], v[176:179], v[208:211], v[66:69]
	v_mfma_f32_16x16x32_bf16 v[114:117], v[172:175], v[188:191], v[114:117]
	v_mfma_f32_16x16x32_bf16 v[110:113], v[180:183], v[188:191], v[110:113]
	v_mfma_f32_16x16x32_bf16 v[102:105], v[172:175], v[196:199], v[102:105]
	v_mfma_f32_16x16x32_bf16 v[98:101], v[180:183], v[196:199], v[98:101]
	v_mfma_f32_16x16x32_bf16 v[86:89], v[172:175], v[204:207], v[86:89]
	v_mfma_f32_16x16x32_bf16 v[82:85], v[180:183], v[204:207], v[82:85]
	v_mfma_f32_16x16x32_bf16 v[70:73], v[172:175], v[212:215], v[70:73]
	v_mfma_f32_16x16x32_bf16 v[66:69], v[180:183], v[212:215], v[66:69]
	s_barrier
; #define PG8_STAGE(bufoff, gbase, voff) do { _Pragma("unroll") for (int _i = 0; _i < 2; ++_i) \
;         __builtin_amdgcn_global_load_lds((const unsigned*)((const char*)(gbase) + (voff)[_i]), (LAS unsigned*)(lds + (bufoff) + ldsw + _i * 8192), 16, 0, 0); } while (0)
; #define PG8_LDA(dst, b, h) do { _Pragma("unroll") for (int m = 0; m < 4; ++m) _Pragma("unroll") for (int k = 0; k < 2; ++k) dst[m][k] = *(const LAS bf16x8*)(lds + PG8_SA(b, h) + aoff + m * 2048 + k * 1024); } while (0)
; #define PG8_MMA(ai, bj, At, Bt) do { __builtin_amdgcn_s_setprio(1); _Pragma("unroll") for (int m = 0; m < 4; ++m) _Pragma("unroll") for (int n = 0; n < 2; ++n) _Pragma("unroll") for (int k = 0; k < 2; ++k) \
;         acc[ai][bj][m][n] = __builtin_amdgcn_mfma_f32_16x16x32_bf16(Bt[n][k], At[m][k], acc[ai][bj][m][n], 0, 0, 0); __builtin_amdgcn_s_setprio(0); } while (0)
; #define PG8_WAIT_V(n) asm volatile("s_waitcnt vmcnt(" #n ")" ::: "memory")
; #define PG8_WAIT_L(n) asm volatile("s_waitcnt lgkmcnt(" #n ")" ::: "memory")
; #define PG8_BAR __builtin_amdgcn_s_barrier()
; #define PG8_SCHED __builtin_amdgcn_sched_barrier(0)
; template <class Epi, bool ALIGN_EPI>
; __device__ __forceinline__ void gemm_phase(LAS unsigned char* lds, const Gemm g, const StaticOrder& S, const Epi& E) {
;     ...
;             PG8_LDA(At, 1, 1); PG8_STAGE(PG8_SB(1, 0), b3, voffB); PG8_STAGE(PG8_SB(1, 1), b3 + hsB, voffB); PG8_STAGE(PG8_SA(1, 0), a3, voffA);
;             PG8_WAIT_V(8); PG8_WAIT_L(0); PG8_BAR; PG8_MMA(1, 0, At, B0); PG8_MMA(1, 1, At, B1); PG8_BAR; PG8_SCHED;
;         }
	s_add_i32 s38, s56, s33
	v_lshl_add_u64 v[216:217], v[216:217], 0, s[10:11]
	s_mov_b32 m0, s38
	ds_read_b128 v[184:187], v162 offset:49152
	ds_read_b128 v[188:191], v162 offset:50176
	ds_read_b128 v[192:195], v162 offset:51200
	ds_read_b128 v[196:199], v162 offset:52224
	ds_read_b128 v[200:203], v162 offset:53248
	ds_read_b128 v[204:207], v162 offset:54272
	ds_read_b128 v[208:211], v162 offset:55296
	ds_read_b128 v[212:215], v162 offset:56320
	global_load_lds_dwordx4 v[216:217], off
	s_add_i32 m0, s38, 0x2000
	s_add_u32 s36, s36, 0x20080
	v_lshl_add_u64 v[216:217], v[218:219], 0, s[10:11]
	s_addc_u32 s37, s37, 0
	s_add_i32 s38, s57, s33
	global_load_lds_dwordx4 v[216:217], off
	v_lshl_add_u64 v[216:217], s[36:37], 0, v[132:133]
	s_mov_b32 m0, s38
	s_nop 0
	global_load_lds_dwordx4 v[216:217], off
	v_lshl_add_u64 v[216:217], s[36:37], 0, v[136:137]
	s_add_i32 m0, s38, 0x2000
	s_nop 0
	global_load_lds_dwordx4 v[216:217], off
	v_lshl_add_u64 v[216:217], v[220:221], 0, s[10:11]
	s_mov_b32 m0, s44
	s_nop 0
	global_load_lds_dwordx4 v[216:217], off
	v_lshl_add_u64 v[216:217], v[222:223], 0, s[10:11]
	s_mov_b32 m0, s45
	s_nop 0
	global_load_lds_dwordx4 v[216:217], off
	s_waitcnt vmcnt(8)
	s_waitcnt lgkmcnt(0)
	s_barrier
	s_waitcnt lgkmcnt(0)
	v_mfma_f32_16x16x32_bf16 v[62:65], v[146:149], v[184:187], v[62:65]
	v_mfma_f32_16x16x32_bf16 v[58:61], v[154:157], v[184:187], v[58:61]
	v_mfma_f32_16x16x32_bf16 v[46:49], v[146:149], v[192:195], v[46:49]
	v_mfma_f32_16x16x32_bf16 v[42:45], v[154:157], v[192:195], v[42:45]
	v_mfma_f32_16x16x32_bf16 v[30:33], v[146:149], v[200:203], v[30:33]
	v_mfma_f32_16x16x32_bf16 v[26:29], v[154:157], v[200:203], v[26:29]
	v_mfma_f32_16x16x32_bf16 v[14:17], v[146:149], v[208:211], v[14:17]
	v_mfma_f32_16x16x32_bf16 v[10:13], v[154:157], v[208:211], v[10:13]
	v_mfma_f32_16x16x32_bf16 v[62:65], v[150:153], v[188:191], v[62:65]
	v_mfma_f32_16x16x32_bf16 v[58:61], v[164:167], v[188:191], v[58:61]
	v_mfma_f32_16x16x32_bf16 v[46:49], v[150:153], v[196:199], v[46:49]
	v_mfma_f32_16x16x32_bf16 v[42:45], v[164:167], v[196:199], v[42:45]
	v_mfma_f32_16x16x32_bf16 v[30:33], v[150:153], v[204:207], v[30:33]
	v_mfma_f32_16x16x32_bf16 v[26:29], v[164:167], v[204:207], v[26:29]
	v_mfma_f32_16x16x32_bf16 v[14:17], v[150:153], v[212:215], v[14:17]
	v_mfma_f32_16x16x32_bf16 v[10:13], v[164:167], v[212:215], v[10:13]
	v_mfma_f32_16x16x32_bf16 v[54:57], v[168:171], v[184:187], v[54:57]
	v_mfma_f32_16x16x32_bf16 v[50:53], v[176:179], v[184:187], v[50:53]
	v_mfma_f32_16x16x32_bf16 v[38:41], v[168:171], v[192:195], v[38:41]
	v_mfma_f32_16x16x32_bf16 v[34:37], v[176:179], v[192:195], v[34:37]
	v_mfma_f32_16x16x32_bf16 v[22:25], v[168:171], v[200:203], v[22:25]
	v_mfma_f32_16x16x32_bf16 v[18:21], v[176:179], v[200:203], v[18:21]
	v_mfma_f32_16x16x32_bf16 v[6:9], v[168:171], v[208:211], v[6:9]
	v_mfma_f32_16x16x32_bf16 v[2:5], v[176:179], v[208:211], v[2:5]
	v_mfma_f32_16x16x32_bf16 v[54:57], v[172:175], v[188:191], v[54:57]
	v_mfma_f32_16x16x32_bf16 v[50:53], v[180:183], v[188:191], v[50:53]
	v_mfma_f32_16x16x32_bf16 v[38:41], v[172:175], v[196:199], v[38:41]
	v_mfma_f32_16x16x32_bf16 v[34:37], v[180:183], v[196:199], v[34:37]
	v_mfma_f32_16x16x32_bf16 v[22:25], v[172:175], v[204:207], v[22:25]
	v_mfma_f32_16x16x32_bf16 v[18:21], v[180:183], v[204:207], v[18:21]
	v_mfma_f32_16x16x32_bf16 v[6:9], v[172:175], v[212:215], v[6:9]
	v_mfma_f32_16x16x32_bf16 v[2:5], v[180:183], v[212:215], v[2:5]
	s_barrier
	s_add_i32 s55, s55, 2
	s_add_u32 s34, s34, 0x100
	s_addc_u32 s35, s35, 0
	s_add_u32 s53, s53, 0x100
	s_addc_u32 s54, s54, 0
	s_cmp_gt_u32 s55, 5
	s_cbranch_scc0 .LBB0_1106
	v_readlane_b32 s52, v251, 40
	s_and_b64 vcc, exec, s[12:13]
	v_readlane_b32 s66, v251, 54
	v_readlane_b32 s67, v251, 55
	v_readlane_b32 s53, v251, 41
	v_readlane_b32 s54, v251, 42
	v_readlane_b32 s55, v251, 43
	v_readlane_b32 s56, v251, 44
	v_readlane_b32 s57, v251, 45
	v_readlane_b32 s58, v251, 46
	v_readlane_b32 s59, v251, 47
	v_readlane_b32 s60, v251, 48
	v_readlane_b32 s61, v251, 49
	v_readlane_b32 s62, v251, 50
	v_readlane_b32 s63, v251, 51
	v_readlane_b32 s64, v251, 52
	v_readlane_b32 s65, v251, 53
	s_cbranch_vccz .LBB0_1109
	s_barrier

; #define PG8_STAGE(bufoff, gbase, voff) do { _Pragma("unroll") for (int _i = 0; _i < 2; ++_i) \
;         __builtin_amdgcn_global_load_lds((const unsigned*)((const char*)(gbase) + (voff)[_i]), (LAS unsigned*)(lds + (bufoff) + ldsw + _i * 8192), 16, 0, 0); } while (0)
; #define PG8_LDA(dst, b, h) do { _Pragma("unroll") for (int m = 0; m < 4; ++m) _Pragma("unroll") for (int k = 0; k < 2; ++k) dst[m][k] = *(const LAS bf16x8*)(lds + PG8_SA(b, h) + aoff + m * 2048 + k * 1024); } while (0)
; #define PG8_LDB(dst, b, h) do { _Pragma("unroll") for (int n = 0; n < 2; ++n) _Pragma("unroll") for (int k = 0; k < 2; ++k) dst[n][k] = *(const LAS bf16x8*)(lds + PG8_SB(b, h) + boff + n * 2048 + k * 1024); } while (0)
; #define PG8_MMA(ai, bj, At, Bt) do { __builtin_amdgcn_s_setprio(1); _Pragma("unroll") for (int m = 0; m < 4; ++m) _Pragma("unroll") for (int n = 0; n < 2; ++n) _Pragma("unroll") for (int k = 0; k < 2; ++k) \
;         acc[ai][bj][m][n] = __builtin_amdgcn_mfma_f32_16x16x32_bf16(Bt[n][k], At[m][k], acc[ai][bj][m][n], 0, 0, 0); __builtin_amdgcn_s_setprio(0); } while (0)
; #define PG8_WAIT_V(n) asm volatile("s_waitcnt vmcnt(" #n ")" ::: "memory")
; #define PG8_WAIT_L(n) asm volatile("s_waitcnt lgkmcnt(" #n ")" ::: "memory")
; #define PG8_BAR __builtin_amdgcn_s_barrier()
; #define PG8_SCHED __builtin_amdgcn_sched_barrier(0)
; template <class Epi, bool ALIGN_EPI>
; __device__ __forceinline__ void gemm_phase(LAS unsigned char* lds, const Gemm g, const StaticOrder& S, const Epi& E) {
;     ...
;         for (int t = 0; t < nt; t += 2) {
;             const bool last = (t == nt - 2);
;             const char* a1 = cA + (size_t)(t + 1) * kstepA;
;             const char* a2 = last ? nA : cA + (size_t)(t + 2) * kstepA; const char* b2 = last ? nB : cB + (size_t)(t + 2) * kstep;
;             const char* a3 = a2 + kstepA; const char* b3 = b2 + kstep;
;             PG8_LDB(B0, 0, 0); PG8_LDB(B1, 0, 1); PG8_SCHED; PG8_LDA(At, 0, 0); PG8_STAGE(PG8_SA(1, 1), a1 + hsA, voffA);
;             PG8_WAIT_V(8); PG8_WAIT_L(0); PG8_BAR; PG8_MMA(0, 0, At, B0); PG8_MMA(0, 1, At, B1); PG8_BAR; PG8_SCHED;
;             PG8_LDA(At, 0, 1); PG8_STAGE(PG8_SB(0, 0), b2, voffB); PG8_STAGE(PG8_SB(0, 1), b2 + hsB, voffB); PG8_STAGE(PG8_SA(0, 0), a2, voffA);
;             PG8_WAIT_V(8); PG8_WAIT_L(0); PG8_BAR; PG8_MMA(1, 0, At, B0); PG8_MMA(1, 1, At, B1); PG8_BAR; PG8_SCHED;
.LBB0_1131:
	ds_read_b128 v[130:133], v184
	ds_read_b128 v[134:137], v184 offset:1024
	ds_read_b128 v[138:141], v184 offset:2048
	ds_read_b128 v[142:145], v184 offset:3072
	ds_read_b128 v[162:165], v185
	ds_read_b128 v[166:169], v185 offset:1024
	ds_read_b128 v[170:173], v185 offset:2048
	ds_read_b128 v[174:177], v185 offset:3072
	s_add_u32 s38, s36, 0xfffe0080
	s_addc_u32 s39, s37, -1
	s_cmp_eq_u32 s57, 4
	s_cselect_b32 s41, s25, s39
	s_cselect_b32 s40, s53, s38
	s_cselect_b32 s39, s27, s56
	s_cselect_b32 s38, s54, s55
	v_lshl_add_u64 v[216:217], s[36:37], 0, v[154:155]
	s_add_i32 m0, s35, 0xc000
	ds_read_b128 v[178:181], v186
	ds_read_b128 v[188:191], v186 offset:1024
	ds_read_b128 v[192:195], v186 offset:2048
	ds_read_b128 v[196:199], v186 offset:3072
	ds_read_b128 v[200:203], v186 offset:4096
	ds_read_b128 v[204:207], v186 offset:5120
	ds_read_b128 v[208:211], v186 offset:6144
	ds_read_b128 v[212:215], v186 offset:7168
	global_load_lds_dwordx4 v[216:217], off
	v_lshl_add_u64 v[216:217], s[36:37], 0, v[156:157]
	s_add_i32 m0, s35, 0xe000
	s_nop 0
	global_load_lds_dwordx4 v[216:217], off
	s_waitcnt vmcnt(8)
	s_waitcnt lgkmcnt(0)
	s_barrier
	s_waitcnt lgkmcnt(0)
	v_mfma_f32_16x16x32_bf16 v[126:129], v[130:133], v[178:181], v[126:129]
	v_mfma_f32_16x16x32_bf16 v[122:125], v[138:141], v[178:181], v[122:125]
	v_mfma_f32_16x16x32_bf16 v[110:113], v[130:133], v[192:195], v[110:113]
	v_mfma_f32_16x16x32_bf16 v[106:109], v[138:141], v[192:195], v[106:109]
	v_mfma_f32_16x16x32_bf16 v[94:97], v[130:133], v[200:203], v[94:97]
	v_mfma_f32_16x16x32_bf16 v[90:93], v[138:141], v[200:203], v[90:93]
	v_mfma_f32_16x16x32_bf16 v[78:81], v[130:133], v[208:211], v[78:81]
	v_mfma_f32_16x16x32_bf16 v[74:77], v[138:141], v[208:211], v[74:77]
	v_mfma_f32_16x16x32_bf16 v[126:129], v[134:137], v[188:191], v[126:129]
	v_mfma_f32_16x16x32_bf16 v[122:125], v[142:145], v[188:191], v[122:125]
	v_mfma_f32_16x16x32_bf16 v[110:113], v[134:137], v[196:199], v[110:113]
	v_mfma_f32_16x16x32_bf16 v[106:109], v[142:145], v[196:199], v[106:109]
	v_mfma_f32_16x16x32_bf16 v[94:97], v[134:137], v[204:207], v[94:97]
	v_mfma_f32_16x16x32_bf16 v[90:93], v[142:145], v[204:207], v[90:93]
	v_mfma_f32_16x16x32_bf16 v[78:81], v[134:137], v[212:215], v[78:81]
	v_mfma_f32_16x16x32_bf16 v[74:77], v[142:145], v[212:215], v[74:77]
	v_mfma_f32_16x16x32_bf16 v[118:121], v[162:165], v[178:181], v[118:121]
	v_mfma_f32_16x16x32_bf16 v[114:117], v[170:173], v[178:181], v[114:117]
	v_mfma_f32_16x16x32_bf16 v[102:105], v[162:165], v[192:195], v[102:105]
	v_mfma_f32_16x16x32_bf16 v[98:101], v[170:173], v[192:195], v[98:101]
	v_mfma_f32_16x16x32_bf16 v[86:89], v[162:165], v[200:203], v[86:89]
	v_mfma_f32_16x16x32_bf16 v[82:85], v[170:173], v[200:203], v[82:85]
	v_mfma_f32_16x16x32_bf16 v[70:73], v[162:165], v[208:211], v[70:73]
	v_mfma_f32_16x16x32_bf16 v[66:69], v[170:173], v[208:211], v[66:69]
	v_mfma_f32_16x16x32_bf16 v[118:121], v[166:169], v[188:191], v[118:121]
	v_mfma_f32_16x16x32_bf16 v[114:117], v[174:177], v[188:191], v[114:117]
	v_mfma_f32_16x16x32_bf16 v[102:105], v[166:169], v[196:199], v[102:105]
	v_mfma_f32_16x16x32_bf16 v[98:101], v[174:177], v[196:199], v[98:101]
	v_mfma_f32_16x16x32_bf16 v[86:89], v[166:169], v[204:207], v[86:89]
	v_mfma_f32_16x16x32_bf16 v[82:85], v[174:177], v[204:207], v[82:85]
	v_mfma_f32_16x16x32_bf16 v[70:73], v[166:169], v[212:215], v[70:73]
	v_mfma_f32_16x16x32_bf16 v[66:69], v[174:177], v[212:215], v[66:69]
	s_barrier
	s_add_i32 s58, s50, s33
	v_lshl_add_u64 v[216:217], s[38:39], 0, v[148:149]
	s_mov_b32 m0, s58
	ds_read_b128 v[178:181], v186 offset:16384
	ds_read_b128 v[188:191], v186 offset:17408
	ds_read_b128 v[192:195], v186 offset:18432
	ds_read_b128 v[196:199], v186 offset:19456
	ds_read_b128 v[200:203], v186 offset:20480
	ds_read_b128 v[204:207], v186 offset:21504
	ds_read_b128 v[208:211], v186 offset:22528
	ds_read_b128 v[212:215], v186 offset:23552
	global_load_lds_dwordx4 v[216:217], off
	s_add_i32 m0, s58, 0x2000
	s_add_u32 s58, s38, 0x20000
	v_lshl_add_u64 v[218:219], s[38:39], 0, v[152:153]
	s_addc_u32 s59, s39, 0
	s_add_i32 s60, s51, s33
	global_load_lds_dwordx4 v[218:219], off
	v_lshl_add_u64 v[220:221], s[58:59], 0, v[148:149]
	s_mov_b32 m0, s60
	v_lshl_add_u64 v[222:223], s[40:41], 0, v[150:151]
	global_load_lds_dwordx4 v[220:221], off
	v_lshl_add_u64 v[220:221], s[58:59], 0, v[152:153]
	s_add_i32 m0, s60, 0x2000
	s_nop 0
	global_load_lds_dwordx4 v[220:221], off
	v_lshl_add_u64 v[220:221], s[40:41], 0, v[146:147]
	s_mov_b32 m0, s35
	s_nop 0
	global_load_lds_dwordx4 v[220:221], off
	s_mov_b32 m0, s42
	s_nop 0
	global_load_lds_dwordx4 v[222:223], off
	s_waitcnt vmcnt(8)
	s_waitcnt lgkmcnt(0)
	s_barrier
; #define PG8_STAGE(bufoff, gbase, voff) do { _Pragma("unroll") for (int _i = 0; _i < 2; ++_i) \
;         __builtin_amdgcn_global_load_lds((const unsigned*)((const char*)(gbase) + (voff)[_i]), (LAS unsigned*)(lds + (bufoff) + ldsw + _i * 8192), 16, 0, 0); } while (0)
; #define PG8_LDA(dst, b, h) do { _Pragma("unroll") for (int m = 0; m < 4; ++m) _Pragma("unroll") for (int k = 0; k < 2; ++k) dst[m][k] = *(const LAS bf16x8*)(lds + PG8_SA(b, h) + aoff + m * 2048 + k * 1024); } while (0)
; #define PG8_LDB(dst, b, h) do { _Pragma("unroll") for (int n = 0; n < 2; ++n) _Pragma("unroll") for (int k = 0; k < 2; ++k) dst[n][k] = *(const LAS bf16x8*)(lds + PG8_SB(b, h) + boff + n * 2048 + k * 1024); } while (0)
; #define PG8_MMA(ai, bj, At, Bt) do { __builtin_amdgcn_s_setprio(1); _Pragma("unroll") for (int m = 0; m < 4; ++m) _Pragma("unroll") for (int n = 0; n < 2; ++n) _Pragma("unroll") for (int k = 0; k < 2; ++k) \
;         acc[ai][bj][m][n] = __builtin_amdgcn_mfma_f32_16x16x32_bf16(Bt[n][k], At[m][k], acc[ai][bj][m][n], 0, 0, 0); __builtin_amdgcn_s_setprio(0); } while (0)
; #define PG8_WAIT_V(n) asm volatile("s_waitcnt vmcnt(" #n ")" ::: "memory")
; #define PG8_WAIT_L(n) asm volatile("s_waitcnt lgkmcnt(" #n ")" ::: "memory")
; #define PG8_BAR __builtin_amdgcn_s_barrier()
; #define PG8_SCHED __builtin_amdgcn_sched_barrier(0)
; template <class Epi, bool ALIGN_EPI>
; __device__ __forceinline__ void gemm_phase(LAS unsigned char* lds, const Gemm g, const StaticOrder& S, const Epi& E) {
;     ...
;             PG8_WAIT_V(8); PG8_WAIT_L(0); PG8_BAR; PG8_MMA(1, 0, At, B0); PG8_MMA(1, 1, At, B1); PG8_BAR; PG8_SCHED;
;             PG8_LDB(B0, 1, 0); PG8_LDB(B1, 1, 1); PG8_SCHED; PG8_LDA(At, 1, 0); PG8_STAGE(PG8_SA(0, 1), a2 + hsA, voffA);
;             PG8_WAIT_V(8); PG8_WAIT_L(0); PG8_BAR; PG8_MMA(0, 0, At, B0); PG8_MMA(0, 1, At, B1); PG8_BAR; PG8_SCHED;
;             PG8_LDA(At, 1, 1); PG8_STAGE(PG8_SB(1, 0), b3, voffB); PG8_STAGE(PG8_SB(1, 1), b3 + hsB, voffB); PG8_STAGE(PG8_SA(1, 0), a3, voffA);
;             PG8_WAIT_V(8); PG8_WAIT_L(0); PG8_BAR; PG8_MMA(1, 0, At, B0); PG8_MMA(1, 1, At, B1); PG8_BAR; PG8_SCHED;
	s_waitcnt lgkmcnt(0)
	v_mfma_f32_16x16x32_bf16 v[62:65], v[130:133], v[178:181], v[62:65]
	v_mfma_f32_16x16x32_bf16 v[58:61], v[138:141], v[178:181], v[58:61]
	v_mfma_f32_16x16x32_bf16 v[46:49], v[130:133], v[192:195], v[46:49]
	v_mfma_f32_16x16x32_bf16 v[42:45], v[138:141], v[192:195], v[42:45]
	v_mfma_f32_16x16x32_bf16 v[30:33], v[130:133], v[200:203], v[30:33]
	v_mfma_f32_16x16x32_bf16 v[26:29], v[138:141], v[200:203], v[26:29]
	v_mfma_f32_16x16x32_bf16 v[14:17], v[130:133], v[208:211], v[14:17]
	v_mfma_f32_16x16x32_bf16 v[10:13], v[138:141], v[208:211], v[10:13]
	v_mfma_f32_16x16x32_bf16 v[62:65], v[134:137], v[188:191], v[62:65]
	v_mfma_f32_16x16x32_bf16 v[58:61], v[142:145], v[188:191], v[58:61]
	v_mfma_f32_16x16x32_bf16 v[46:49], v[134:137], v[196:199], v[46:49]
	v_mfma_f32_16x16x32_bf16 v[42:45], v[142:145], v[196:199], v[42:45]
	v_mfma_f32_16x16x32_bf16 v[30:33], v[134:137], v[204:207], v[30:33]
	v_mfma_f32_16x16x32_bf16 v[26:29], v[142:145], v[204:207], v[26:29]
	v_mfma_f32_16x16x32_bf16 v[14:17], v[134:137], v[212:215], v[14:17]
	v_mfma_f32_16x16x32_bf16 v[10:13], v[142:145], v[212:215], v[10:13]
	v_mfma_f32_16x16x32_bf16 v[54:57], v[162:165], v[178:181], v[54:57]
	v_mfma_f32_16x16x32_bf16 v[50:53], v[170:173], v[178:181], v[50:53]
	v_mfma_f32_16x16x32_bf16 v[38:41], v[162:165], v[192:195], v[38:41]
	v_mfma_f32_16x16x32_bf16 v[34:37], v[170:173], v[192:195], v[34:37]
	v_mfma_f32_16x16x32_bf16 v[22:25], v[162:165], v[200:203], v[22:25]
	v_mfma_f32_16x16x32_bf16 v[18:21], v[170:173], v[200:203], v[18:21]
	v_mfma_f32_16x16x32_bf16 v[6:9], v[162:165], v[208:211], v[6:9]
	v_mfma_f32_16x16x32_bf16 v[2:5], v[170:173], v[208:211], v[2:5]
	v_mfma_f32_16x16x32_bf16 v[54:57], v[166:169], v[188:191], v[54:57]
	v_mfma_f32_16x16x32_bf16 v[50:53], v[174:177], v[188:191], v[50:53]
	v_mfma_f32_16x16x32_bf16 v[38:41], v[166:169], v[196:199], v[38:41]
	v_mfma_f32_16x16x32_bf16 v[34:37], v[174:177], v[196:199], v[34:37]
	v_mfma_f32_16x16x32_bf16 v[22:25], v[166:169], v[204:207], v[22:25]
	v_mfma_f32_16x16x32_bf16 v[18:21], v[174:177], v[204:207], v[18:21]
	v_mfma_f32_16x16x32_bf16 v[6:9], v[166:169], v[212:215], v[6:9]
	v_mfma_f32_16x16x32_bf16 v[2:5], v[174:177], v[212:215], v[2:5]
	s_barrier
	s_add_i32 s58, 0, 0x18000
	s_add_i32 s59, 0, 0x1c000
	v_add_u32_e32 v142, s58, v182
	v_add_u32_e32 v174, s59, v182
	ds_read_b128 v[130:133], v142
	ds_read_b128 v[134:137], v142 offset:1024
	ds_read_b128 v[138:141], v142 offset:2048
	ds_read_b128 v[142:145], v142 offset:3072
	ds_read_b128 v[162:165], v174
	ds_read_b128 v[166:169], v174 offset:1024
	ds_read_b128 v[170:173], v174 offset:2048
	ds_read_b128 v[174:177], v174 offset:3072
	s_add_u32 s40, s40, 0x20000
	s_addc_u32 s41, s41, 0
	s_mov_b32 m0, s43
	v_lshl_add_u64 v[224:225], s[40:41], 0, v[146:147]
	ds_read_b128 v[178:181], v186 offset:32768
	ds_read_b128 v[188:191], v186 offset:33792
	ds_read_b128 v[192:195], v186 offset:34816
	ds_read_b128 v[196:199], v186 offset:35840
	ds_read_b128 v[200:203], v186 offset:36864
	ds_read_b128 v[204:207], v186 offset:37888
	ds_read_b128 v[208:211], v186 offset:38912
	ds_read_b128 v[212:215], v186 offset:39936
	global_load_lds_dwordx4 v[224:225], off
	v_lshl_add_u64 v[224:225], s[40:41], 0, v[150:151]
	s_mov_b32 m0, s44
	s_nop 0
	global_load_lds_dwordx4 v[224:225], off
	s_waitcnt vmcnt(8)
	s_waitcnt lgkmcnt(0)
	s_barrier
	s_waitcnt lgkmcnt(0)
	v_mfma_f32_16x16x32_bf16 v[126:129], v[130:133], v[178:181], v[126:129]
	v_mfma_f32_16x16x32_bf16 v[122:125], v[138:141], v[178:181], v[122:125]
	v_mfma_f32_16x16x32_bf16 v[110:113], v[130:133], v[192:195], v[110:113]
	v_mfma_f32_16x16x32_bf16 v[106:109], v[138:141], v[192:195], v[106:109]
	v_mfma_f32_16x16x32_bf16 v[94:97], v[130:133], v[200:203], v[94:97]
	v_mfma_f32_16x16x32_bf16 v[90:93], v[138:141], v[200:203], v[90:93]
	v_mfma_f32_16x16x32_bf16 v[78:81], v[130:133], v[208:211], v[78:81]
	v_mfma_f32_16x16x32_bf16 v[74:77], v[138:141], v[208:211], v[74:77]
	v_mfma_f32_16x16x32_bf16 v[126:129], v[134:137], v[188:191], v[126:129]
	v_mfma_f32_16x16x32_bf16 v[122:125], v[142:145], v[188:191], v[122:125]
	v_mfma_f32_16x16x32_bf16 v[110:113], v[134:137], v[196:199], v[110:113]
	v_mfma_f32_16x16x32_bf16 v[106:109], v[142:145], v[196:199], v[106:109]
	v_mfma_f32_16x16x32_bf16 v[94:97], v[134:137], v[204:207], v[94:97]
	v_mfma_f32_16x16x32_bf16 v[90:93], v[142:145], v[204:207], v[90:93]
	v_mfma_f32_16x16x32_bf16 v[78:81], v[134:137], v[212:215], v[78:81]
	v_mfma_f32_16x16x32_bf16 v[74:77], v[142:145], v[212:215], v[74:77]
	v_mfma_f32_16x16x32_bf16 v[118:121], v[162:165], v[178:181], v[118:121]
	v_mfma_f32_16x16x32_bf16 v[114:117], v[170:173], v[178:181], v[114:117]
	v_mfma_f32_16x16x32_bf16 v[102:105], v[162:165], v[192:195], v[102:105]
	v_mfma_f32_16x16x32_bf16 v[98:101], v[170:173], v[192:195], v[98:101]
	v_mfma_f32_16x16x32_bf16 v[86:89], v[162:165], v[200:203], v[86:89]
	v_mfma_f32_16x16x32_bf16 v[82:85], v[170:173], v[200:203], v[82:85]
	v_mfma_f32_16x16x32_bf16 v[70:73], v[162:165], v[208:211], v[70:73]
	v_mfma_f32_16x16x32_bf16 v[66:69], v[170:173], v[208:211], v[66:69]
	v_mfma_f32_16x16x32_bf16 v[118:121], v[166:169], v[188:191], v[118:121]
	v_mfma_f32_16x16x32_bf16 v[114:117], v[174:177], v[188:191], v[114:117]
	v_mfma_f32_16x16x32_bf16 v[102:105], v[166:169], v[196:199], v[102:105]
	v_mfma_f32_16x16x32_bf16 v[98:101], v[174:177], v[196:199], v[98:101]
	v_mfma_f32_16x16x32_bf16 v[86:89], v[166:169], v[204:207], v[86:89]
	v_mfma_f32_16x16x32_bf16 v[82:85], v[174:177], v[204:207], v[82:85]
	v_mfma_f32_16x16x32_bf16 v[70:73], v[166:169], v[212:215], v[70:73]
	v_mfma_f32_16x16x32_bf16 v[66:69], v[174:177], v[212:215], v[66:69]
	s_barrier
; #define PG8_STAGE(bufoff, gbase, voff) do { _Pragma("unroll") for (int _i = 0; _i < 2; ++_i) \
;         __builtin_amdgcn_global_load_lds((const unsigned*)((const char*)(gbase) + (voff)[_i]), (LAS unsigned*)(lds + (bufoff) + ldsw + _i * 8192), 16, 0, 0); } while (0)
; #define PG8_LDA(dst, b, h) do { _Pragma("unroll") for (int m = 0; m < 4; ++m) _Pragma("unroll") for (int k = 0; k < 2; ++k) dst[m][k] = *(const LAS bf16x8*)(lds + PG8_SA(b, h) + aoff + m * 2048 + k * 1024); } while (0)
; #define PG8_MMA(ai, bj, At, Bt) do { __builtin_amdgcn_s_setprio(1); _Pragma("unroll") for (int m = 0; m < 4; ++m) _Pragma("unroll") for (int n = 0; n < 2; ++n) _Pragma("unroll") for (int k = 0; k < 2; ++k) \
;         acc[ai][bj][m][n] = __builtin_amdgcn_mfma_f32_16x16x32_bf16(Bt[n][k], At[m][k], acc[ai][bj][m][n], 0, 0, 0); __builtin_amdgcn_s_setprio(0); } while (0)
; #define PG8_WAIT_V(n) asm volatile("s_waitcnt vmcnt(" #n ")" ::: "memory")
; #define PG8_WAIT_L(n) asm volatile("s_waitcnt lgkmcnt(" #n ")" ::: "memory")
; #define PG8_BAR __builtin_amdgcn_s_barrier()
; #define PG8_SCHED __builtin_amdgcn_sched_barrier(0)
; template <class Epi, bool ALIGN_EPI>
; __device__ __forceinline__ void gemm_phase(LAS unsigned char* lds, const Gemm g, const StaticOrder& S, const Epi& E) {
;     ...
;             PG8_LDA(At, 1, 1); PG8_STAGE(PG8_SB(1, 0), b3, voffB); PG8_STAGE(PG8_SB(1, 1), b3 + hsB, voffB); PG8_STAGE(PG8_SA(1, 0), a3, voffA);
;             PG8_WAIT_V(8); PG8_WAIT_L(0); PG8_BAR; PG8_MMA(1, 0, At, B0); PG8_MMA(1, 1, At, B1); PG8_BAR; PG8_SCHED;
;         }
	s_add_i32 s40, s58, s33
	v_lshl_add_u64 v[216:217], v[216:217], 0, s[8:9]
	s_mov_b32 m0, s40
	ds_read_b128 v[178:181], v186 offset:49152
	ds_read_b128 v[188:191], v186 offset:50176
	ds_read_b128 v[192:195], v186 offset:51200
	ds_read_b128 v[196:199], v186 offset:52224
	ds_read_b128 v[200:203], v186 offset:53248
	ds_read_b128 v[204:207], v186 offset:54272
	ds_read_b128 v[208:211], v186 offset:55296
	ds_read_b128 v[212:215], v186 offset:56320
	global_load_lds_dwordx4 v[216:217], off
	s_add_i32 m0, s40, 0x2000
	s_add_u32 s38, s38, 0x20080
	v_lshl_add_u64 v[216:217], v[218:219], 0, s[8:9]
	s_addc_u32 s39, s39, 0
	s_add_i32 s40, s59, s33
	global_load_lds_dwordx4 v[216:217], off
	v_lshl_add_u64 v[216:217], s[38:39], 0, v[148:149]
	s_mov_b32 m0, s40
	s_nop 0
	global_load_lds_dwordx4 v[216:217], off
	v_lshl_add_u64 v[216:217], s[38:39], 0, v[152:153]
	s_add_i32 m0, s40, 0x2000
	s_nop 0
	global_load_lds_dwordx4 v[216:217], off
	v_lshl_add_u64 v[216:217], v[220:221], 0, s[8:9]
	s_mov_b32 m0, s46
	s_nop 0
	global_load_lds_dwordx4 v[216:217], off
	v_lshl_add_u64 v[216:217], v[222:223], 0, s[8:9]
	s_mov_b32 m0, s47
	s_nop 0
	global_load_lds_dwordx4 v[216:217], off
	s_waitcnt vmcnt(8)
	s_waitcnt lgkmcnt(0)
	s_barrier
	s_waitcnt lgkmcnt(0)
	v_mfma_f32_16x16x32_bf16 v[62:65], v[130:133], v[178:181], v[62:65]
	v_mfma_f32_16x16x32_bf16 v[58:61], v[138:141], v[178:181], v[58:61]
	v_mfma_f32_16x16x32_bf16 v[46:49], v[130:133], v[192:195], v[46:49]
	v_mfma_f32_16x16x32_bf16 v[42:45], v[138:141], v[192:195], v[42:45]
	v_mfma_f32_16x16x32_bf16 v[30:33], v[130:133], v[200:203], v[30:33]
	v_mfma_f32_16x16x32_bf16 v[26:29], v[138:141], v[200:203], v[26:29]
	v_mfma_f32_16x16x32_bf16 v[14:17], v[130:133], v[208:211], v[14:17]
	v_mfma_f32_16x16x32_bf16 v[10:13], v[138:141], v[208:211], v[10:13]
	v_mfma_f32_16x16x32_bf16 v[62:65], v[134:137], v[188:191], v[62:65]
	v_mfma_f32_16x16x32_bf16 v[58:61], v[142:145], v[188:191], v[58:61]
	v_mfma_f32_16x16x32_bf16 v[46:49], v[134:137], v[196:199], v[46:49]
	v_mfma_f32_16x16x32_bf16 v[42:45], v[142:145], v[196:199], v[42:45]
	v_mfma_f32_16x16x32_bf16 v[30:33], v[134:137], v[204:207], v[30:33]
	v_mfma_f32_16x16x32_bf16 v[26:29], v[142:145], v[204:207], v[26:29]
	v_mfma_f32_16x16x32_bf16 v[14:17], v[134:137], v[212:215], v[14:17]
	v_mfma_f32_16x16x32_bf16 v[10:13], v[142:145], v[212:215], v[10:13]
	v_mfma_f32_16x16x32_bf16 v[54:57], v[162:165], v[178:181], v[54:57]
	v_mfma_f32_16x16x32_bf16 v[50:53], v[170:173], v[178:181], v[50:53]
	v_mfma_f32_16x16x32_bf16 v[38:41], v[162:165], v[192:195], v[38:41]
	v_mfma_f32_16x16x32_bf16 v[34:37], v[170:173], v[192:195], v[34:37]
	v_mfma_f32_16x16x32_bf16 v[22:25], v[162:165], v[200:203], v[22:25]
	v_mfma_f32_16x16x32_bf16 v[18:21], v[170:173], v[200:203], v[18:21]
	v_mfma_f32_16x16x32_bf16 v[6:9], v[162:165], v[208:211], v[6:9]
	v_mfma_f32_16x16x32_bf16 v[2:5], v[170:173], v[208:211], v[2:5]
	v_mfma_f32_16x16x32_bf16 v[54:57], v[166:169], v[188:191], v[54:57]
	v_mfma_f32_16x16x32_bf16 v[50:53], v[174:177], v[188:191], v[50:53]
	v_mfma_f32_16x16x32_bf16 v[38:41], v[166:169], v[196:199], v[38:41]
	v_mfma_f32_16x16x32_bf16 v[34:37], v[174:177], v[196:199], v[34:37]
	v_mfma_f32_16x16x32_bf16 v[22:25], v[166:169], v[204:207], v[22:25]
	v_mfma_f32_16x16x32_bf16 v[18:21], v[174:177], v[204:207], v[18:21]
	v_mfma_f32_16x16x32_bf16 v[6:9], v[166:169], v[212:215], v[6:9]
	v_mfma_f32_16x16x32_bf16 v[2:5], v[174:177], v[212:215], v[2:5]
	s_barrier
	s_add_i32 s57, s57, 2
	s_add_u32 s36, s36, 0x100
	s_addc_u32 s37, s37, 0
	s_add_u32 s55, s55, 0x100
	s_addc_u32 s56, s56, 0
	s_cmp_gt_u32 s57, 5
	s_cbranch_scc0 .LBB0_1131
	s_and_b64 vcc, exec, s[10:11]
	s_cbranch_vccz .LBB0_1134
	s_barrier

; #define PG8_STAGE(bufoff, gbase, voff) do { _Pragma("unroll") for (int _i = 0; _i < 2; ++_i) \
;         __builtin_amdgcn_global_load_lds((const unsigned*)((const char*)(gbase) + (voff)[_i]), (LAS unsigned*)(lds + (bufoff) + ldsw + _i * 8192), 16, 0, 0); } while (0)
; #define PG8_LDA(dst, b, h) do { _Pragma("unroll") for (int m = 0; m < 4; ++m) _Pragma("unroll") for (int k = 0; k < 2; ++k) dst[m][k] = *(const LAS bf16x8*)(lds + PG8_SA(b, h) + aoff + m * 2048 + k * 1024); } while (0)
; #define PG8_LDB(dst, b, h) do { _Pragma("unroll") for (int n = 0; n < 2; ++n) _Pragma("unroll") for (int k = 0; k < 2; ++k) dst[n][k] = *(const LAS bf16x8*)(lds + PG8_SB(b, h) + boff + n * 2048 + k * 1024); } while (0)
; #define PG8_MMA(ai, bj, At, Bt) do { __builtin_amdgcn_s_setprio(1); _Pragma("unroll") for (int m = 0; m < 4; ++m) _Pragma("unroll") for (int n = 0; n < 2; ++n) _Pragma("unroll") for (int k = 0; k < 2; ++k) \
;         acc[ai][bj][m][n] = __builtin_amdgcn_mfma_f32_16x16x32_bf16(Bt[n][k], At[m][k], acc[ai][bj][m][n], 0, 0, 0); __builtin_amdgcn_s_setprio(0); } while (0)
; #define PG8_WAIT_V(n) asm volatile("s_waitcnt vmcnt(" #n ")" ::: "memory")
; #define PG8_WAIT_L(n) asm volatile("s_waitcnt lgkmcnt(" #n ")" ::: "memory")
; #define PG8_BAR __builtin_amdgcn_s_barrier()
; #define PG8_SCHED __builtin_amdgcn_sched_barrier(0)
; template <class Epi, bool ALIGN_EPI>
; __device__ __forceinline__ void gemm_phase(LAS unsigned char* lds, const Gemm g, const StaticOrder& S, const Epi& E) {
;     ...
;         for (int t = 0; t < nt; t += 2) {
;             const bool last = (t == nt - 2);
;             const char* a1 = cA + (size_t)(t + 1) * kstepA;
;             const char* a2 = last ? nA : cA + (size_t)(t + 2) * kstepA; const char* b2 = last ? nB : cB + (size_t)(t + 2) * kstep;
;             const char* a3 = a2 + kstepA; const char* b3 = b2 + kstep;
;             PG8_LDB(B0, 0, 0); PG8_LDB(B1, 0, 1); PG8_SCHED; PG8_LDA(At, 0, 0); PG8_STAGE(PG8_SA(1, 1), a1 + hsA, voffA);
;             PG8_WAIT_V(8); PG8_WAIT_L(0); PG8_BAR; PG8_MMA(0, 0, At, B0); PG8_MMA(0, 1, At, B1); PG8_BAR; PG8_SCHED;
;             PG8_LDA(At, 0, 1); PG8_STAGE(PG8_SB(0, 0), b2, voffB); PG8_STAGE(PG8_SB(0, 1), b2 + hsB, voffB); PG8_STAGE(PG8_SA(0, 0), a2, voffA);
;             PG8_WAIT_V(8); PG8_WAIT_L(0); PG8_BAR; PG8_MMA(1, 0, At, B0); PG8_MMA(1, 1, At, B1); PG8_BAR; PG8_SCHED;
.LBB0_1212:
	ds_read_b128 v[130:133], v190
	ds_read_b128 v[134:137], v190 offset:1024
	ds_read_b128 v[138:141], v190 offset:2048
	ds_read_b128 v[142:145], v190 offset:3072
	ds_read_b128 v[146:149], v191
	ds_read_b128 v[150:153], v191 offset:1024
	ds_read_b128 v[170:173], v191 offset:2048
	ds_read_b128 v[174:177], v191 offset:3072
	s_add_u32 s26, s24, 0xfffc0080
	s_addc_u32 s27, s25, -1
	s_cmp_eq_u32 s46, 12
	s_cselect_b32 s29, s13, s27
	s_cselect_b32 s28, s21, s26
	s_cselect_b32 s27, s15, s45
	s_cselect_b32 s26, s43, s44
	v_lshl_add_u64 v[186:187], s[24:25], 0, v[162:163]
	s_add_i32 m0, s23, 0xc000
	ds_read_b128 v[178:181], v192
	ds_read_b128 v[182:185], v192 offset:1024
	ds_read_b128 v[194:197], v192 offset:2048
	ds_read_b128 v[198:201], v192 offset:3072
	ds_read_b128 v[202:205], v192 offset:4096
	ds_read_b128 v[206:209], v192 offset:5120
	ds_read_b128 v[210:213], v192 offset:6144
	ds_read_b128 v[214:217], v192 offset:7168
	global_load_lds_dwordx4 v[186:187], off
	v_lshl_add_u64 v[186:187], s[24:25], 0, v[164:165]
	s_add_i32 m0, s23, 0xe000
	s_nop 0
	global_load_lds_dwordx4 v[186:187], off
	s_waitcnt vmcnt(8)
	s_waitcnt lgkmcnt(0)
	s_barrier
	s_waitcnt lgkmcnt(0)
	v_mfma_f32_16x16x32_bf16 v[126:129], v[130:133], v[178:181], v[126:129]
	v_mfma_f32_16x16x32_bf16 v[122:125], v[138:141], v[178:181], v[122:125]
	v_mfma_f32_16x16x32_bf16 v[110:113], v[130:133], v[194:197], v[110:113]
	v_mfma_f32_16x16x32_bf16 v[106:109], v[138:141], v[194:197], v[106:109]
	v_mfma_f32_16x16x32_bf16 v[94:97], v[130:133], v[202:205], v[94:97]
	v_mfma_f32_16x16x32_bf16 v[90:93], v[138:141], v[202:205], v[90:93]
	v_mfma_f32_16x16x32_bf16 v[78:81], v[130:133], v[210:213], v[78:81]
	v_mfma_f32_16x16x32_bf16 v[74:77], v[138:141], v[210:213], v[74:77]
	v_mfma_f32_16x16x32_bf16 v[126:129], v[134:137], v[182:185], v[126:129]
	v_mfma_f32_16x16x32_bf16 v[122:125], v[142:145], v[182:185], v[122:125]
	v_mfma_f32_16x16x32_bf16 v[110:113], v[134:137], v[198:201], v[110:113]
	v_mfma_f32_16x16x32_bf16 v[106:109], v[142:145], v[198:201], v[106:109]
	v_mfma_f32_16x16x32_bf16 v[94:97], v[134:137], v[206:209], v[94:97]
	v_mfma_f32_16x16x32_bf16 v[90:93], v[142:145], v[206:209], v[90:93]
	v_mfma_f32_16x16x32_bf16 v[78:81], v[134:137], v[214:217], v[78:81]
	v_mfma_f32_16x16x32_bf16 v[74:77], v[142:145], v[214:217], v[74:77]
	v_mfma_f32_16x16x32_bf16 v[118:121], v[146:149], v[178:181], v[118:121]
	v_mfma_f32_16x16x32_bf16 v[114:117], v[170:173], v[178:181], v[114:117]
	v_mfma_f32_16x16x32_bf16 v[102:105], v[146:149], v[194:197], v[102:105]
	v_mfma_f32_16x16x32_bf16 v[98:101], v[170:173], v[194:197], v[98:101]
	v_mfma_f32_16x16x32_bf16 v[86:89], v[146:149], v[202:205], v[86:89]
	v_mfma_f32_16x16x32_bf16 v[82:85], v[170:173], v[202:205], v[82:85]
	v_mfma_f32_16x16x32_bf16 v[70:73], v[146:149], v[210:213], v[70:73]
	v_mfma_f32_16x16x32_bf16 v[66:69], v[170:173], v[210:213], v[66:69]
	v_mfma_f32_16x16x32_bf16 v[118:121], v[150:153], v[182:185], v[118:121]
	v_mfma_f32_16x16x32_bf16 v[114:117], v[174:177], v[182:185], v[114:117]
	v_mfma_f32_16x16x32_bf16 v[102:105], v[150:153], v[198:201], v[102:105]
	v_mfma_f32_16x16x32_bf16 v[98:101], v[174:177], v[198:201], v[98:101]
	v_mfma_f32_16x16x32_bf16 v[86:89], v[150:153], v[206:209], v[86:89]
	v_mfma_f32_16x16x32_bf16 v[82:85], v[174:177], v[206:209], v[82:85]
	v_mfma_f32_16x16x32_bf16 v[70:73], v[150:153], v[214:217], v[70:73]
	v_mfma_f32_16x16x32_bf16 v[66:69], v[174:177], v[214:217], v[66:69]
	s_barrier
	s_add_i32 s47, s41, s30
	v_lshl_add_u64 v[186:187], s[26:27], 0, v[156:157]
	s_mov_b32 m0, s47
	ds_read_b128 v[178:181], v192 offset:16384
	ds_read_b128 v[182:185], v192 offset:17408
	ds_read_b128 v[194:197], v192 offset:18432
	ds_read_b128 v[198:201], v192 offset:19456
	ds_read_b128 v[202:205], v192 offset:20480
	ds_read_b128 v[206:209], v192 offset:21504
	ds_read_b128 v[210:213], v192 offset:22528
	ds_read_b128 v[214:217], v192 offset:23552
	global_load_lds_dwordx4 v[186:187], off
	s_add_i32 m0, s47, 0x2000
	s_add_u32 s48, s26, 0x40000
	v_lshl_add_u64 v[218:219], s[26:27], 0, v[160:161]
	s_addc_u32 s49, s27, 0
	s_add_i32 s47, s42, s30
	global_load_lds_dwordx4 v[218:219], off
	v_lshl_add_u64 v[220:221], s[48:49], 0, v[156:157]
	s_mov_b32 m0, s47
	v_lshl_add_u64 v[222:223], s[28:29], 0, v[158:159]
	global_load_lds_dwordx4 v[220:221], off
	v_lshl_add_u64 v[220:221], s[48:49], 0, v[160:161]
	s_add_i32 m0, s47, 0x2000
	s_nop 0
	global_load_lds_dwordx4 v[220:221], off
	v_lshl_add_u64 v[220:221], s[28:29], 0, v[154:155]
	s_mov_b32 m0, s23
	s_nop 0
	global_load_lds_dwordx4 v[220:221], off
	s_mov_b32 m0, s31
	s_nop 0
	global_load_lds_dwordx4 v[222:223], off
	s_waitcnt vmcnt(8)
	s_waitcnt lgkmcnt(0)
	s_barrier
; #define PG8_STAGE(bufoff, gbase, voff) do { _Pragma("unroll") for (int _i = 0; _i < 2; ++_i) \
;         __builtin_amdgcn_global_load_lds((const unsigned*)((const char*)(gbase) + (voff)[_i]), (LAS unsigned*)(lds + (bufoff) + ldsw + _i * 8192), 16, 0, 0); } while (0)
; #define PG8_LDA(dst, b, h) do { _Pragma("unroll") for (int m = 0; m < 4; ++m) _Pragma("unroll") for (int k = 0; k < 2; ++k) dst[m][k] = *(const LAS bf16x8*)(lds + PG8_SA(b, h) + aoff + m * 2048 + k * 1024); } while (0)
; #define PG8_LDB(dst, b, h) do { _Pragma("unroll") for (int n = 0; n < 2; ++n) _Pragma("unroll") for (int k = 0; k < 2; ++k) dst[n][k] = *(const LAS bf16x8*)(lds + PG8_SB(b, h) + boff + n * 2048 + k * 1024); } while (0)
; #define PG8_MMA(ai, bj, At, Bt) do { __builtin_amdgcn_s_setprio(1); _Pragma("unroll") for (int m = 0; m < 4; ++m) _Pragma("unroll") for (int n = 0; n < 2; ++n) _Pragma("unroll") for (int k = 0; k < 2; ++k) \
;         acc[ai][bj][m][n] = __builtin_amdgcn_mfma_f32_16x16x32_bf16(Bt[n][k], At[m][k], acc[ai][bj][m][n], 0, 0, 0); __builtin_amdgcn_s_setprio(0); } while (0)
; #define PG8_WAIT_V(n) asm volatile("s_waitcnt vmcnt(" #n ")" ::: "memory")
; #define PG8_WAIT_L(n) asm volatile("s_waitcnt lgkmcnt(" #n ")" ::: "memory")
; #define PG8_BAR __builtin_amdgcn_s_barrier()
; #define PG8_SCHED __builtin_amdgcn_sched_barrier(0)
; template <class Epi, bool ALIGN_EPI>
; __device__ __forceinline__ void gemm_phase(LAS unsigned char* lds, const Gemm g, const StaticOrder& S, const Epi& E) {
;     ...
;             PG8_WAIT_V(8); PG8_WAIT_L(0); PG8_BAR; PG8_MMA(1, 0, At, B0); PG8_MMA(1, 1, At, B1); PG8_BAR; PG8_SCHED;
;             PG8_LDB(B0, 1, 0); PG8_LDB(B1, 1, 1); PG8_SCHED; PG8_LDA(At, 1, 0); PG8_STAGE(PG8_SA(0, 1), a2 + hsA, voffA);
;             PG8_WAIT_V(8); PG8_WAIT_L(0); PG8_BAR; PG8_MMA(0, 0, At, B0); PG8_MMA(0, 1, At, B1); PG8_BAR; PG8_SCHED;
;             PG8_LDA(At, 1, 1); PG8_STAGE(PG8_SB(1, 0), b3, voffB); PG8_STAGE(PG8_SB(1, 1), b3 + hsB, voffB); PG8_STAGE(PG8_SA(1, 0), a3, voffA);
;             PG8_WAIT_V(8); PG8_WAIT_L(0); PG8_BAR; PG8_MMA(1, 0, At, B0); PG8_MMA(1, 1, At, B1); PG8_BAR; PG8_SCHED;
	s_waitcnt lgkmcnt(0)
	v_mfma_f32_16x16x32_bf16 v[62:65], v[130:133], v[178:181], v[62:65]
	v_mfma_f32_16x16x32_bf16 v[58:61], v[138:141], v[178:181], v[58:61]
	v_mfma_f32_16x16x32_bf16 v[46:49], v[130:133], v[194:197], v[46:49]
	v_mfma_f32_16x16x32_bf16 v[42:45], v[138:141], v[194:197], v[42:45]
	v_mfma_f32_16x16x32_bf16 v[30:33], v[130:133], v[202:205], v[30:33]
	v_mfma_f32_16x16x32_bf16 v[26:29], v[138:141], v[202:205], v[26:29]
	v_mfma_f32_16x16x32_bf16 v[14:17], v[130:133], v[210:213], v[14:17]
	v_mfma_f32_16x16x32_bf16 v[10:13], v[138:141], v[210:213], v[10:13]
	v_mfma_f32_16x16x32_bf16 v[62:65], v[134:137], v[182:185], v[62:65]
	v_mfma_f32_16x16x32_bf16 v[58:61], v[142:145], v[182:185], v[58:61]
	v_mfma_f32_16x16x32_bf16 v[46:49], v[134:137], v[198:201], v[46:49]
	v_mfma_f32_16x16x32_bf16 v[42:45], v[142:145], v[198:201], v[42:45]
	v_mfma_f32_16x16x32_bf16 v[30:33], v[134:137], v[206:209], v[30:33]
	v_mfma_f32_16x16x32_bf16 v[26:29], v[142:145], v[206:209], v[26:29]
	v_mfma_f32_16x16x32_bf16 v[14:17], v[134:137], v[214:217], v[14:17]
	v_mfma_f32_16x16x32_bf16 v[10:13], v[142:145], v[214:217], v[10:13]
	v_mfma_f32_16x16x32_bf16 v[54:57], v[146:149], v[178:181], v[54:57]
	v_mfma_f32_16x16x32_bf16 v[50:53], v[170:173], v[178:181], v[50:53]
	v_mfma_f32_16x16x32_bf16 v[38:41], v[146:149], v[194:197], v[38:41]
	v_mfma_f32_16x16x32_bf16 v[34:37], v[170:173], v[194:197], v[34:37]
	v_mfma_f32_16x16x32_bf16 v[22:25], v[146:149], v[202:205], v[22:25]
	v_mfma_f32_16x16x32_bf16 v[18:21], v[170:173], v[202:205], v[18:21]
	v_mfma_f32_16x16x32_bf16 v[6:9], v[146:149], v[210:213], v[6:9]
	v_mfma_f32_16x16x32_bf16 v[2:5], v[170:173], v[210:213], v[2:5]
	v_mfma_f32_16x16x32_bf16 v[54:57], v[150:153], v[182:185], v[54:57]
	v_mfma_f32_16x16x32_bf16 v[50:53], v[174:177], v[182:185], v[50:53]
	v_mfma_f32_16x16x32_bf16 v[38:41], v[150:153], v[198:201], v[38:41]
	v_mfma_f32_16x16x32_bf16 v[34:37], v[174:177], v[198:201], v[34:37]
	v_mfma_f32_16x16x32_bf16 v[22:25], v[150:153], v[206:209], v[22:25]
	v_mfma_f32_16x16x32_bf16 v[18:21], v[174:177], v[206:209], v[18:21]
	v_mfma_f32_16x16x32_bf16 v[6:9], v[150:153], v[214:217], v[6:9]
	v_mfma_f32_16x16x32_bf16 v[2:5], v[174:177], v[214:217], v[2:5]
	s_barrier
	s_add_i32 s47, 0, 0x18000
	s_add_i32 s48, 0, 0x1c000
	v_add_u32_e32 v142, s47, v188
	v_add_u32_e32 v174, s48, v188
	ds_read_b128 v[130:133], v142
	ds_read_b128 v[134:137], v142 offset:1024
	ds_read_b128 v[138:141], v142 offset:2048
	ds_read_b128 v[142:145], v142 offset:3072
	ds_read_b128 v[146:149], v174
	ds_read_b128 v[150:153], v174 offset:1024
	ds_read_b128 v[170:173], v174 offset:2048
	ds_read_b128 v[174:177], v174 offset:3072
	s_add_u32 s28, s28, 0x40000
	s_addc_u32 s29, s29, 0
	s_mov_b32 m0, s33
	v_lshl_add_u64 v[224:225], s[28:29], 0, v[154:155]
	ds_read_b128 v[178:181], v192 offset:32768
	ds_read_b128 v[182:185], v192 offset:33792
	ds_read_b128 v[194:197], v192 offset:34816
	ds_read_b128 v[198:201], v192 offset:35840
	ds_read_b128 v[202:205], v192 offset:36864
	ds_read_b128 v[206:209], v192 offset:37888
	ds_read_b128 v[210:213], v192 offset:38912
	ds_read_b128 v[214:217], v192 offset:39936
	global_load_lds_dwordx4 v[224:225], off
	v_lshl_add_u64 v[224:225], s[28:29], 0, v[158:159]
	s_mov_b32 m0, s34
	s_nop 0
	global_load_lds_dwordx4 v[224:225], off
	s_waitcnt vmcnt(8)
	s_waitcnt lgkmcnt(0)
	s_barrier
	s_waitcnt lgkmcnt(0)
	v_mfma_f32_16x16x32_bf16 v[126:129], v[130:133], v[178:181], v[126:129]
	v_mfma_f32_16x16x32_bf16 v[122:125], v[138:141], v[178:181], v[122:125]
	v_mfma_f32_16x16x32_bf16 v[110:113], v[130:133], v[194:197], v[110:113]
	v_mfma_f32_16x16x32_bf16 v[106:109], v[138:141], v[194:197], v[106:109]
	v_mfma_f32_16x16x32_bf16 v[94:97], v[130:133], v[202:205], v[94:97]
	v_mfma_f32_16x16x32_bf16 v[90:93], v[138:141], v[202:205], v[90:93]
	v_mfma_f32_16x16x32_bf16 v[78:81], v[130:133], v[210:213], v[78:81]
	v_mfma_f32_16x16x32_bf16 v[74:77], v[138:141], v[210:213], v[74:77]
	v_mfma_f32_16x16x32_bf16 v[126:129], v[134:137], v[182:185], v[126:129]
	v_mfma_f32_16x16x32_bf16 v[122:125], v[142:145], v[182:185], v[122:125]
	v_mfma_f32_16x16x32_bf16 v[110:113], v[134:137], v[198:201], v[110:113]
	v_mfma_f32_16x16x32_bf16 v[106:109], v[142:145], v[198:201], v[106:109]
	v_mfma_f32_16x16x32_bf16 v[94:97], v[134:137], v[206:209], v[94:97]
	v_mfma_f32_16x16x32_bf16 v[90:93], v[142:145], v[206:209], v[90:93]
	v_mfma_f32_16x16x32_bf16 v[78:81], v[134:137], v[214:217], v[78:81]
	v_mfma_f32_16x16x32_bf16 v[74:77], v[142:145], v[214:217], v[74:77]
	v_mfma_f32_16x16x32_bf16 v[118:121], v[146:149], v[178:181], v[118:121]
	v_mfma_f32_16x16x32_bf16 v[114:117], v[170:173], v[178:181], v[114:117]
	v_mfma_f32_16x16x32_bf16 v[102:105], v[146:149], v[194:197], v[102:105]
	v_mfma_f32_16x16x32_bf16 v[98:101], v[170:173], v[194:197], v[98:101]
	v_mfma_f32_16x16x32_bf16 v[86:89], v[146:149], v[202:205], v[86:89]
	v_mfma_f32_16x16x32_bf16 v[82:85], v[170:173], v[202:205], v[82:85]
	v_mfma_f32_16x16x32_bf16 v[70:73], v[146:149], v[210:213], v[70:73]
	v_mfma_f32_16x16x32_bf16 v[66:69], v[170:173], v[210:213], v[66:69]
	v_mfma_f32_16x16x32_bf16 v[118:121], v[150:153], v[182:185], v[118:121]
	v_mfma_f32_16x16x32_bf16 v[114:117], v[174:177], v[182:185], v[114:117]
	v_mfma_f32_16x16x32_bf16 v[102:105], v[150:153], v[198:201], v[102:105]
	v_mfma_f32_16x16x32_bf16 v[98:101], v[174:177], v[198:201], v[98:101]
	v_mfma_f32_16x16x32_bf16 v[86:89], v[150:153], v[206:209], v[86:89]
	v_mfma_f32_16x16x32_bf16 v[82:85], v[174:177], v[206:209], v[82:85]
	v_mfma_f32_16x16x32_bf16 v[70:73], v[150:153], v[214:217], v[70:73]
	v_mfma_f32_16x16x32_bf16 v[66:69], v[174:177], v[214:217], v[66:69]
	s_barrier
; #define PG8_STAGE(bufoff, gbase, voff) do { _Pragma("unroll") for (int _i = 0; _i < 2; ++_i) \
;         __builtin_amdgcn_global_load_lds((const unsigned*)((const char*)(gbase) + (voff)[_i]), (LAS unsigned*)(lds + (bufoff) + ldsw + _i * 8192), 16, 0, 0); } while (0)
; #define PG8_LDA(dst, b, h) do { _Pragma("unroll") for (int m = 0; m < 4; ++m) _Pragma("unroll") for (int k = 0; k < 2; ++k) dst[m][k] = *(const LAS bf16x8*)(lds + PG8_SA(b, h) + aoff + m * 2048 + k * 1024); } while (0)
; #define PG8_MMA(ai, bj, At, Bt) do { __builtin_amdgcn_s_setprio(1); _Pragma("unroll") for (int m = 0; m < 4; ++m) _Pragma("unroll") for (int n = 0; n < 2; ++n) _Pragma("unroll") for (int k = 0; k < 2; ++k) \
;         acc[ai][bj][m][n] = __builtin_amdgcn_mfma_f32_16x16x32_bf16(Bt[n][k], At[m][k], acc[ai][bj][m][n], 0, 0, 0); __builtin_amdgcn_s_setprio(0); } while (0)
; #define PG8_WAIT_V(n) asm volatile("s_waitcnt vmcnt(" #n ")" ::: "memory")
; #define PG8_WAIT_L(n) asm volatile("s_waitcnt lgkmcnt(" #n ")" ::: "memory")
; #define PG8_BAR __builtin_amdgcn_s_barrier()
; #define PG8_SCHED __builtin_amdgcn_sched_barrier(0)
; template <class Epi, bool ALIGN_EPI>
; __device__ __forceinline__ void gemm_phase(LAS unsigned char* lds, const Gemm g, const StaticOrder& S, const Epi& E) {
;     ...
;             PG8_LDA(At, 1, 1); PG8_STAGE(PG8_SB(1, 0), b3, voffB); PG8_STAGE(PG8_SB(1, 1), b3 + hsB, voffB); PG8_STAGE(PG8_SA(1, 0), a3, voffA);
;             PG8_WAIT_V(8); PG8_WAIT_L(0); PG8_BAR; PG8_MMA(1, 0, At, B0); PG8_MMA(1, 1, At, B1); PG8_BAR; PG8_SCHED;
;         }
	s_add_i32 s28, s47, s30
	v_lshl_add_u64 v[186:187], v[186:187], 0, s[8:9]
	s_mov_b32 m0, s28
	ds_read_b128 v[178:181], v192 offset:49152
	ds_read_b128 v[182:185], v192 offset:50176
	ds_read_b128 v[194:197], v192 offset:51200
	ds_read_b128 v[198:201], v192 offset:52224
	ds_read_b128 v[202:205], v192 offset:53248
	ds_read_b128 v[206:209], v192 offset:54272
	ds_read_b128 v[210:213], v192 offset:55296
	ds_read_b128 v[214:217], v192 offset:56320
	global_load_lds_dwordx4 v[186:187], off
	s_add_i32 m0, s28, 0x2000
	s_add_u32 s26, s26, 0x40080
	v_lshl_add_u64 v[186:187], v[218:219], 0, s[8:9]
	s_addc_u32 s27, s27, 0
	s_add_i32 s28, s48, s30
	global_load_lds_dwordx4 v[186:187], off
	v_lshl_add_u64 v[186:187], s[26:27], 0, v[156:157]
	s_mov_b32 m0, s28
	s_nop 0
	global_load_lds_dwordx4 v[186:187], off
	v_lshl_add_u64 v[186:187], s[26:27], 0, v[160:161]
	s_add_i32 m0, s28, 0x2000
	s_nop 0
	global_load_lds_dwordx4 v[186:187], off
	v_lshl_add_u64 v[186:187], v[220:221], 0, s[8:9]
	s_mov_b32 m0, s36
	s_nop 0
	global_load_lds_dwordx4 v[186:187], off
	v_lshl_add_u64 v[186:187], v[222:223], 0, s[8:9]
	s_mov_b32 m0, s37
	s_nop 0
	global_load_lds_dwordx4 v[186:187], off
	s_waitcnt vmcnt(8)
	s_waitcnt lgkmcnt(0)
	s_barrier
	s_waitcnt lgkmcnt(0)
	v_mfma_f32_16x16x32_bf16 v[62:65], v[130:133], v[178:181], v[62:65]
	v_mfma_f32_16x16x32_bf16 v[58:61], v[138:141], v[178:181], v[58:61]
	v_mfma_f32_16x16x32_bf16 v[46:49], v[130:133], v[194:197], v[46:49]
	v_mfma_f32_16x16x32_bf16 v[42:45], v[138:141], v[194:197], v[42:45]
	v_mfma_f32_16x16x32_bf16 v[30:33], v[130:133], v[202:205], v[30:33]
	v_mfma_f32_16x16x32_bf16 v[26:29], v[138:141], v[202:205], v[26:29]
	v_mfma_f32_16x16x32_bf16 v[14:17], v[130:133], v[210:213], v[14:17]
	v_mfma_f32_16x16x32_bf16 v[10:13], v[138:141], v[210:213], v[10:13]
	v_mfma_f32_16x16x32_bf16 v[62:65], v[134:137], v[182:185], v[62:65]
	v_mfma_f32_16x16x32_bf16 v[58:61], v[142:145], v[182:185], v[58:61]
	v_mfma_f32_16x16x32_bf16 v[46:49], v[134:137], v[198:201], v[46:49]
	v_mfma_f32_16x16x32_bf16 v[42:45], v[142:145], v[198:201], v[42:45]
	v_mfma_f32_16x16x32_bf16 v[30:33], v[134:137], v[206:209], v[30:33]
	v_mfma_f32_16x16x32_bf16 v[26:29], v[142:145], v[206:209], v[26:29]
	v_mfma_f32_16x16x32_bf16 v[14:17], v[134:137], v[214:217], v[14:17]
	v_mfma_f32_16x16x32_bf16 v[10:13], v[142:145], v[214:217], v[10:13]
	v_mfma_f32_16x16x32_bf16 v[54:57], v[146:149], v[178:181], v[54:57]
	v_mfma_f32_16x16x32_bf16 v[50:53], v[170:173], v[178:181], v[50:53]
	v_mfma_f32_16x16x32_bf16 v[38:41], v[146:149], v[194:197], v[38:41]
	v_mfma_f32_16x16x32_bf16 v[34:37], v[170:173], v[194:197], v[34:37]
	v_mfma_f32_16x16x32_bf16 v[22:25], v[146:149], v[202:205], v[22:25]
	v_mfma_f32_16x16x32_bf16 v[18:21], v[170:173], v[202:205], v[18:21]
	v_mfma_f32_16x16x32_bf16 v[6:9], v[146:149], v[210:213], v[6:9]
	v_mfma_f32_16x16x32_bf16 v[2:5], v[170:173], v[210:213], v[2:5]
	v_mfma_f32_16x16x32_bf16 v[54:57], v[150:153], v[182:185], v[54:57]
	v_mfma_f32_16x16x32_bf16 v[50:53], v[174:177], v[182:185], v[50:53]
	v_mfma_f32_16x16x32_bf16 v[38:41], v[150:153], v[198:201], v[38:41]
	v_mfma_f32_16x16x32_bf16 v[34:37], v[174:177], v[198:201], v[34:37]
	v_mfma_f32_16x16x32_bf16 v[22:25], v[150:153], v[206:209], v[22:25]
	v_mfma_f32_16x16x32_bf16 v[18:21], v[174:177], v[206:209], v[18:21]
	v_mfma_f32_16x16x32_bf16 v[6:9], v[150:153], v[214:217], v[6:9]
	v_mfma_f32_16x16x32_bf16 v[2:5], v[174:177], v[214:217], v[2:5]
	s_barrier
	s_add_i32 s46, s46, 2
	s_add_u32 s24, s24, 0x100
	s_addc_u32 s25, s25, 0
	s_add_u32 s44, s44, 0x100
	s_addc_u32 s45, s45, 0
	s_cmp_gt_u32 s46, 13
	s_cbranch_scc0 .LBB0_1212
	s_and_b64 vcc, exec, s[10:11]
	s_cbranch_vccz .LBB0_1215
	s_barrier

; #define PG8_STAGE(bufoff, gbase, voff) do { _Pragma("unroll") for (int _i = 0; _i < 2; ++_i) \
;         __builtin_amdgcn_global_load_lds((const unsigned*)((const char*)(gbase) + (voff)[_i]), (LAS unsigned*)(lds + (bufoff) + ldsw + _i * 8192), 16, 0, 0); } while (0)
; #define PG8_LDA(dst, b, h) do { _Pragma("unroll") for (int m = 0; m < 4; ++m) _Pragma("unroll") for (int k = 0; k < 2; ++k) dst[m][k] = *(const LAS bf16x8*)(lds + PG8_SA(b, h) + aoff + m * 2048 + k * 1024); } while (0)
; #define PG8_LDB(dst, b, h) do { _Pragma("unroll") for (int n = 0; n < 2; ++n) _Pragma("unroll") for (int k = 0; k < 2; ++k) dst[n][k] = *(const LAS bf16x8*)(lds + PG8_SB(b, h) + boff + n * 2048 + k * 1024); } while (0)
; #define PG8_MMA(ai, bj, At, Bt) do { __builtin_amdgcn_s_setprio(1); _Pragma("unroll") for (int m = 0; m < 4; ++m) _Pragma("unroll") for (int n = 0; n < 2; ++n) _Pragma("unroll") for (int k = 0; k < 2; ++k) \
;         acc[ai][bj][m][n] = __builtin_amdgcn_mfma_f32_16x16x32_bf16(Bt[n][k], At[m][k], acc[ai][bj][m][n], 0, 0, 0); __builtin_amdgcn_s_setprio(0); } while (0)
; #define PG8_WAIT_V(n) asm volatile("s_waitcnt vmcnt(" #n ")" ::: "memory")
; #define PG8_WAIT_L(n) asm volatile("s_waitcnt lgkmcnt(" #n ")" ::: "memory")
; #define PG8_BAR __builtin_amdgcn_s_barrier()
; #define PG8_SCHED __builtin_amdgcn_sched_barrier(0)
; template <class Epi, bool ALIGN_EPI>
; __device__ __forceinline__ void gemm_phase(LAS unsigned char* lds, const Gemm g, const StaticOrder& S, const Epi& E) {
;     ...
;         for (int t = 0; t < nt; t += 2) {
;             const bool last = (t == nt - 2);
;             const char* a1 = cA + (size_t)(t + 1) * kstepA;
;             const char* a2 = last ? nA : cA + (size_t)(t + 2) * kstepA; const char* b2 = last ? nB : cB + (size_t)(t + 2) * kstep;
;             const char* a3 = a2 + kstepA; const char* b3 = b2 + kstep;
;             PG8_LDB(B0, 0, 0); PG8_LDB(B1, 0, 1); PG8_SCHED; PG8_LDA(At, 0, 0); PG8_STAGE(PG8_SA(1, 1), a1 + hsA, voffA);
;             PG8_WAIT_V(8); PG8_WAIT_L(0); PG8_BAR; PG8_MMA(0, 0, At, B0); PG8_MMA(0, 1, At, B1); PG8_BAR; PG8_SCHED;
;             PG8_LDA(At, 0, 1); PG8_STAGE(PG8_SB(0, 0), b2, voffB); PG8_STAGE(PG8_SB(0, 1), b2 + hsB, voffB); PG8_STAGE(PG8_SA(0, 0), a2, voffA);
;             PG8_WAIT_V(8); PG8_WAIT_L(0); PG8_BAR; PG8_MMA(1, 0, At, B0); PG8_MMA(1, 1, At, B1); PG8_BAR; PG8_SCHED;
.LBB0_1299:
	ds_read_b128 v[156:159], v151
	ds_read_b128 v[160:163], v151 offset:1024
	ds_read_b128 v[164:167], v151 offset:2048
	ds_read_b128 v[168:171], v151 offset:3072
	ds_read_b128 v[172:175], v152
	ds_read_b128 v[176:179], v152 offset:1024
	ds_read_b128 v[180:183], v152 offset:2048
	ds_read_b128 v[184:187], v152 offset:3072
	s_add_u32 s22, s20, 0xfffc0080
	s_addc_u32 s23, s21, -1
	s_cmp_eq_u32 s48, 12
	s_cselect_b32 s25, s11, s23
	s_cselect_b32 s24, s44, s22
	s_cselect_b32 s23, s13, s47
	s_cselect_b32 s22, s45, s46
	v_lshl_add_u64 v[220:221], s[20:21], 0, v[140:141]
	s_add_i32 m0, s19, 0xc000
	ds_read_b128 v[188:191], v153
	ds_read_b128 v[192:195], v153 offset:1024
	ds_read_b128 v[196:199], v153 offset:2048
	ds_read_b128 v[200:203], v153 offset:3072
	ds_read_b128 v[204:207], v153 offset:4096
	ds_read_b128 v[208:211], v153 offset:5120
	ds_read_b128 v[212:215], v153 offset:6144
	ds_read_b128 v[216:219], v153 offset:7168
	global_load_lds_dwordx4 v[220:221], off
	v_lshl_add_u64 v[220:221], s[20:21], 0, v[142:143]
	s_add_i32 m0, s19, 0xe000
	s_nop 0
	global_load_lds_dwordx4 v[220:221], off
	s_waitcnt vmcnt(8)
	s_waitcnt lgkmcnt(0)
	s_barrier
	s_waitcnt lgkmcnt(0)
	v_mfma_f32_16x16x32_bf16 v[118:121], v[156:159], v[188:191], v[118:121]
	v_mfma_f32_16x16x32_bf16 v[114:117], v[164:167], v[188:191], v[114:117]
	v_mfma_f32_16x16x32_bf16 v[106:109], v[156:159], v[196:199], v[106:109]
	v_mfma_f32_16x16x32_bf16 v[102:105], v[164:167], v[196:199], v[102:105]
	v_mfma_f32_16x16x32_bf16 v[94:97], v[156:159], v[204:207], v[94:97]
	v_mfma_f32_16x16x32_bf16 v[90:93], v[164:167], v[204:207], v[90:93]
	v_mfma_f32_16x16x32_bf16 v[78:81], v[156:159], v[212:215], v[78:81]
	v_mfma_f32_16x16x32_bf16 v[74:77], v[164:167], v[212:215], v[74:77]
	v_mfma_f32_16x16x32_bf16 v[118:121], v[160:163], v[192:195], v[118:121]
	v_mfma_f32_16x16x32_bf16 v[114:117], v[168:171], v[192:195], v[114:117]
	v_mfma_f32_16x16x32_bf16 v[106:109], v[160:163], v[200:203], v[106:109]
	v_mfma_f32_16x16x32_bf16 v[102:105], v[168:171], v[200:203], v[102:105]
	v_mfma_f32_16x16x32_bf16 v[94:97], v[160:163], v[208:211], v[94:97]
	v_mfma_f32_16x16x32_bf16 v[90:93], v[168:171], v[208:211], v[90:93]
	v_mfma_f32_16x16x32_bf16 v[78:81], v[160:163], v[216:219], v[78:81]
	v_mfma_f32_16x16x32_bf16 v[74:77], v[168:171], v[216:219], v[74:77]
	v_mfma_f32_16x16x32_bf16 v[126:129], v[172:175], v[188:191], v[126:129]
	v_mfma_f32_16x16x32_bf16 v[122:125], v[180:183], v[188:191], v[122:125]
	v_mfma_f32_16x16x32_bf16 v[110:113], v[172:175], v[196:199], v[110:113]
	v_mfma_f32_16x16x32_bf16 v[98:101], v[180:183], v[196:199], v[98:101]
	v_mfma_f32_16x16x32_bf16 v[86:89], v[172:175], v[204:207], v[86:89]
	v_mfma_f32_16x16x32_bf16 v[82:85], v[180:183], v[204:207], v[82:85]
	v_mfma_f32_16x16x32_bf16 v[70:73], v[172:175], v[212:215], v[70:73]
	v_mfma_f32_16x16x32_bf16 v[66:69], v[180:183], v[212:215], v[66:69]
	v_mfma_f32_16x16x32_bf16 v[126:129], v[176:179], v[192:195], v[126:129]
	v_mfma_f32_16x16x32_bf16 v[122:125], v[184:187], v[192:195], v[122:125]
	v_mfma_f32_16x16x32_bf16 v[110:113], v[176:179], v[200:203], v[110:113]
	v_mfma_f32_16x16x32_bf16 v[98:101], v[184:187], v[200:203], v[98:101]
	v_mfma_f32_16x16x32_bf16 v[86:89], v[176:179], v[208:211], v[86:89]
	v_mfma_f32_16x16x32_bf16 v[82:85], v[184:187], v[208:211], v[82:85]
	v_mfma_f32_16x16x32_bf16 v[70:73], v[176:179], v[216:219], v[70:73]
	v_mfma_f32_16x16x32_bf16 v[66:69], v[184:187], v[216:219], v[66:69]
	s_barrier
	s_add_i32 s49, s40, s26
	v_lshl_add_u64 v[220:221], s[22:23], 0, v[134:135]
	s_mov_b32 m0, s49
	ds_read_b128 v[188:191], v153 offset:16384
	ds_read_b128 v[192:195], v153 offset:17408
	ds_read_b128 v[196:199], v153 offset:18432
	ds_read_b128 v[200:203], v153 offset:19456
	ds_read_b128 v[204:207], v153 offset:20480
	ds_read_b128 v[208:211], v153 offset:21504
	ds_read_b128 v[212:215], v153 offset:22528
	ds_read_b128 v[216:219], v153 offset:23552
	global_load_lds_dwordx4 v[220:221], off
	s_add_i32 m0, s49, 0x2000
	s_add_u32 s50, s22, 0x40000
	v_lshl_add_u64 v[222:223], s[22:23], 0, v[130:131]
	s_addc_u32 s51, s23, 0
	s_add_i32 s49, s41, s26
	global_load_lds_dwordx4 v[222:223], off
	v_lshl_add_u64 v[224:225], s[50:51], 0, v[134:135]
	s_mov_b32 m0, s49
	v_lshl_add_u64 v[226:227], s[24:25], 0, v[132:133]
	global_load_lds_dwordx4 v[224:225], off
	v_lshl_add_u64 v[224:225], s[50:51], 0, v[130:131]
	s_add_i32 m0, s49, 0x2000
	s_nop 0
	global_load_lds_dwordx4 v[224:225], off
	v_lshl_add_u64 v[224:225], s[24:25], 0, v[136:137]
	s_mov_b32 m0, s19
	s_nop 0
	global_load_lds_dwordx4 v[224:225], off
	s_mov_b32 m0, s29
	s_nop 0
	global_load_lds_dwordx4 v[226:227], off
	s_waitcnt vmcnt(8)
	s_waitcnt lgkmcnt(0)
	s_barrier
; #define PG8_STAGE(bufoff, gbase, voff) do { _Pragma("unroll") for (int _i = 0; _i < 2; ++_i) \
;         __builtin_amdgcn_global_load_lds((const unsigned*)((const char*)(gbase) + (voff)[_i]), (LAS unsigned*)(lds + (bufoff) + ldsw + _i * 8192), 16, 0, 0); } while (0)
; #define PG8_LDA(dst, b, h) do { _Pragma("unroll") for (int m = 0; m < 4; ++m) _Pragma("unroll") for (int k = 0; k < 2; ++k) dst[m][k] = *(const LAS bf16x8*)(lds + PG8_SA(b, h) + aoff + m * 2048 + k * 1024); } while (0)
; #define PG8_LDB(dst, b, h) do { _Pragma("unroll") for (int n = 0; n < 2; ++n) _Pragma("unroll") for (int k = 0; k < 2; ++k) dst[n][k] = *(const LAS bf16x8*)(lds + PG8_SB(b, h) + boff + n * 2048 + k * 1024); } while (0)
; #define PG8_MMA(ai, bj, At, Bt) do { __builtin_amdgcn_s_setprio(1); _Pragma("unroll") for (int m = 0; m < 4; ++m) _Pragma("unroll") for (int n = 0; n < 2; ++n) _Pragma("unroll") for (int k = 0; k < 2; ++k) \
;         acc[ai][bj][m][n] = __builtin_amdgcn_mfma_f32_16x16x32_bf16(Bt[n][k], At[m][k], acc[ai][bj][m][n], 0, 0, 0); __builtin_amdgcn_s_setprio(0); } while (0)
; #define PG8_WAIT_V(n) asm volatile("s_waitcnt vmcnt(" #n ")" ::: "memory")
; #define PG8_WAIT_L(n) asm volatile("s_waitcnt lgkmcnt(" #n ")" ::: "memory")
; #define PG8_BAR __builtin_amdgcn_s_barrier()
; #define PG8_SCHED __builtin_amdgcn_sched_barrier(0)
; template <class Epi, bool ALIGN_EPI>
; __device__ __forceinline__ void gemm_phase(LAS unsigned char* lds, const Gemm g, const StaticOrder& S, const Epi& E) {
;     ...
;             PG8_WAIT_V(8); PG8_WAIT_L(0); PG8_BAR; PG8_MMA(1, 0, At, B0); PG8_MMA(1, 1, At, B1); PG8_BAR; PG8_SCHED;
;             PG8_LDB(B0, 1, 0); PG8_LDB(B1, 1, 1); PG8_SCHED; PG8_LDA(At, 1, 0); PG8_STAGE(PG8_SA(0, 1), a2 + hsA, voffA);
;             PG8_WAIT_V(8); PG8_WAIT_L(0); PG8_BAR; PG8_MMA(0, 0, At, B0); PG8_MMA(0, 1, At, B1); PG8_BAR; PG8_SCHED;
;             PG8_LDA(At, 1, 1); PG8_STAGE(PG8_SB(1, 0), b3, voffB); PG8_STAGE(PG8_SB(1, 1), b3 + hsB, voffB); PG8_STAGE(PG8_SA(1, 0), a3, voffA);
;             PG8_WAIT_V(8); PG8_WAIT_L(0); PG8_BAR; PG8_MMA(1, 0, At, B0); PG8_MMA(1, 1, At, B1); PG8_BAR; PG8_SCHED;
	s_waitcnt lgkmcnt(0)
	v_mfma_f32_16x16x32_bf16 v[62:65], v[156:159], v[188:191], v[62:65]
	v_mfma_f32_16x16x32_bf16 v[58:61], v[164:167], v[188:191], v[58:61]
	v_mfma_f32_16x16x32_bf16 v[46:49], v[156:159], v[196:199], v[46:49]
	v_mfma_f32_16x16x32_bf16 v[42:45], v[164:167], v[196:199], v[42:45]
	v_mfma_f32_16x16x32_bf16 v[30:33], v[156:159], v[204:207], v[30:33]
	v_mfma_f32_16x16x32_bf16 v[26:29], v[164:167], v[204:207], v[26:29]
	v_mfma_f32_16x16x32_bf16 v[14:17], v[156:159], v[212:215], v[14:17]
	v_mfma_f32_16x16x32_bf16 v[10:13], v[164:167], v[212:215], v[10:13]
	v_mfma_f32_16x16x32_bf16 v[62:65], v[160:163], v[192:195], v[62:65]
	v_mfma_f32_16x16x32_bf16 v[58:61], v[168:171], v[192:195], v[58:61]
	v_mfma_f32_16x16x32_bf16 v[46:49], v[160:163], v[200:203], v[46:49]
	v_mfma_f32_16x16x32_bf16 v[42:45], v[168:171], v[200:203], v[42:45]
	v_mfma_f32_16x16x32_bf16 v[30:33], v[160:163], v[208:211], v[30:33]
	v_mfma_f32_16x16x32_bf16 v[26:29], v[168:171], v[208:211], v[26:29]
	v_mfma_f32_16x16x32_bf16 v[14:17], v[160:163], v[216:219], v[14:17]
	v_mfma_f32_16x16x32_bf16 v[10:13], v[168:171], v[216:219], v[10:13]
	v_mfma_f32_16x16x32_bf16 v[54:57], v[172:175], v[188:191], v[54:57]
	v_mfma_f32_16x16x32_bf16 v[50:53], v[180:183], v[188:191], v[50:53]
	v_mfma_f32_16x16x32_bf16 v[38:41], v[172:175], v[196:199], v[38:41]
	v_mfma_f32_16x16x32_bf16 v[34:37], v[180:183], v[196:199], v[34:37]
	v_mfma_f32_16x16x32_bf16 v[22:25], v[172:175], v[204:207], v[22:25]
	v_mfma_f32_16x16x32_bf16 v[18:21], v[180:183], v[204:207], v[18:21]
	v_mfma_f32_16x16x32_bf16 v[6:9], v[172:175], v[212:215], v[6:9]
	v_mfma_f32_16x16x32_bf16 v[2:5], v[180:183], v[212:215], v[2:5]
	v_mfma_f32_16x16x32_bf16 v[54:57], v[176:179], v[192:195], v[54:57]
	v_mfma_f32_16x16x32_bf16 v[50:53], v[184:187], v[192:195], v[50:53]
	v_mfma_f32_16x16x32_bf16 v[38:41], v[176:179], v[200:203], v[38:41]
	v_mfma_f32_16x16x32_bf16 v[34:37], v[184:187], v[200:203], v[34:37]
	v_mfma_f32_16x16x32_bf16 v[22:25], v[176:179], v[208:211], v[22:25]
	v_mfma_f32_16x16x32_bf16 v[18:21], v[184:187], v[208:211], v[18:21]
	v_mfma_f32_16x16x32_bf16 v[6:9], v[176:179], v[216:219], v[6:9]
	v_mfma_f32_16x16x32_bf16 v[2:5], v[184:187], v[216:219], v[2:5]
	s_barrier
	s_add_i32 s49, 0, 0x18000
	v_add_u32_e32 v138, s49, v150
	s_add_i32 s50, 0, 0x1c000
	ds_read_b128 v[156:159], v138
	ds_read_b128 v[160:163], v138 offset:1024
	ds_read_b128 v[164:167], v138 offset:2048
	ds_read_b128 v[168:171], v138 offset:3072
	v_add_u32_e32 v138, s50, v150
	ds_read_b128 v[172:175], v138
	ds_read_b128 v[176:179], v138 offset:1024
	ds_read_b128 v[180:183], v138 offset:2048
	ds_read_b128 v[184:187], v138 offset:3072
	s_add_u32 s24, s24, 0x40000
	s_addc_u32 s25, s25, 0
	s_mov_b32 m0, s30
	v_lshl_add_u64 v[228:229], s[24:25], 0, v[136:137]
	ds_read_b128 v[188:191], v153 offset:32768
	ds_read_b128 v[192:195], v153 offset:33792
	ds_read_b128 v[196:199], v153 offset:34816
	ds_read_b128 v[200:203], v153 offset:35840
	ds_read_b128 v[204:207], v153 offset:36864
	ds_read_b128 v[208:211], v153 offset:37888
	ds_read_b128 v[212:215], v153 offset:38912
	ds_read_b128 v[216:219], v153 offset:39936
	global_load_lds_dwordx4 v[228:229], off
	v_lshl_add_u64 v[228:229], s[24:25], 0, v[132:133]
	s_mov_b32 m0, s31
	s_nop 0
	global_load_lds_dwordx4 v[228:229], off
	s_waitcnt vmcnt(8)
	s_waitcnt lgkmcnt(0)
	s_barrier
	s_waitcnt lgkmcnt(0)
	v_mfma_f32_16x16x32_bf16 v[118:121], v[156:159], v[188:191], v[118:121]
	v_mfma_f32_16x16x32_bf16 v[114:117], v[164:167], v[188:191], v[114:117]
	v_mfma_f32_16x16x32_bf16 v[106:109], v[156:159], v[196:199], v[106:109]
	v_mfma_f32_16x16x32_bf16 v[102:105], v[164:167], v[196:199], v[102:105]
	v_mfma_f32_16x16x32_bf16 v[94:97], v[156:159], v[204:207], v[94:97]
	v_mfma_f32_16x16x32_bf16 v[90:93], v[164:167], v[204:207], v[90:93]
	v_mfma_f32_16x16x32_bf16 v[78:81], v[156:159], v[212:215], v[78:81]
	v_mfma_f32_16x16x32_bf16 v[74:77], v[164:167], v[212:215], v[74:77]
	v_mfma_f32_16x16x32_bf16 v[118:121], v[160:163], v[192:195], v[118:121]
	v_mfma_f32_16x16x32_bf16 v[114:117], v[168:171], v[192:195], v[114:117]
	v_mfma_f32_16x16x32_bf16 v[106:109], v[160:163], v[200:203], v[106:109]
	v_mfma_f32_16x16x32_bf16 v[102:105], v[168:171], v[200:203], v[102:105]
	v_mfma_f32_16x16x32_bf16 v[94:97], v[160:163], v[208:211], v[94:97]
	v_mfma_f32_16x16x32_bf16 v[90:93], v[168:171], v[208:211], v[90:93]
	v_mfma_f32_16x16x32_bf16 v[78:81], v[160:163], v[216:219], v[78:81]
	v_mfma_f32_16x16x32_bf16 v[74:77], v[168:171], v[216:219], v[74:77]
	v_mfma_f32_16x16x32_bf16 v[126:129], v[172:175], v[188:191], v[126:129]
	v_mfma_f32_16x16x32_bf16 v[122:125], v[180:183], v[188:191], v[122:125]
	v_mfma_f32_16x16x32_bf16 v[110:113], v[172:175], v[196:199], v[110:113]
	v_mfma_f32_16x16x32_bf16 v[98:101], v[180:183], v[196:199], v[98:101]
	v_mfma_f32_16x16x32_bf16 v[86:89], v[172:175], v[204:207], v[86:89]
	v_mfma_f32_16x16x32_bf16 v[82:85], v[180:183], v[204:207], v[82:85]
	v_mfma_f32_16x16x32_bf16 v[70:73], v[172:175], v[212:215], v[70:73]
	v_mfma_f32_16x16x32_bf16 v[66:69], v[180:183], v[212:215], v[66:69]
	v_mfma_f32_16x16x32_bf16 v[126:129], v[176:179], v[192:195], v[126:129]
	v_mfma_f32_16x16x32_bf16 v[122:125], v[184:187], v[192:195], v[122:125]
	v_mfma_f32_16x16x32_bf16 v[110:113], v[176:179], v[200:203], v[110:113]
	v_mfma_f32_16x16x32_bf16 v[98:101], v[184:187], v[200:203], v[98:101]
	v_mfma_f32_16x16x32_bf16 v[86:89], v[176:179], v[208:211], v[86:89]
	v_mfma_f32_16x16x32_bf16 v[82:85], v[184:187], v[208:211], v[82:85]
	v_mfma_f32_16x16x32_bf16 v[70:73], v[176:179], v[216:219], v[70:73]
	v_mfma_f32_16x16x32_bf16 v[66:69], v[184:187], v[216:219], v[66:69]
	s_barrier
; #define PG8_STAGE(bufoff, gbase, voff) do { _Pragma("unroll") for (int _i = 0; _i < 2; ++_i) \
;         __builtin_amdgcn_global_load_lds((const unsigned*)((const char*)(gbase) + (voff)[_i]), (LAS unsigned*)(lds + (bufoff) + ldsw + _i * 8192), 16, 0, 0); } while (0)
; #define PG8_LDA(dst, b, h) do { _Pragma("unroll") for (int m = 0; m < 4; ++m) _Pragma("unroll") for (int k = 0; k < 2; ++k) dst[m][k] = *(const LAS bf16x8*)(lds + PG8_SA(b, h) + aoff + m * 2048 + k * 1024); } while (0)
; #define PG8_MMA(ai, bj, At, Bt) do { __builtin_amdgcn_s_setprio(1); _Pragma("unroll") for (int m = 0; m < 4; ++m) _Pragma("unroll") for (int n = 0; n < 2; ++n) _Pragma("unroll") for (int k = 0; k < 2; ++k) \
;         acc[ai][bj][m][n] = __builtin_amdgcn_mfma_f32_16x16x32_bf16(Bt[n][k], At[m][k], acc[ai][bj][m][n], 0, 0, 0); __builtin_amdgcn_s_setprio(0); } while (0)
; #define PG8_WAIT_V(n) asm volatile("s_waitcnt vmcnt(" #n ")" ::: "memory")
; #define PG8_WAIT_L(n) asm volatile("s_waitcnt lgkmcnt(" #n ")" ::: "memory")
; #define PG8_BAR __builtin_amdgcn_s_barrier()
; #define PG8_SCHED __builtin_amdgcn_sched_barrier(0)
; template <class Epi, bool ALIGN_EPI>
; __device__ __forceinline__ void gemm_phase(LAS unsigned char* lds, const Gemm g, const StaticOrder& S, const Epi& E) {
;     ...
;             PG8_LDA(At, 1, 1); PG8_STAGE(PG8_SB(1, 0), b3, voffB); PG8_STAGE(PG8_SB(1, 1), b3 + hsB, voffB); PG8_STAGE(PG8_SA(1, 0), a3, voffA);
;             PG8_WAIT_V(8); PG8_WAIT_L(0); PG8_BAR; PG8_MMA(1, 0, At, B0); PG8_MMA(1, 1, At, B1); PG8_BAR; PG8_SCHED;
;         }
	s_add_i32 s24, s49, s26
	v_lshl_add_u64 v[220:221], v[220:221], 0, s[6:7]
	s_mov_b32 m0, s24
	ds_read_b128 v[188:191], v153 offset:49152
	ds_read_b128 v[192:195], v153 offset:50176
	ds_read_b128 v[196:199], v153 offset:51200
	ds_read_b128 v[200:203], v153 offset:52224
	ds_read_b128 v[204:207], v153 offset:53248
	ds_read_b128 v[208:211], v153 offset:54272
	ds_read_b128 v[212:215], v153 offset:55296
	ds_read_b128 v[216:219], v153 offset:56320
	global_load_lds_dwordx4 v[220:221], off
	s_add_i32 m0, s24, 0x2000
	s_add_u32 s22, s22, 0x40080
	v_lshl_add_u64 v[220:221], v[222:223], 0, s[6:7]
	s_addc_u32 s23, s23, 0
	s_add_i32 s24, s50, s26
	global_load_lds_dwordx4 v[220:221], off
	v_lshl_add_u64 v[220:221], s[22:23], 0, v[134:135]
	s_mov_b32 m0, s24
	s_nop 0
	global_load_lds_dwordx4 v[220:221], off
	v_lshl_add_u64 v[220:221], s[22:23], 0, v[130:131]
	s_add_i32 m0, s24, 0x2000
	s_nop 0
	global_load_lds_dwordx4 v[220:221], off
	v_lshl_add_u64 v[220:221], v[224:225], 0, s[6:7]
	s_mov_b32 m0, s36
	s_nop 0
	global_load_lds_dwordx4 v[220:221], off
	v_lshl_add_u64 v[220:221], v[226:227], 0, s[6:7]
	s_mov_b32 m0, s37
	s_nop 0
	global_load_lds_dwordx4 v[220:221], off
	s_waitcnt vmcnt(8)
	s_waitcnt lgkmcnt(0)
	s_barrier
	s_waitcnt lgkmcnt(0)
	v_mfma_f32_16x16x32_bf16 v[62:65], v[156:159], v[188:191], v[62:65]
	v_mfma_f32_16x16x32_bf16 v[58:61], v[164:167], v[188:191], v[58:61]
	v_mfma_f32_16x16x32_bf16 v[46:49], v[156:159], v[196:199], v[46:49]
	v_mfma_f32_16x16x32_bf16 v[42:45], v[164:167], v[196:199], v[42:45]
	v_mfma_f32_16x16x32_bf16 v[30:33], v[156:159], v[204:207], v[30:33]
	v_mfma_f32_16x16x32_bf16 v[26:29], v[164:167], v[204:207], v[26:29]
	v_mfma_f32_16x16x32_bf16 v[14:17], v[156:159], v[212:215], v[14:17]
	v_mfma_f32_16x16x32_bf16 v[10:13], v[164:167], v[212:215], v[10:13]
	v_mfma_f32_16x16x32_bf16 v[62:65], v[160:163], v[192:195], v[62:65]
	v_mfma_f32_16x16x32_bf16 v[58:61], v[168:171], v[192:195], v[58:61]
	v_mfma_f32_16x16x32_bf16 v[46:49], v[160:163], v[200:203], v[46:49]
	v_mfma_f32_16x16x32_bf16 v[42:45], v[168:171], v[200:203], v[42:45]
	v_mfma_f32_16x16x32_bf16 v[30:33], v[160:163], v[208:211], v[30:33]
	v_mfma_f32_16x16x32_bf16 v[26:29], v[168:171], v[208:211], v[26:29]
	v_mfma_f32_16x16x32_bf16 v[14:17], v[160:163], v[216:219], v[14:17]
	v_mfma_f32_16x16x32_bf16 v[10:13], v[168:171], v[216:219], v[10:13]
	v_mfma_f32_16x16x32_bf16 v[54:57], v[172:175], v[188:191], v[54:57]
	v_mfma_f32_16x16x32_bf16 v[50:53], v[180:183], v[188:191], v[50:53]
	v_mfma_f32_16x16x32_bf16 v[38:41], v[172:175], v[196:199], v[38:41]
	v_mfma_f32_16x16x32_bf16 v[34:37], v[180:183], v[196:199], v[34:37]
	v_mfma_f32_16x16x32_bf16 v[22:25], v[172:175], v[204:207], v[22:25]
	v_mfma_f32_16x16x32_bf16 v[18:21], v[180:183], v[204:207], v[18:21]
	v_mfma_f32_16x16x32_bf16 v[6:9], v[172:175], v[212:215], v[6:9]
	v_mfma_f32_16x16x32_bf16 v[2:5], v[180:183], v[212:215], v[2:5]
	v_mfma_f32_16x16x32_bf16 v[54:57], v[176:179], v[192:195], v[54:57]
	v_mfma_f32_16x16x32_bf16 v[50:53], v[184:187], v[192:195], v[50:53]
	v_mfma_f32_16x16x32_bf16 v[38:41], v[176:179], v[200:203], v[38:41]
	v_mfma_f32_16x16x32_bf16 v[34:37], v[184:187], v[200:203], v[34:37]
	v_mfma_f32_16x16x32_bf16 v[22:25], v[176:179], v[208:211], v[22:25]
	v_mfma_f32_16x16x32_bf16 v[18:21], v[184:187], v[208:211], v[18:21]
	v_mfma_f32_16x16x32_bf16 v[6:9], v[176:179], v[216:219], v[6:9]
	v_mfma_f32_16x16x32_bf16 v[2:5], v[184:187], v[216:219], v[2:5]
	s_barrier
	s_add_i32 s48, s48, 2
	s_add_u32 s20, s20, 0x100
	s_addc_u32 s21, s21, 0
	s_add_u32 s46, s46, 0x100
	s_addc_u32 s47, s47, 0
	s_cmp_gt_u32 s48, 13
	s_cbranch_scc0 .LBB0_1299
	s_and_b64 vcc, exec, s[8:9]
	s_cbranch_vccz .LBB0_1302
	s_barrier

; #define PG8_STAGE(bufoff, gbase, voff) do { _Pragma("unroll") for (int _i = 0; _i < 2; ++_i) \
;         __builtin_amdgcn_global_load_lds((const unsigned*)((const char*)(gbase) + (voff)[_i]), (LAS unsigned*)(lds + (bufoff) + ldsw + _i * 8192), 16, 0, 0); } while (0)
; #define PG8_LDA(dst, b, h) do { _Pragma("unroll") for (int m = 0; m < 4; ++m) _Pragma("unroll") for (int k = 0; k < 2; ++k) dst[m][k] = *(const LAS bf16x8*)(lds + PG8_SA(b, h) + aoff + m * 2048 + k * 1024); } while (0)
; #define PG8_LDB(dst, b, h) do { _Pragma("unroll") for (int n = 0; n < 2; ++n) _Pragma("unroll") for (int k = 0; k < 2; ++k) dst[n][k] = *(const LAS bf16x8*)(lds + PG8_SB(b, h) + boff + n * 2048 + k * 1024); } while (0)
; #define PG8_MMA(ai, bj, At, Bt) do { __builtin_amdgcn_s_setprio(1); _Pragma("unroll") for (int m = 0; m < 4; ++m) _Pragma("unroll") for (int n = 0; n < 2; ++n) _Pragma("unroll") for (int k = 0; k < 2; ++k) \
;         acc[ai][bj][m][n] = __builtin_amdgcn_mfma_f32_16x16x32_bf16(Bt[n][k], At[m][k], acc[ai][bj][m][n], 0, 0, 0); __builtin_amdgcn_s_setprio(0); } while (0)
; #define PG8_WAIT_V(n) asm volatile("s_waitcnt vmcnt(" #n ")" ::: "memory")
; #define PG8_WAIT_L(n) asm volatile("s_waitcnt lgkmcnt(" #n ")" ::: "memory")
; #define PG8_BAR __builtin_amdgcn_s_barrier()
; #define PG8_SCHED __builtin_amdgcn_sched_barrier(0)
; template <class Epi, bool ALIGN_EPI>
; __device__ __forceinline__ void gemm_phase(LAS unsigned char* lds, const Gemm g, const StaticOrder& S, const Epi& E) {
;     ...
;         for (int t = 0; t < nt; t += 2) {
;             const bool last = (t == nt - 2);
;             const char* a1 = cA + (size_t)(t + 1) * kstepA;
;             const char* a2 = last ? nA : cA + (size_t)(t + 2) * kstepA; const char* b2 = last ? nB : cB + (size_t)(t + 2) * kstep;
;             const char* a3 = a2 + kstepA; const char* b3 = b2 + kstep;
;             PG8_LDB(B0, 0, 0); PG8_LDB(B1, 0, 1); PG8_SCHED; PG8_LDA(At, 0, 0); PG8_STAGE(PG8_SA(1, 1), a1 + hsA, voffA);
;             PG8_WAIT_V(8); PG8_WAIT_L(0); PG8_BAR; PG8_MMA(0, 0, At, B0); PG8_MMA(0, 1, At, B1); PG8_BAR; PG8_SCHED;
;             PG8_LDA(At, 0, 1); PG8_STAGE(PG8_SB(0, 0), b2, voffB); PG8_STAGE(PG8_SB(0, 1), b2 + hsB, voffB); PG8_STAGE(PG8_SA(0, 0), a2, voffA);
;             PG8_WAIT_V(8); PG8_WAIT_L(0); PG8_BAR; PG8_MMA(1, 0, At, B0); PG8_MMA(1, 1, At, B1); PG8_BAR; PG8_SCHED;
.LBB0_1405:
	ds_read_b128 v[130:133], v190
	ds_read_b128 v[134:137], v190 offset:1024
	ds_read_b128 v[138:141], v190 offset:2048
	ds_read_b128 v[142:145], v190 offset:3072
	ds_read_b128 v[146:149], v191
	ds_read_b128 v[150:153], v191 offset:1024
	ds_read_b128 v[170:173], v191 offset:2048
	ds_read_b128 v[174:177], v191 offset:3072
	s_add_u32 s18, s16, 0x4000
	s_addc_u32 s19, s17, 0
	s_cmp_eq_u32 s44, 40
	s_cselect_b32 s22, s6, s18
	s_cselect_b32 s23, s7, s19
	s_cselect_b32 s20, s14, s42
	s_cselect_b32 s21, s15, s43
	s_add_u32 s18, s22, 0x8000
	s_addc_u32 s19, s23, 0
	v_lshl_add_u64 v[186:187], s[16:17], 0, v[162:163]
	s_add_i32 m0, s25, 0xc000
	ds_read_b128 v[178:181], v192
	ds_read_b128 v[182:185], v192 offset:1024
	ds_read_b128 v[194:197], v192 offset:2048
	ds_read_b128 v[198:201], v192 offset:3072
	ds_read_b128 v[202:205], v192 offset:4096
	ds_read_b128 v[206:209], v192 offset:5120
	ds_read_b128 v[210:213], v192 offset:6144
	ds_read_b128 v[214:217], v192 offset:7168
	global_load_lds_dwordx4 v[186:187], off
	v_lshl_add_u64 v[186:187], s[16:17], 0, v[164:165]
	s_add_i32 m0, s25, 0xe000
	s_nop 0
	global_load_lds_dwordx4 v[186:187], off
	s_waitcnt vmcnt(8)
	s_waitcnt lgkmcnt(0)
	s_barrier
	s_waitcnt lgkmcnt(0)
	v_mfma_f32_16x16x32_bf16 v[126:129], v[130:133], v[178:181], v[126:129]
	v_mfma_f32_16x16x32_bf16 v[122:125], v[138:141], v[178:181], v[122:125]
	v_mfma_f32_16x16x32_bf16 v[110:113], v[130:133], v[194:197], v[110:113]
	v_mfma_f32_16x16x32_bf16 v[106:109], v[138:141], v[194:197], v[106:109]
	v_mfma_f32_16x16x32_bf16 v[94:97], v[130:133], v[202:205], v[94:97]
	v_mfma_f32_16x16x32_bf16 v[90:93], v[138:141], v[202:205], v[90:93]
	v_mfma_f32_16x16x32_bf16 v[78:81], v[130:133], v[210:213], v[78:81]
	v_mfma_f32_16x16x32_bf16 v[74:77], v[138:141], v[210:213], v[74:77]
	v_mfma_f32_16x16x32_bf16 v[126:129], v[134:137], v[182:185], v[126:129]
	v_mfma_f32_16x16x32_bf16 v[122:125], v[142:145], v[182:185], v[122:125]
	v_mfma_f32_16x16x32_bf16 v[110:113], v[134:137], v[198:201], v[110:113]
	v_mfma_f32_16x16x32_bf16 v[106:109], v[142:145], v[198:201], v[106:109]
	v_mfma_f32_16x16x32_bf16 v[94:97], v[134:137], v[206:209], v[94:97]
	v_mfma_f32_16x16x32_bf16 v[90:93], v[142:145], v[206:209], v[90:93]
	v_mfma_f32_16x16x32_bf16 v[78:81], v[134:137], v[214:217], v[78:81]
	v_mfma_f32_16x16x32_bf16 v[74:77], v[142:145], v[214:217], v[74:77]
	v_mfma_f32_16x16x32_bf16 v[118:121], v[146:149], v[178:181], v[118:121]
	v_mfma_f32_16x16x32_bf16 v[114:117], v[170:173], v[178:181], v[114:117]
	v_mfma_f32_16x16x32_bf16 v[102:105], v[146:149], v[194:197], v[102:105]
	v_mfma_f32_16x16x32_bf16 v[98:101], v[170:173], v[194:197], v[98:101]
	v_mfma_f32_16x16x32_bf16 v[86:89], v[146:149], v[202:205], v[86:89]
	v_mfma_f32_16x16x32_bf16 v[82:85], v[170:173], v[202:205], v[82:85]
	v_mfma_f32_16x16x32_bf16 v[70:73], v[146:149], v[210:213], v[70:73]
	v_mfma_f32_16x16x32_bf16 v[66:69], v[170:173], v[210:213], v[66:69]
	v_mfma_f32_16x16x32_bf16 v[118:121], v[150:153], v[182:185], v[118:121]
	v_mfma_f32_16x16x32_bf16 v[114:117], v[174:177], v[182:185], v[114:117]
	v_mfma_f32_16x16x32_bf16 v[102:105], v[150:153], v[198:201], v[102:105]
	v_mfma_f32_16x16x32_bf16 v[98:101], v[174:177], v[198:201], v[98:101]
	v_mfma_f32_16x16x32_bf16 v[86:89], v[150:153], v[206:209], v[86:89]
	v_mfma_f32_16x16x32_bf16 v[82:85], v[174:177], v[206:209], v[82:85]
	v_mfma_f32_16x16x32_bf16 v[70:73], v[150:153], v[214:217], v[70:73]
	v_mfma_f32_16x16x32_bf16 v[66:69], v[174:177], v[214:217], v[66:69]
	s_barrier
	s_add_i32 s45, s36, s24
	v_lshl_add_u64 v[186:187], s[20:21], 0, v[156:157]
	s_mov_b32 m0, s45
	ds_read_b128 v[178:181], v192 offset:16384
	ds_read_b128 v[182:185], v192 offset:17408
	ds_read_b128 v[194:197], v192 offset:18432
	ds_read_b128 v[198:201], v192 offset:19456
	ds_read_b128 v[202:205], v192 offset:20480
	ds_read_b128 v[206:209], v192 offset:21504
	ds_read_b128 v[210:213], v192 offset:22528
	ds_read_b128 v[214:217], v192 offset:23552
	global_load_lds_dwordx4 v[186:187], off
	s_add_i32 m0, s45, 0x2000
	s_add_u32 s46, s20, 0xb0000
	v_lshl_add_u64 v[218:219], s[20:21], 0, v[160:161]
	s_addc_u32 s47, s21, 0
	s_add_i32 s45, s37, s24
	global_load_lds_dwordx4 v[218:219], off
	v_lshl_add_u64 v[220:221], s[46:47], 0, v[156:157]
	s_mov_b32 m0, s45
	s_nop 0
	global_load_lds_dwordx4 v[220:221], off
	v_lshl_add_u64 v[220:221], s[46:47], 0, v[160:161]
	s_add_i32 m0, s45, 0x2000
	s_nop 0
	global_load_lds_dwordx4 v[220:221], off
	v_lshl_add_u64 v[220:221], s[22:23], 0, v[154:155]
	s_mov_b32 m0, s25
	s_nop 0
	global_load_lds_dwordx4 v[220:221], off
	v_lshl_add_u64 v[220:221], s[22:23], 0, v[158:159]
	s_mov_b32 m0, s26
	s_nop 0
	global_load_lds_dwordx4 v[220:221], off
	s_waitcnt vmcnt(8)
	s_waitcnt lgkmcnt(0)
	s_barrier
; #define PG8_STAGE(bufoff, gbase, voff) do { _Pragma("unroll") for (int _i = 0; _i < 2; ++_i) \
;         __builtin_amdgcn_global_load_lds((const unsigned*)((const char*)(gbase) + (voff)[_i]), (LAS unsigned*)(lds + (bufoff) + ldsw + _i * 8192), 16, 0, 0); } while (0)
; #define PG8_LDA(dst, b, h) do { _Pragma("unroll") for (int m = 0; m < 4; ++m) _Pragma("unroll") for (int k = 0; k < 2; ++k) dst[m][k] = *(const LAS bf16x8*)(lds + PG8_SA(b, h) + aoff + m * 2048 + k * 1024); } while (0)
; #define PG8_LDB(dst, b, h) do { _Pragma("unroll") for (int n = 0; n < 2; ++n) _Pragma("unroll") for (int k = 0; k < 2; ++k) dst[n][k] = *(const LAS bf16x8*)(lds + PG8_SB(b, h) + boff + n * 2048 + k * 1024); } while (0)
; #define PG8_MMA(ai, bj, At, Bt) do { __builtin_amdgcn_s_setprio(1); _Pragma("unroll") for (int m = 0; m < 4; ++m) _Pragma("unroll") for (int n = 0; n < 2; ++n) _Pragma("unroll") for (int k = 0; k < 2; ++k) \
;         acc[ai][bj][m][n] = __builtin_amdgcn_mfma_f32_16x16x32_bf16(Bt[n][k], At[m][k], acc[ai][bj][m][n], 0, 0, 0); __builtin_amdgcn_s_setprio(0); } while (0)
; #define PG8_WAIT_V(n) asm volatile("s_waitcnt vmcnt(" #n ")" ::: "memory")
; #define PG8_WAIT_L(n) asm volatile("s_waitcnt lgkmcnt(" #n ")" ::: "memory")
; #define PG8_BAR __builtin_amdgcn_s_barrier()
; #define PG8_SCHED __builtin_amdgcn_sched_barrier(0)
; template <class Epi, bool ALIGN_EPI>
; __device__ __forceinline__ void gemm_phase(LAS unsigned char* lds, const Gemm g, const StaticOrder& S, const Epi& E) {
;     ...
;             PG8_WAIT_V(8); PG8_WAIT_L(0); PG8_BAR; PG8_MMA(1, 0, At, B0); PG8_MMA(1, 1, At, B1); PG8_BAR; PG8_SCHED;
;             PG8_LDB(B0, 1, 0); PG8_LDB(B1, 1, 1); PG8_SCHED; PG8_LDA(At, 1, 0); PG8_STAGE(PG8_SA(0, 1), a2 + hsA, voffA);
;             PG8_WAIT_V(8); PG8_WAIT_L(0); PG8_BAR; PG8_MMA(0, 0, At, B0); PG8_MMA(0, 1, At, B1); PG8_BAR; PG8_SCHED;
;             PG8_LDA(At, 1, 1); PG8_STAGE(PG8_SB(1, 0), b3, voffB); PG8_STAGE(PG8_SB(1, 1), b3 + hsB, voffB); PG8_STAGE(PG8_SA(1, 0), a3, voffA);
;             PG8_WAIT_V(8); PG8_WAIT_L(0); PG8_BAR; PG8_MMA(1, 0, At, B0); PG8_MMA(1, 1, At, B1); PG8_BAR; PG8_SCHED;
	s_waitcnt lgkmcnt(0)
	v_mfma_f32_16x16x32_bf16 v[62:65], v[130:133], v[178:181], v[62:65]
	v_mfma_f32_16x16x32_bf16 v[58:61], v[138:141], v[178:181], v[58:61]
	v_mfma_f32_16x16x32_bf16 v[46:49], v[130:133], v[194:197], v[46:49]
	v_mfma_f32_16x16x32_bf16 v[42:45], v[138:141], v[194:197], v[42:45]
	v_mfma_f32_16x16x32_bf16 v[30:33], v[130:133], v[202:205], v[30:33]
	v_mfma_f32_16x16x32_bf16 v[26:29], v[138:141], v[202:205], v[26:29]
	v_mfma_f32_16x16x32_bf16 v[14:17], v[130:133], v[210:213], v[14:17]
	v_mfma_f32_16x16x32_bf16 v[10:13], v[138:141], v[210:213], v[10:13]
	v_mfma_f32_16x16x32_bf16 v[62:65], v[134:137], v[182:185], v[62:65]
	v_mfma_f32_16x16x32_bf16 v[58:61], v[142:145], v[182:185], v[58:61]
	v_mfma_f32_16x16x32_bf16 v[46:49], v[134:137], v[198:201], v[46:49]
	v_mfma_f32_16x16x32_bf16 v[42:45], v[142:145], v[198:201], v[42:45]
	v_mfma_f32_16x16x32_bf16 v[30:33], v[134:137], v[206:209], v[30:33]
	v_mfma_f32_16x16x32_bf16 v[26:29], v[142:145], v[206:209], v[26:29]
	v_mfma_f32_16x16x32_bf16 v[14:17], v[134:137], v[214:217], v[14:17]
	v_mfma_f32_16x16x32_bf16 v[10:13], v[142:145], v[214:217], v[10:13]
	v_mfma_f32_16x16x32_bf16 v[54:57], v[146:149], v[178:181], v[54:57]
	v_mfma_f32_16x16x32_bf16 v[50:53], v[170:173], v[178:181], v[50:53]
	v_mfma_f32_16x16x32_bf16 v[38:41], v[146:149], v[194:197], v[38:41]
	v_mfma_f32_16x16x32_bf16 v[34:37], v[170:173], v[194:197], v[34:37]
	v_mfma_f32_16x16x32_bf16 v[22:25], v[146:149], v[202:205], v[22:25]
	v_mfma_f32_16x16x32_bf16 v[18:21], v[170:173], v[202:205], v[18:21]
	v_mfma_f32_16x16x32_bf16 v[6:9], v[146:149], v[210:213], v[6:9]
	v_mfma_f32_16x16x32_bf16 v[2:5], v[170:173], v[210:213], v[2:5]
	v_mfma_f32_16x16x32_bf16 v[54:57], v[150:153], v[182:185], v[54:57]
	v_mfma_f32_16x16x32_bf16 v[50:53], v[174:177], v[182:185], v[50:53]
	v_mfma_f32_16x16x32_bf16 v[38:41], v[150:153], v[198:201], v[38:41]
	v_mfma_f32_16x16x32_bf16 v[34:37], v[174:177], v[198:201], v[34:37]
	v_mfma_f32_16x16x32_bf16 v[22:25], v[150:153], v[206:209], v[22:25]
	v_mfma_f32_16x16x32_bf16 v[18:21], v[174:177], v[206:209], v[18:21]
	v_mfma_f32_16x16x32_bf16 v[6:9], v[150:153], v[214:217], v[6:9]
	v_mfma_f32_16x16x32_bf16 v[2:5], v[174:177], v[214:217], v[2:5]
	s_barrier
	s_add_i32 s45, 0, 0x18000
	s_add_i32 s46, 0, 0x1c000
	v_add_u32_e32 v142, s45, v188
	v_add_u32_e32 v174, s46, v188
	ds_read_b128 v[130:133], v142
	ds_read_b128 v[134:137], v142 offset:1024
	ds_read_b128 v[138:141], v142 offset:2048
	ds_read_b128 v[142:145], v142 offset:3072
	ds_read_b128 v[146:149], v174
	ds_read_b128 v[150:153], v174 offset:1024
	ds_read_b128 v[170:173], v174 offset:2048
	ds_read_b128 v[174:177], v174 offset:3072
	s_add_u32 s22, s22, 0x4000
	s_addc_u32 s23, s23, 0
	s_mov_b32 m0, s27
	v_lshl_add_u64 v[220:221], s[22:23], 0, v[154:155]
	ds_read_b128 v[178:181], v192 offset:32768
	ds_read_b128 v[182:185], v192 offset:33792
	ds_read_b128 v[194:197], v192 offset:34816
	ds_read_b128 v[198:201], v192 offset:35840
	ds_read_b128 v[202:205], v192 offset:36864
	ds_read_b128 v[206:209], v192 offset:37888
	ds_read_b128 v[210:213], v192 offset:38912
	ds_read_b128 v[214:217], v192 offset:39936
	global_load_lds_dwordx4 v[220:221], off
	v_lshl_add_u64 v[220:221], s[22:23], 0, v[158:159]
	s_mov_b32 m0, s28
	s_nop 0
	global_load_lds_dwordx4 v[220:221], off
	s_waitcnt vmcnt(8)
	s_waitcnt lgkmcnt(0)
	s_barrier
	s_waitcnt lgkmcnt(0)
	v_mfma_f32_16x16x32_bf16 v[126:129], v[130:133], v[178:181], v[126:129]
	v_mfma_f32_16x16x32_bf16 v[122:125], v[138:141], v[178:181], v[122:125]
	v_mfma_f32_16x16x32_bf16 v[110:113], v[130:133], v[194:197], v[110:113]
	v_mfma_f32_16x16x32_bf16 v[106:109], v[138:141], v[194:197], v[106:109]
	v_mfma_f32_16x16x32_bf16 v[94:97], v[130:133], v[202:205], v[94:97]
	v_mfma_f32_16x16x32_bf16 v[90:93], v[138:141], v[202:205], v[90:93]
	v_mfma_f32_16x16x32_bf16 v[78:81], v[130:133], v[210:213], v[78:81]
	v_mfma_f32_16x16x32_bf16 v[74:77], v[138:141], v[210:213], v[74:77]
	v_mfma_f32_16x16x32_bf16 v[126:129], v[134:137], v[182:185], v[126:129]
	v_mfma_f32_16x16x32_bf16 v[122:125], v[142:145], v[182:185], v[122:125]
	v_mfma_f32_16x16x32_bf16 v[110:113], v[134:137], v[198:201], v[110:113]
	v_mfma_f32_16x16x32_bf16 v[106:109], v[142:145], v[198:201], v[106:109]
	v_mfma_f32_16x16x32_bf16 v[94:97], v[134:137], v[206:209], v[94:97]
	v_mfma_f32_16x16x32_bf16 v[90:93], v[142:145], v[206:209], v[90:93]
	v_mfma_f32_16x16x32_bf16 v[78:81], v[134:137], v[214:217], v[78:81]
	v_mfma_f32_16x16x32_bf16 v[74:77], v[142:145], v[214:217], v[74:77]
	v_mfma_f32_16x16x32_bf16 v[118:121], v[146:149], v[178:181], v[118:121]
	v_mfma_f32_16x16x32_bf16 v[114:117], v[170:173], v[178:181], v[114:117]
	v_mfma_f32_16x16x32_bf16 v[102:105], v[146:149], v[194:197], v[102:105]
	v_mfma_f32_16x16x32_bf16 v[98:101], v[170:173], v[194:197], v[98:101]
	v_mfma_f32_16x16x32_bf16 v[86:89], v[146:149], v[202:205], v[86:89]
	v_mfma_f32_16x16x32_bf16 v[82:85], v[170:173], v[202:205], v[82:85]
	v_mfma_f32_16x16x32_bf16 v[70:73], v[146:149], v[210:213], v[70:73]
	v_mfma_f32_16x16x32_bf16 v[66:69], v[170:173], v[210:213], v[66:69]
	v_mfma_f32_16x16x32_bf16 v[118:121], v[150:153], v[182:185], v[118:121]
	v_mfma_f32_16x16x32_bf16 v[114:117], v[174:177], v[182:185], v[114:117]
	v_mfma_f32_16x16x32_bf16 v[102:105], v[150:153], v[198:201], v[102:105]
	v_mfma_f32_16x16x32_bf16 v[98:101], v[174:177], v[198:201], v[98:101]
	v_mfma_f32_16x16x32_bf16 v[86:89], v[150:153], v[206:209], v[86:89]
	v_mfma_f32_16x16x32_bf16 v[82:85], v[174:177], v[206:209], v[82:85]
	v_mfma_f32_16x16x32_bf16 v[70:73], v[150:153], v[214:217], v[70:73]
	v_mfma_f32_16x16x32_bf16 v[66:69], v[174:177], v[214:217], v[66:69]
	s_barrier
; #define PG8_STAGE(bufoff, gbase, voff) do { _Pragma("unroll") for (int _i = 0; _i < 2; ++_i) \
;         __builtin_amdgcn_global_load_lds((const unsigned*)((const char*)(gbase) + (voff)[_i]), (LAS unsigned*)(lds + (bufoff) + ldsw + _i * 8192), 16, 0, 0); } while (0)
; #define PG8_LDA(dst, b, h) do { _Pragma("unroll") for (int m = 0; m < 4; ++m) _Pragma("unroll") for (int k = 0; k < 2; ++k) dst[m][k] = *(const LAS bf16x8*)(lds + PG8_SA(b, h) + aoff + m * 2048 + k * 1024); } while (0)
; #define PG8_MMA(ai, bj, At, Bt) do { __builtin_amdgcn_s_setprio(1); _Pragma("unroll") for (int m = 0; m < 4; ++m) _Pragma("unroll") for (int n = 0; n < 2; ++n) _Pragma("unroll") for (int k = 0; k < 2; ++k) \
;         acc[ai][bj][m][n] = __builtin_amdgcn_mfma_f32_16x16x32_bf16(Bt[n][k], At[m][k], acc[ai][bj][m][n], 0, 0, 0); __builtin_amdgcn_s_setprio(0); } while (0)
; #define PG8_WAIT_V(n) asm volatile("s_waitcnt vmcnt(" #n ")" ::: "memory")
; #define PG8_WAIT_L(n) asm volatile("s_waitcnt lgkmcnt(" #n ")" ::: "memory")
; #define PG8_BAR __builtin_amdgcn_s_barrier()
; #define PG8_SCHED __builtin_amdgcn_sched_barrier(0)
; template <class Epi, bool ALIGN_EPI>
; __device__ __forceinline__ void gemm_phase(LAS unsigned char* lds, const Gemm g, const StaticOrder& S, const Epi& E) {
;     ...
;             PG8_LDA(At, 1, 1); PG8_STAGE(PG8_SB(1, 0), b3, voffB); PG8_STAGE(PG8_SB(1, 1), b3 + hsB, voffB); PG8_STAGE(PG8_SA(1, 0), a3, voffA);
;             PG8_WAIT_V(8); PG8_WAIT_L(0); PG8_BAR; PG8_MMA(1, 0, At, B0); PG8_MMA(1, 1, At, B1); PG8_BAR; PG8_SCHED;
;         }
	s_add_i32 s22, s45, s24
	v_lshl_add_u64 v[186:187], v[186:187], 0, s[10:11]
	s_mov_b32 m0, s22
	ds_read_b128 v[178:181], v192 offset:49152
	ds_read_b128 v[182:185], v192 offset:50176
	ds_read_b128 v[194:197], v192 offset:51200
	ds_read_b128 v[198:201], v192 offset:52224
	ds_read_b128 v[202:205], v192 offset:53248
	ds_read_b128 v[206:209], v192 offset:54272
	ds_read_b128 v[210:213], v192 offset:55296
	ds_read_b128 v[214:217], v192 offset:56320
	global_load_lds_dwordx4 v[186:187], off
	s_add_i32 m0, s22, 0x2000
	s_add_u32 s20, s20, 0xb0080
	v_lshl_add_u64 v[186:187], v[218:219], 0, s[10:11]
	s_addc_u32 s21, s21, 0
	s_add_i32 s22, s46, s24
	global_load_lds_dwordx4 v[186:187], off
	v_lshl_add_u64 v[186:187], s[20:21], 0, v[156:157]
	s_mov_b32 m0, s22
	s_nop 0
	global_load_lds_dwordx4 v[186:187], off
	v_lshl_add_u64 v[186:187], s[20:21], 0, v[160:161]
	s_add_i32 m0, s22, 0x2000
	s_nop 0
	global_load_lds_dwordx4 v[186:187], off
	v_lshl_add_u64 v[186:187], s[18:19], 0, v[154:155]
	s_mov_b32 m0, s30
	s_nop 0
	global_load_lds_dwordx4 v[186:187], off
	v_lshl_add_u64 v[186:187], s[18:19], 0, v[158:159]
	s_mov_b32 m0, s31
	s_nop 0
	global_load_lds_dwordx4 v[186:187], off
	s_waitcnt vmcnt(8)
	s_waitcnt lgkmcnt(0)
	s_barrier
	s_waitcnt lgkmcnt(0)
	v_mfma_f32_16x16x32_bf16 v[62:65], v[130:133], v[178:181], v[62:65]
	v_mfma_f32_16x16x32_bf16 v[58:61], v[138:141], v[178:181], v[58:61]
	v_mfma_f32_16x16x32_bf16 v[46:49], v[130:133], v[194:197], v[46:49]
	v_mfma_f32_16x16x32_bf16 v[42:45], v[138:141], v[194:197], v[42:45]
	v_mfma_f32_16x16x32_bf16 v[30:33], v[130:133], v[202:205], v[30:33]
	v_mfma_f32_16x16x32_bf16 v[26:29], v[138:141], v[202:205], v[26:29]
	v_mfma_f32_16x16x32_bf16 v[14:17], v[130:133], v[210:213], v[14:17]
	v_mfma_f32_16x16x32_bf16 v[10:13], v[138:141], v[210:213], v[10:13]
	v_mfma_f32_16x16x32_bf16 v[62:65], v[134:137], v[182:185], v[62:65]
	v_mfma_f32_16x16x32_bf16 v[58:61], v[142:145], v[182:185], v[58:61]
	v_mfma_f32_16x16x32_bf16 v[46:49], v[134:137], v[198:201], v[46:49]
	v_mfma_f32_16x16x32_bf16 v[42:45], v[142:145], v[198:201], v[42:45]
	v_mfma_f32_16x16x32_bf16 v[30:33], v[134:137], v[206:209], v[30:33]
	v_mfma_f32_16x16x32_bf16 v[26:29], v[142:145], v[206:209], v[26:29]
	v_mfma_f32_16x16x32_bf16 v[14:17], v[134:137], v[214:217], v[14:17]
	v_mfma_f32_16x16x32_bf16 v[10:13], v[142:145], v[214:217], v[10:13]
	v_mfma_f32_16x16x32_bf16 v[54:57], v[146:149], v[178:181], v[54:57]
	v_mfma_f32_16x16x32_bf16 v[50:53], v[170:173], v[178:181], v[50:53]
	v_mfma_f32_16x16x32_bf16 v[38:41], v[146:149], v[194:197], v[38:41]
	v_mfma_f32_16x16x32_bf16 v[34:37], v[170:173], v[194:197], v[34:37]
	v_mfma_f32_16x16x32_bf16 v[22:25], v[146:149], v[202:205], v[22:25]
	v_mfma_f32_16x16x32_bf16 v[18:21], v[170:173], v[202:205], v[18:21]
	v_mfma_f32_16x16x32_bf16 v[6:9], v[146:149], v[210:213], v[6:9]
	v_mfma_f32_16x16x32_bf16 v[2:5], v[170:173], v[210:213], v[2:5]
	v_mfma_f32_16x16x32_bf16 v[54:57], v[150:153], v[182:185], v[54:57]
	v_mfma_f32_16x16x32_bf16 v[50:53], v[174:177], v[182:185], v[50:53]
	v_mfma_f32_16x16x32_bf16 v[38:41], v[150:153], v[198:201], v[38:41]
	v_mfma_f32_16x16x32_bf16 v[34:37], v[174:177], v[198:201], v[34:37]
	v_mfma_f32_16x16x32_bf16 v[22:25], v[150:153], v[206:209], v[22:25]
	v_mfma_f32_16x16x32_bf16 v[18:21], v[174:177], v[206:209], v[18:21]
	v_mfma_f32_16x16x32_bf16 v[6:9], v[150:153], v[214:217], v[6:9]
	v_mfma_f32_16x16x32_bf16 v[2:5], v[174:177], v[214:217], v[2:5]
	s_barrier
	s_add_i32 s44, s44, 2
	s_add_u32 s16, s16, 0x10000
	s_addc_u32 s17, s17, 0
	s_add_u32 s42, s42, 0x100
	s_addc_u32 s43, s43, 0
	s_cmp_gt_u32 s44, 41
	s_cbranch_scc0 .LBB0_1405
	s_and_b64 vcc, exec, s[12:13]
	s_cbranch_vccz .LBB0_1408
	s_barrier

; #define PG8_STAGE(bufoff, gbase, voff) do { _Pragma("unroll") for (int _i = 0; _i < 2; ++_i) \
;         __builtin_amdgcn_global_load_lds((const unsigned*)((const char*)(gbase) + (voff)[_i]), (LAS unsigned*)(lds + (bufoff) + ldsw + _i * 8192), 16, 0, 0); } while (0)
; #define PG8_LDA(dst, b, h) do { _Pragma("unroll") for (int m = 0; m < 4; ++m) _Pragma("unroll") for (int k = 0; k < 2; ++k) dst[m][k] = *(const LAS bf16x8*)(lds + PG8_SA(b, h) + aoff + m * 2048 + k * 1024); } while (0)
; #define PG8_LDB(dst, b, h) do { _Pragma("unroll") for (int n = 0; n < 2; ++n) _Pragma("unroll") for (int k = 0; k < 2; ++k) dst[n][k] = *(const LAS bf16x8*)(lds + PG8_SB(b, h) + boff + n * 2048 + k * 1024); } while (0)
; #define PG8_MMA(ai, bj, At, Bt) do { __builtin_amdgcn_s_setprio(1); _Pragma("unroll") for (int m = 0; m < 4; ++m) _Pragma("unroll") for (int n = 0; n < 2; ++n) _Pragma("unroll") for (int k = 0; k < 2; ++k) \
;         acc[ai][bj][m][n] = __builtin_amdgcn_mfma_f32_16x16x32_bf16(Bt[n][k], At[m][k], acc[ai][bj][m][n], 0, 0, 0); __builtin_amdgcn_s_setprio(0); } while (0)
; #define PG8_WAIT_V(n) asm volatile("s_waitcnt vmcnt(" #n ")" ::: "memory")
; #define PG8_WAIT_L(n) asm volatile("s_waitcnt lgkmcnt(" #n ")" ::: "memory")
; #define PG8_BAR __builtin_amdgcn_s_barrier()
; #define PG8_SCHED __builtin_amdgcn_sched_barrier(0)
; template <class Epi, bool ALIGN_EPI>
; __device__ __forceinline__ void gemm_phase(LAS unsigned char* lds, const Gemm g, const StaticOrder& S, const Epi& E) {
;     ...
;         for (int t = 0; t < nt; t += 2) {
;             const bool last = (t == nt - 2);
;             const char* a1 = cA + (size_t)(t + 1) * kstepA;
;             const char* a2 = last ? nA : cA + (size_t)(t + 2) * kstepA; const char* b2 = last ? nB : cB + (size_t)(t + 2) * kstep;
;             const char* a3 = a2 + kstepA; const char* b3 = b2 + kstep;
;             PG8_LDB(B0, 0, 0); PG8_LDB(B1, 0, 1); PG8_SCHED; PG8_LDA(At, 0, 0); PG8_STAGE(PG8_SA(1, 1), a1 + hsA, voffA);
;             PG8_WAIT_V(8); PG8_WAIT_L(0); PG8_BAR; PG8_MMA(0, 0, At, B0); PG8_MMA(0, 1, At, B1); PG8_BAR; PG8_SCHED;
;             PG8_LDA(At, 0, 1); PG8_STAGE(PG8_SB(0, 0), b2, voffB); PG8_STAGE(PG8_SB(0, 1), b2 + hsB, voffB); PG8_STAGE(PG8_SA(0, 0), a2, voffA);
;             PG8_WAIT_V(8); PG8_WAIT_L(0); PG8_BAR; PG8_MMA(1, 0, At, B0); PG8_MMA(1, 1, At, B1); PG8_BAR; PG8_SCHED;
.LBB0_1501:
	ds_read_b128 v[128:131], v203
	ds_read_b128 v[132:135], v203 offset:1024
	ds_read_b128 v[136:139], v203 offset:2048
	ds_read_b128 v[140:143], v203 offset:3072
	ds_read_b128 v[144:147], v204
	ds_read_b128 v[148:151], v204 offset:1024
	ds_read_b128 v[152:155], v204 offset:2048
	ds_read_b128 v[156:159], v204 offset:3072
	s_add_u32 s28, s24, 0xfffc0080
	s_addc_u32 s29, s25, -1
	s_cmp_eq_u32 s49, 12
	s_cselect_b32 s31, s19, s29
	s_cselect_b32 s30, s45, s28
	s_cselect_b32 s29, s21, s48
	s_cselect_b32 s28, s46, s47
	v_lshl_add_u64 v[216:217], s[24:25], 0, v[184:185]
	s_add_i32 m0, s9, 0xc000
	ds_read_b128 v[160:163], v205
	ds_read_b128 v[164:167], v205 offset:1024
	ds_read_b128 v[168:171], v205 offset:2048
	ds_read_b128 v[172:175], v205 offset:3072
	ds_read_b128 v[192:195], v205 offset:4096
	ds_read_b128 v[196:199], v205 offset:5120
	ds_read_b128 v[208:211], v205 offset:6144
	ds_read_b128 v[212:215], v205 offset:7168
	global_load_lds_dwordx4 v[216:217], off
	v_lshl_add_u64 v[216:217], s[24:25], 0, v[186:187]
	s_add_i32 m0, s9, 0xe000
	s_nop 0
	global_load_lds_dwordx4 v[216:217], off
	s_waitcnt vmcnt(8)
	s_waitcnt lgkmcnt(0)
	s_barrier
	s_waitcnt lgkmcnt(0)
	v_mfma_f32_16x16x32_bf16 v[124:127], v[128:131], v[160:163], v[124:127]
	v_mfma_f32_16x16x32_bf16 v[120:123], v[136:139], v[160:163], v[120:123]
	v_mfma_f32_16x16x32_bf16 v[108:111], v[128:131], v[168:171], v[108:111]
	v_mfma_f32_16x16x32_bf16 v[104:107], v[136:139], v[168:171], v[104:107]
	v_mfma_f32_16x16x32_bf16 v[92:95], v[128:131], v[192:195], v[92:95]
	v_mfma_f32_16x16x32_bf16 v[88:91], v[136:139], v[192:195], v[88:91]
	v_mfma_f32_16x16x32_bf16 v[76:79], v[128:131], v[208:211], v[76:79]
	v_mfma_f32_16x16x32_bf16 v[72:75], v[136:139], v[208:211], v[72:75]
	v_mfma_f32_16x16x32_bf16 v[124:127], v[132:135], v[164:167], v[124:127]
	v_mfma_f32_16x16x32_bf16 v[120:123], v[140:143], v[164:167], v[120:123]
	v_mfma_f32_16x16x32_bf16 v[108:111], v[132:135], v[172:175], v[108:111]
	v_mfma_f32_16x16x32_bf16 v[104:107], v[140:143], v[172:175], v[104:107]
	v_mfma_f32_16x16x32_bf16 v[92:95], v[132:135], v[196:199], v[92:95]
	v_mfma_f32_16x16x32_bf16 v[88:91], v[140:143], v[196:199], v[88:91]
	v_mfma_f32_16x16x32_bf16 v[76:79], v[132:135], v[212:215], v[76:79]
	v_mfma_f32_16x16x32_bf16 v[72:75], v[140:143], v[212:215], v[72:75]
	v_mfma_f32_16x16x32_bf16 v[116:119], v[144:147], v[160:163], v[116:119]
	v_mfma_f32_16x16x32_bf16 v[112:115], v[152:155], v[160:163], v[112:115]
	v_mfma_f32_16x16x32_bf16 v[100:103], v[144:147], v[168:171], v[100:103]
	v_mfma_f32_16x16x32_bf16 v[96:99], v[152:155], v[168:171], v[96:99]
	v_mfma_f32_16x16x32_bf16 v[84:87], v[144:147], v[192:195], v[84:87]
	v_mfma_f32_16x16x32_bf16 v[80:83], v[152:155], v[192:195], v[80:83]
	v_mfma_f32_16x16x32_bf16 v[68:71], v[144:147], v[208:211], v[68:71]
	v_mfma_f32_16x16x32_bf16 v[64:67], v[152:155], v[208:211], v[64:67]
	v_mfma_f32_16x16x32_bf16 v[116:119], v[148:151], v[164:167], v[116:119]
	v_mfma_f32_16x16x32_bf16 v[112:115], v[156:159], v[164:167], v[112:115]
	v_mfma_f32_16x16x32_bf16 v[100:103], v[148:151], v[172:175], v[100:103]
	v_mfma_f32_16x16x32_bf16 v[96:99], v[156:159], v[172:175], v[96:99]
	v_mfma_f32_16x16x32_bf16 v[84:87], v[148:151], v[196:199], v[84:87]
	v_mfma_f32_16x16x32_bf16 v[80:83], v[156:159], v[196:199], v[80:83]
	v_mfma_f32_16x16x32_bf16 v[68:71], v[148:151], v[212:215], v[68:71]
	v_mfma_f32_16x16x32_bf16 v[64:67], v[156:159], v[212:215], v[64:67]
	s_barrier
	s_add_i32 s50, s42, s34
	v_lshl_add_u64 v[216:217], s[28:29], 0, v[178:179]
	s_mov_b32 m0, s50
	ds_read_b128 v[160:163], v205 offset:16384
	ds_read_b128 v[164:167], v205 offset:17408
	ds_read_b128 v[168:171], v205 offset:18432
	ds_read_b128 v[172:175], v205 offset:19456
	ds_read_b128 v[192:195], v205 offset:20480
	ds_read_b128 v[196:199], v205 offset:21504
	ds_read_b128 v[208:211], v205 offset:22528
	ds_read_b128 v[212:215], v205 offset:23552
	global_load_lds_dwordx4 v[216:217], off
	s_add_i32 m0, s50, 0x2000
	s_add_u32 s50, s28, 0x40000
	v_lshl_add_u64 v[218:219], s[28:29], 0, v[182:183]
	s_addc_u32 s51, s29, 0
	s_add_i32 s52, s43, s34
	global_load_lds_dwordx4 v[218:219], off
	v_lshl_add_u64 v[220:221], s[50:51], 0, v[178:179]
	s_mov_b32 m0, s52
	v_lshl_add_u64 v[222:223], s[30:31], 0, v[180:181]
	global_load_lds_dwordx4 v[220:221], off
	v_lshl_add_u64 v[220:221], s[50:51], 0, v[182:183]
	s_add_i32 m0, s52, 0x2000
	s_nop 0
	global_load_lds_dwordx4 v[220:221], off
	v_lshl_add_u64 v[220:221], s[30:31], 0, v[176:177]
	s_mov_b32 m0, s9
	s_nop 0
	global_load_lds_dwordx4 v[220:221], off
	s_mov_b32 m0, s35
	s_nop 0
	global_load_lds_dwordx4 v[222:223], off
	s_waitcnt vmcnt(8)
	s_waitcnt lgkmcnt(0)
	s_barrier
; #define PG8_STAGE(bufoff, gbase, voff) do { _Pragma("unroll") for (int _i = 0; _i < 2; ++_i) \
;         __builtin_amdgcn_global_load_lds((const unsigned*)((const char*)(gbase) + (voff)[_i]), (LAS unsigned*)(lds + (bufoff) + ldsw + _i * 8192), 16, 0, 0); } while (0)
; #define PG8_LDA(dst, b, h) do { _Pragma("unroll") for (int m = 0; m < 4; ++m) _Pragma("unroll") for (int k = 0; k < 2; ++k) dst[m][k] = *(const LAS bf16x8*)(lds + PG8_SA(b, h) + aoff + m * 2048 + k * 1024); } while (0)
; #define PG8_LDB(dst, b, h) do { _Pragma("unroll") for (int n = 0; n < 2; ++n) _Pragma("unroll") for (int k = 0; k < 2; ++k) dst[n][k] = *(const LAS bf16x8*)(lds + PG8_SB(b, h) + boff + n * 2048 + k * 1024); } while (0)
; #define PG8_MMA(ai, bj, At, Bt) do { __builtin_amdgcn_s_setprio(1); _Pragma("unroll") for (int m = 0; m < 4; ++m) _Pragma("unroll") for (int n = 0; n < 2; ++n) _Pragma("unroll") for (int k = 0; k < 2; ++k) \
;         acc[ai][bj][m][n] = __builtin_amdgcn_mfma_f32_16x16x32_bf16(Bt[n][k], At[m][k], acc[ai][bj][m][n], 0, 0, 0); __builtin_amdgcn_s_setprio(0); } while (0)
; #define PG8_WAIT_V(n) asm volatile("s_waitcnt vmcnt(" #n ")" ::: "memory")
; #define PG8_WAIT_L(n) asm volatile("s_waitcnt lgkmcnt(" #n ")" ::: "memory")
; #define PG8_BAR __builtin_amdgcn_s_barrier()
; #define PG8_SCHED __builtin_amdgcn_sched_barrier(0)
; template <class Epi, bool ALIGN_EPI>
; __device__ __forceinline__ void gemm_phase(LAS unsigned char* lds, const Gemm g, const StaticOrder& S, const Epi& E) {
;     ...
;             PG8_WAIT_V(8); PG8_WAIT_L(0); PG8_BAR; PG8_MMA(1, 0, At, B0); PG8_MMA(1, 1, At, B1); PG8_BAR; PG8_SCHED;
;             PG8_LDB(B0, 1, 0); PG8_LDB(B1, 1, 1); PG8_SCHED; PG8_LDA(At, 1, 0); PG8_STAGE(PG8_SA(0, 1), a2 + hsA, voffA);
;             PG8_WAIT_V(8); PG8_WAIT_L(0); PG8_BAR; PG8_MMA(0, 0, At, B0); PG8_MMA(0, 1, At, B1); PG8_BAR; PG8_SCHED;
;             PG8_LDA(At, 1, 1); PG8_STAGE(PG8_SB(1, 0), b3, voffB); PG8_STAGE(PG8_SB(1, 1), b3 + hsB, voffB); PG8_STAGE(PG8_SA(1, 0), a3, voffA);
;             PG8_WAIT_V(8); PG8_WAIT_L(0); PG8_BAR; PG8_MMA(1, 0, At, B0); PG8_MMA(1, 1, At, B1); PG8_BAR; PG8_SCHED;
	s_waitcnt lgkmcnt(0)
	v_mfma_f32_16x16x32_bf16 v[60:63], v[128:131], v[160:163], v[60:63]
	v_mfma_f32_16x16x32_bf16 v[56:59], v[136:139], v[160:163], v[56:59]
	v_mfma_f32_16x16x32_bf16 v[44:47], v[128:131], v[168:171], v[44:47]
	v_mfma_f32_16x16x32_bf16 v[40:43], v[136:139], v[168:171], v[40:43]
	v_mfma_f32_16x16x32_bf16 v[28:31], v[128:131], v[192:195], v[28:31]
	v_mfma_f32_16x16x32_bf16 v[24:27], v[136:139], v[192:195], v[24:27]
	v_mfma_f32_16x16x32_bf16 v[12:15], v[128:131], v[208:211], v[12:15]
	v_mfma_f32_16x16x32_bf16 v[8:11], v[136:139], v[208:211], v[8:11]
	v_mfma_f32_16x16x32_bf16 v[60:63], v[132:135], v[164:167], v[60:63]
	v_mfma_f32_16x16x32_bf16 v[56:59], v[140:143], v[164:167], v[56:59]
	v_mfma_f32_16x16x32_bf16 v[44:47], v[132:135], v[172:175], v[44:47]
	v_mfma_f32_16x16x32_bf16 v[40:43], v[140:143], v[172:175], v[40:43]
	v_mfma_f32_16x16x32_bf16 v[28:31], v[132:135], v[196:199], v[28:31]
	v_mfma_f32_16x16x32_bf16 v[24:27], v[140:143], v[196:199], v[24:27]
	v_mfma_f32_16x16x32_bf16 v[12:15], v[132:135], v[212:215], v[12:15]
	v_mfma_f32_16x16x32_bf16 v[8:11], v[140:143], v[212:215], v[8:11]
	v_mfma_f32_16x16x32_bf16 v[52:55], v[144:147], v[160:163], v[52:55]
	v_mfma_f32_16x16x32_bf16 v[48:51], v[152:155], v[160:163], v[48:51]
	v_mfma_f32_16x16x32_bf16 v[36:39], v[144:147], v[168:171], v[36:39]
	v_mfma_f32_16x16x32_bf16 v[32:35], v[152:155], v[168:171], v[32:35]
	v_mfma_f32_16x16x32_bf16 v[20:23], v[144:147], v[192:195], v[20:23]
	v_mfma_f32_16x16x32_bf16 v[16:19], v[152:155], v[192:195], v[16:19]
	v_mfma_f32_16x16x32_bf16 v[4:7], v[144:147], v[208:211], v[4:7]
	v_mfma_f32_16x16x32_bf16 v[0:3], v[152:155], v[208:211], v[0:3]
	v_mfma_f32_16x16x32_bf16 v[52:55], v[148:151], v[164:167], v[52:55]
	v_mfma_f32_16x16x32_bf16 v[48:51], v[156:159], v[164:167], v[48:51]
	v_mfma_f32_16x16x32_bf16 v[36:39], v[148:151], v[172:175], v[36:39]
	v_mfma_f32_16x16x32_bf16 v[32:35], v[156:159], v[172:175], v[32:35]
	v_mfma_f32_16x16x32_bf16 v[20:23], v[148:151], v[196:199], v[20:23]
	v_mfma_f32_16x16x32_bf16 v[16:19], v[156:159], v[196:199], v[16:19]
	v_mfma_f32_16x16x32_bf16 v[4:7], v[148:151], v[212:215], v[4:7]
	v_mfma_f32_16x16x32_bf16 v[0:3], v[156:159], v[212:215], v[0:3]
	s_barrier
	s_add_i32 s50, 0, 0x18000
	s_add_i32 s51, 0, 0x1c000
	v_add_u32_e32 v140, s50, v201
	v_add_u32_e32 v156, s51, v201
	ds_read_b128 v[128:131], v140
	ds_read_b128 v[132:135], v140 offset:1024
	ds_read_b128 v[136:139], v140 offset:2048
	ds_read_b128 v[140:143], v140 offset:3072
	ds_read_b128 v[144:147], v156
	ds_read_b128 v[148:151], v156 offset:1024
	ds_read_b128 v[152:155], v156 offset:2048
	ds_read_b128 v[156:159], v156 offset:3072
	s_add_u32 s30, s30, 0x40000
	s_addc_u32 s31, s31, 0
	s_mov_b32 m0, s36
	v_lshl_add_u64 v[224:225], s[30:31], 0, v[176:177]
	ds_read_b128 v[160:163], v205 offset:32768
	ds_read_b128 v[164:167], v205 offset:33792
	ds_read_b128 v[168:171], v205 offset:34816
	ds_read_b128 v[172:175], v205 offset:35840
	ds_read_b128 v[192:195], v205 offset:36864
	ds_read_b128 v[196:199], v205 offset:37888
	ds_read_b128 v[208:211], v205 offset:38912
	ds_read_b128 v[212:215], v205 offset:39936
	global_load_lds_dwordx4 v[224:225], off
	v_lshl_add_u64 v[224:225], s[30:31], 0, v[180:181]
	s_mov_b32 m0, s37
	s_nop 0
	global_load_lds_dwordx4 v[224:225], off
	s_waitcnt vmcnt(8)
	s_waitcnt lgkmcnt(0)
	s_barrier
	s_waitcnt lgkmcnt(0)
	v_mfma_f32_16x16x32_bf16 v[124:127], v[128:131], v[160:163], v[124:127]
	v_mfma_f32_16x16x32_bf16 v[120:123], v[136:139], v[160:163], v[120:123]
	v_mfma_f32_16x16x32_bf16 v[108:111], v[128:131], v[168:171], v[108:111]
	v_mfma_f32_16x16x32_bf16 v[104:107], v[136:139], v[168:171], v[104:107]
	v_mfma_f32_16x16x32_bf16 v[92:95], v[128:131], v[192:195], v[92:95]
	v_mfma_f32_16x16x32_bf16 v[88:91], v[136:139], v[192:195], v[88:91]
	v_mfma_f32_16x16x32_bf16 v[76:79], v[128:131], v[208:211], v[76:79]
	v_mfma_f32_16x16x32_bf16 v[72:75], v[136:139], v[208:211], v[72:75]
	v_mfma_f32_16x16x32_bf16 v[124:127], v[132:135], v[164:167], v[124:127]
	v_mfma_f32_16x16x32_bf16 v[120:123], v[140:143], v[164:167], v[120:123]
	v_mfma_f32_16x16x32_bf16 v[108:111], v[132:135], v[172:175], v[108:111]
	v_mfma_f32_16x16x32_bf16 v[104:107], v[140:143], v[172:175], v[104:107]
	v_mfma_f32_16x16x32_bf16 v[92:95], v[132:135], v[196:199], v[92:95]
	v_mfma_f32_16x16x32_bf16 v[88:91], v[140:143], v[196:199], v[88:91]
	v_mfma_f32_16x16x32_bf16 v[76:79], v[132:135], v[212:215], v[76:79]
	v_mfma_f32_16x16x32_bf16 v[72:75], v[140:143], v[212:215], v[72:75]
	v_mfma_f32_16x16x32_bf16 v[116:119], v[144:147], v[160:163], v[116:119]
	v_mfma_f32_16x16x32_bf16 v[112:115], v[152:155], v[160:163], v[112:115]
	v_mfma_f32_16x16x32_bf16 v[100:103], v[144:147], v[168:171], v[100:103]
	v_mfma_f32_16x16x32_bf16 v[96:99], v[152:155], v[168:171], v[96:99]
	v_mfma_f32_16x16x32_bf16 v[84:87], v[144:147], v[192:195], v[84:87]
	v_mfma_f32_16x16x32_bf16 v[80:83], v[152:155], v[192:195], v[80:83]
	v_mfma_f32_16x16x32_bf16 v[68:71], v[144:147], v[208:211], v[68:71]
	v_mfma_f32_16x16x32_bf16 v[64:67], v[152:155], v[208:211], v[64:67]
	v_mfma_f32_16x16x32_bf16 v[116:119], v[148:151], v[164:167], v[116:119]
	v_mfma_f32_16x16x32_bf16 v[112:115], v[156:159], v[164:167], v[112:115]
	v_mfma_f32_16x16x32_bf16 v[100:103], v[148:151], v[172:175], v[100:103]
	v_mfma_f32_16x16x32_bf16 v[96:99], v[156:159], v[172:175], v[96:99]
	v_mfma_f32_16x16x32_bf16 v[84:87], v[148:151], v[196:199], v[84:87]
	v_mfma_f32_16x16x32_bf16 v[80:83], v[156:159], v[196:199], v[80:83]
	v_mfma_f32_16x16x32_bf16 v[68:71], v[148:151], v[212:215], v[68:71]
	v_mfma_f32_16x16x32_bf16 v[64:67], v[156:159], v[212:215], v[64:67]
	s_barrier
; #define PG8_STAGE(bufoff, gbase, voff) do { _Pragma("unroll") for (int _i = 0; _i < 2; ++_i) \
;         __builtin_amdgcn_global_load_lds((const unsigned*)((const char*)(gbase) + (voff)[_i]), (LAS unsigned*)(lds + (bufoff) + ldsw + _i * 8192), 16, 0, 0); } while (0)
; #define PG8_LDA(dst, b, h) do { _Pragma("unroll") for (int m = 0; m < 4; ++m) _Pragma("unroll") for (int k = 0; k < 2; ++k) dst[m][k] = *(const LAS bf16x8*)(lds + PG8_SA(b, h) + aoff + m * 2048 + k * 1024); } while (0)
; #define PG8_MMA(ai, bj, At, Bt) do { __builtin_amdgcn_s_setprio(1); _Pragma("unroll") for (int m = 0; m < 4; ++m) _Pragma("unroll") for (int n = 0; n < 2; ++n) _Pragma("unroll") for (int k = 0; k < 2; ++k) \
;         acc[ai][bj][m][n] = __builtin_amdgcn_mfma_f32_16x16x32_bf16(Bt[n][k], At[m][k], acc[ai][bj][m][n], 0, 0, 0); __builtin_amdgcn_s_setprio(0); } while (0)
; #define PG8_WAIT_V(n) asm volatile("s_waitcnt vmcnt(" #n ")" ::: "memory")
; #define PG8_WAIT_L(n) asm volatile("s_waitcnt lgkmcnt(" #n ")" ::: "memory")
; #define PG8_BAR __builtin_amdgcn_s_barrier()
; #define PG8_SCHED __builtin_amdgcn_sched_barrier(0)
; template <class Epi, bool ALIGN_EPI>
; __device__ __forceinline__ void gemm_phase(LAS unsigned char* lds, const Gemm g, const StaticOrder& S, const Epi& E) {
;     ...
;             PG8_LDA(At, 1, 1); PG8_STAGE(PG8_SB(1, 0), b3, voffB); PG8_STAGE(PG8_SB(1, 1), b3 + hsB, voffB); PG8_STAGE(PG8_SA(1, 0), a3, voffA);
;             PG8_WAIT_V(8); PG8_WAIT_L(0); PG8_BAR; PG8_MMA(1, 0, At, B0); PG8_MMA(1, 1, At, B1); PG8_BAR; PG8_SCHED;
;         }
	s_add_i32 s30, s50, s34
	v_lshl_add_u64 v[216:217], v[216:217], 0, s[4:5]
	s_mov_b32 m0, s30
	ds_read_b128 v[160:163], v205 offset:49152
	ds_read_b128 v[164:167], v205 offset:50176
	ds_read_b128 v[168:171], v205 offset:51200
	ds_read_b128 v[172:175], v205 offset:52224
	ds_read_b128 v[192:195], v205 offset:53248
	ds_read_b128 v[196:199], v205 offset:54272
	ds_read_b128 v[208:211], v205 offset:55296
	ds_read_b128 v[212:215], v205 offset:56320
	global_load_lds_dwordx4 v[216:217], off
	s_add_i32 m0, s30, 0x2000
	s_add_u32 s28, s28, 0x40080
	v_lshl_add_u64 v[216:217], v[218:219], 0, s[4:5]
	s_addc_u32 s29, s29, 0
	s_add_i32 s30, s51, s34
	global_load_lds_dwordx4 v[216:217], off
	v_lshl_add_u64 v[216:217], s[28:29], 0, v[178:179]
	s_mov_b32 m0, s30
	s_nop 0
	global_load_lds_dwordx4 v[216:217], off
	v_lshl_add_u64 v[216:217], s[28:29], 0, v[182:183]
	s_add_i32 m0, s30, 0x2000
	s_nop 0
	global_load_lds_dwordx4 v[216:217], off
	v_lshl_add_u64 v[216:217], v[220:221], 0, s[4:5]
	s_mov_b32 m0, s39
	s_nop 0
	global_load_lds_dwordx4 v[216:217], off
	v_lshl_add_u64 v[216:217], v[222:223], 0, s[4:5]
	s_mov_b32 m0, s40
	s_nop 0
	global_load_lds_dwordx4 v[216:217], off
	s_waitcnt vmcnt(8)
	s_waitcnt lgkmcnt(0)
	s_barrier
	s_waitcnt lgkmcnt(0)
	v_mfma_f32_16x16x32_bf16 v[60:63], v[128:131], v[160:163], v[60:63]
	v_mfma_f32_16x16x32_bf16 v[56:59], v[136:139], v[160:163], v[56:59]
	v_mfma_f32_16x16x32_bf16 v[44:47], v[128:131], v[168:171], v[44:47]
	v_mfma_f32_16x16x32_bf16 v[40:43], v[136:139], v[168:171], v[40:43]
	v_mfma_f32_16x16x32_bf16 v[28:31], v[128:131], v[192:195], v[28:31]
	v_mfma_f32_16x16x32_bf16 v[24:27], v[136:139], v[192:195], v[24:27]
	v_mfma_f32_16x16x32_bf16 v[12:15], v[128:131], v[208:211], v[12:15]
	v_mfma_f32_16x16x32_bf16 v[8:11], v[136:139], v[208:211], v[8:11]
	v_mfma_f32_16x16x32_bf16 v[60:63], v[132:135], v[164:167], v[60:63]
	v_mfma_f32_16x16x32_bf16 v[56:59], v[140:143], v[164:167], v[56:59]
	v_mfma_f32_16x16x32_bf16 v[44:47], v[132:135], v[172:175], v[44:47]
	v_mfma_f32_16x16x32_bf16 v[40:43], v[140:143], v[172:175], v[40:43]
	v_mfma_f32_16x16x32_bf16 v[28:31], v[132:135], v[196:199], v[28:31]
	v_mfma_f32_16x16x32_bf16 v[24:27], v[140:143], v[196:199], v[24:27]
	v_mfma_f32_16x16x32_bf16 v[12:15], v[132:135], v[212:215], v[12:15]
	v_mfma_f32_16x16x32_bf16 v[8:11], v[140:143], v[212:215], v[8:11]
	v_mfma_f32_16x16x32_bf16 v[52:55], v[144:147], v[160:163], v[52:55]
	v_mfma_f32_16x16x32_bf16 v[48:51], v[152:155], v[160:163], v[48:51]
	v_mfma_f32_16x16x32_bf16 v[36:39], v[144:147], v[168:171], v[36:39]
	v_mfma_f32_16x16x32_bf16 v[32:35], v[152:155], v[168:171], v[32:35]
	v_mfma_f32_16x16x32_bf16 v[20:23], v[144:147], v[192:195], v[20:23]
	v_mfma_f32_16x16x32_bf16 v[16:19], v[152:155], v[192:195], v[16:19]
	v_mfma_f32_16x16x32_bf16 v[4:7], v[144:147], v[208:211], v[4:7]
	v_mfma_f32_16x16x32_bf16 v[0:3], v[152:155], v[208:211], v[0:3]
	v_mfma_f32_16x16x32_bf16 v[52:55], v[148:151], v[164:167], v[52:55]
	v_mfma_f32_16x16x32_bf16 v[48:51], v[156:159], v[164:167], v[48:51]
	v_mfma_f32_16x16x32_bf16 v[36:39], v[148:151], v[172:175], v[36:39]
	v_mfma_f32_16x16x32_bf16 v[32:35], v[156:159], v[172:175], v[32:35]
	v_mfma_f32_16x16x32_bf16 v[20:23], v[148:151], v[196:199], v[20:23]
	v_mfma_f32_16x16x32_bf16 v[16:19], v[156:159], v[196:199], v[16:19]
	v_mfma_f32_16x16x32_bf16 v[4:7], v[148:151], v[212:215], v[4:7]
	v_mfma_f32_16x16x32_bf16 v[0:3], v[156:159], v[212:215], v[0:3]
	s_barrier
	s_add_i32 s49, s49, 2
	s_add_u32 s24, s24, 0x100
	s_addc_u32 s25, s25, 0
	s_add_u32 s47, s47, 0x100
	s_addc_u32 s48, s48, 0
	s_cmp_gt_u32 s49, 13
	s_cbranch_scc0 .LBB0_1501
	s_and_b64 vcc, exec, s[6:7]
	s_cbranch_vccz .LBB0_1504
	s_barrier
